# GEMM K-loops: MFMA issue order inside each 16-MFMA block changed to a snake order (weight-side operand reused across the pair boundary)
# speedup vs baseline: 1.0024x; 1.0024x over previous
; #define PG8_STAGE(bufoff, gbase, voff) do { _Pragma("unroll") for (int _i = 0; _i < 2; ++_i) \
;         __builtin_amdgcn_global_load_lds((const unsigned*)((const char*)(gbase) + (voff)[_i]), (PG8_LAS unsigned*)(lds + (bufoff) + ldsw + _i * 8192), 16, 0, 0); } while (0)
; #define PG8_LDA(dst, b, h) do { _Pragma("unroll") for (int m = 0; m < 4; ++m) _Pragma("unroll") for (int k = 0; k < 2; ++k) dst[m][k] = *(const PG8_LAS bf16x8*)(lds + PG8_SA(b, h) + aoff + m * 2048 + k * 1024); } while (0)
; #define PG8_LDB(dst, b, h) do { _Pragma("unroll") for (int n = 0; n < 2; ++n) _Pragma("unroll") for (int k = 0; k < 2; ++k) dst[n][k] = *(const PG8_LAS bf16x8*)(lds + PG8_SB(b, h) + boff + n * 2048 + k * 1024); } while (0)
; #define PG8_MMA(ai, bj, At, Bt) do { __builtin_amdgcn_s_setprio(1); _Pragma("unroll") for (int m = 0; m < 4; ++m) _Pragma("unroll") for (int n = 0; n < 2; ++n) _Pragma("unroll") for (int k = 0; k < 2; ++k) \
;         acc[ai][bj][m][n] = __builtin_amdgcn_mfma_f32_16x16x32_bf16(Bt[n][k], At[m][k], acc[ai][bj][m][n], 0, 0, 0); __builtin_amdgcn_s_setprio(0); } while (0)
; #define PG8_WAIT_V(n) asm volatile("s_waitcnt vmcnt(" #n ")" ::: "memory")
; #define PG8_WAIT_L(n) asm volatile("s_waitcnt lgkmcnt(" #n ")" ::: "memory")
; #define PG8_BAR __builtin_amdgcn_s_barrier()
; #define PG8_SCHED __builtin_amdgcn_sched_barrier(0)
; template <class Epi, class Sched, bool ALIGN_EPI = false, bool SP2 = false, bool A_TILED = false, bool B_TILED = false>
; __device__ __forceinline__ void gemm_phase(PG8_LAS unsigned char* lds, const Gemm g, const Sched& S, const Epi& E) {
;     ...
;             PG8_LDB(B0, 0, 0); PG8_LDB(B1, 0, 1); PG8_SCHED; PG8_LDA(At, 0, 0); PG8_STAGE(PG8_SA(1, 1), a1 + hstepA, voffA);
;             PG8_WAIT_V(8); PG8_WAIT_L(0); PG8_BAR; PG8_MMA(0, 0, At, B0); PG8_MMA(0, 1, At, B1); PG8_BAR; PG8_SCHED;
;             PG8_LDA(At, 0, 1); PG8_STAGE(PG8_SB(0, 0), b2, voffB); PG8_STAGE(PG8_SB(0, 1), b2 + hstepB, voffB); PG8_STAGE(PG8_SA(0, 0), a2, voffA);
.LBB0_102:
	ds_read_b128 v[142:145], v148
	ds_read_b128 v[152:155], v148 offset:1024
	ds_read_b128 v[156:159], v148 offset:2048
	ds_read_b128 v[160:163], v148 offset:3072
	ds_read_b128 v[164:167], v149
	ds_read_b128 v[168:171], v149 offset:1024
	ds_read_b128 v[172:175], v149 offset:2048
	ds_read_b128 v[176:179], v149 offset:3072
	s_add_u32 s36, s34, 0xfff00080
	s_addc_u32 s37, s35, -1
	s_cmp_eq_u32 s68, 60
	s_cselect_b32 s39, s21, s37
	s_cselect_b32 s38, s23, s36
	s_cselect_b32 s37, s19, s67
	s_cselect_b32 s36, s65, s66
	v_lshl_add_u64 v[214:215], s[34:35], 0, v[138:139]
	s_add_i32 m0, s25, 0xc000
	ds_read_b128 v[180:183], v150
	ds_read_b128 v[184:187], v150 offset:1024
	ds_read_b128 v[190:193], v150 offset:2048
	ds_read_b128 v[194:197], v150 offset:3072
	ds_read_b128 v[198:201], v150 offset:4096
	ds_read_b128 v[202:205], v150 offset:5120
	ds_read_b128 v[206:209], v150 offset:6144
	ds_read_b128 v[210:213], v150 offset:7168
	global_load_lds_dwordx4 v[214:215], off
	v_lshl_add_u64 v[214:215], s[34:35], 0, v[140:141]
	s_add_i32 m0, s25, 0xe000
	s_nop 0
	global_load_lds_dwordx4 v[214:215], off
	s_waitcnt vmcnt(8)
	s_waitcnt lgkmcnt(0)
	s_barrier
	s_setprio 1
	s_waitcnt lgkmcnt(0)
	v_mfma_f32_16x16x32_bf16 v[126:129], v[142:145], v[180:183], v[126:129]
	v_mfma_f32_16x16x32_bf16 v[122:125], v[156:159], v[180:183], v[122:125]
	v_mfma_f32_16x16x32_bf16 v[110:113], v[156:159], v[190:193], v[110:113]
	v_mfma_f32_16x16x32_bf16 v[118:121], v[142:145], v[190:193], v[118:121]
	v_mfma_f32_16x16x32_bf16 v[102:105], v[142:145], v[198:201], v[102:105]
	v_mfma_f32_16x16x32_bf16 v[94:97], v[156:159], v[198:201], v[94:97]
	v_mfma_f32_16x16x32_bf16 v[78:81], v[156:159], v[206:209], v[78:81]
	v_mfma_f32_16x16x32_bf16 v[86:89], v[142:145], v[206:209], v[86:89]
	v_mfma_f32_16x16x32_bf16 v[126:129], v[152:155], v[184:187], v[126:129]
	v_mfma_f32_16x16x32_bf16 v[122:125], v[160:163], v[184:187], v[122:125]
	v_mfma_f32_16x16x32_bf16 v[110:113], v[160:163], v[194:197], v[110:113]
	v_mfma_f32_16x16x32_bf16 v[118:121], v[152:155], v[194:197], v[118:121]
	v_mfma_f32_16x16x32_bf16 v[102:105], v[152:155], v[202:205], v[102:105]
	v_mfma_f32_16x16x32_bf16 v[94:97], v[160:163], v[202:205], v[94:97]
	v_mfma_f32_16x16x32_bf16 v[78:81], v[160:163], v[210:213], v[78:81]
	v_mfma_f32_16x16x32_bf16 v[86:89], v[152:155], v[210:213], v[86:89]
	s_setprio 0
	s_setprio 1
	v_mfma_f32_16x16x32_bf16 v[114:117], v[164:167], v[180:183], v[114:117]
	v_mfma_f32_16x16x32_bf16 v[106:109], v[172:175], v[180:183], v[106:109]
	v_mfma_f32_16x16x32_bf16 v[90:93], v[172:175], v[190:193], v[90:93]
	v_mfma_f32_16x16x32_bf16 v[98:101], v[164:167], v[190:193], v[98:101]
	v_mfma_f32_16x16x32_bf16 v[82:85], v[164:167], v[198:201], v[82:85]
	v_mfma_f32_16x16x32_bf16 v[74:77], v[172:175], v[198:201], v[74:77]
	v_mfma_f32_16x16x32_bf16 v[66:69], v[172:175], v[206:209], v[66:69]
	v_mfma_f32_16x16x32_bf16 v[70:73], v[164:167], v[206:209], v[70:73]
	v_mfma_f32_16x16x32_bf16 v[114:117], v[168:171], v[184:187], v[114:117]
	v_mfma_f32_16x16x32_bf16 v[106:109], v[176:179], v[184:187], v[106:109]
	v_mfma_f32_16x16x32_bf16 v[90:93], v[176:179], v[194:197], v[90:93]
	v_mfma_f32_16x16x32_bf16 v[98:101], v[168:171], v[194:197], v[98:101]
	v_mfma_f32_16x16x32_bf16 v[82:85], v[168:171], v[202:205], v[82:85]
	v_mfma_f32_16x16x32_bf16 v[74:77], v[176:179], v[202:205], v[74:77]
	v_mfma_f32_16x16x32_bf16 v[66:69], v[176:179], v[210:213], v[66:69]
	v_mfma_f32_16x16x32_bf16 v[70:73], v[168:171], v[210:213], v[70:73]
	s_setprio 0
	s_barrier
	s_add_i32 s69, s61, s43
	v_lshl_add_u64 v[214:215], s[36:37], 0, v[132:133]
	s_mov_b32 m0, s69
	ds_read_b128 v[180:183], v150 offset:16384
	ds_read_b128 v[184:187], v150 offset:17408
	ds_read_b128 v[190:193], v150 offset:18432
	ds_read_b128 v[194:197], v150 offset:19456
	ds_read_b128 v[198:201], v150 offset:20480
	ds_read_b128 v[202:205], v150 offset:21504
	ds_read_b128 v[206:209], v150 offset:22528
	ds_read_b128 v[210:213], v150 offset:23552
	global_load_lds_dwordx4 v[214:215], off
	s_add_i32 m0, s69, 0x2000
	s_add_u32 s70, s36, 0x100000
	v_lshl_add_u64 v[216:217], s[36:37], 0, v[136:137]
	s_addc_u32 s71, s37, 0
	s_add_i32 s69, s62, s43
	global_load_lds_dwordx4 v[216:217], off
	v_lshl_add_u64 v[218:219], s[70:71], 0, v[132:133]
	s_mov_b32 m0, s69
	v_lshl_add_u64 v[220:221], s[38:39], 0, v[134:135]
	global_load_lds_dwordx4 v[218:219], off
	v_lshl_add_u64 v[218:219], s[70:71], 0, v[136:137]
	s_add_i32 m0, s69, 0x2000
	s_nop 0
	global_load_lds_dwordx4 v[218:219], off
	v_lshl_add_u64 v[218:219], s[38:39], 0, v[130:131]
	s_mov_b32 m0, s25
	s_nop 0
	global_load_lds_dwordx4 v[218:219], off
	s_mov_b32 m0, s44
	s_nop 0
	global_load_lds_dwordx4 v[220:221], off
	s_waitcnt vmcnt(8)
	s_waitcnt lgkmcnt(0)
	s_barrier
; #define PG8_STAGE(bufoff, gbase, voff) do { _Pragma("unroll") for (int _i = 0; _i < 2; ++_i) \
;         __builtin_amdgcn_global_load_lds((const unsigned*)((const char*)(gbase) + (voff)[_i]), (PG8_LAS unsigned*)(lds + (bufoff) + ldsw + _i * 8192), 16, 0, 0); } while (0)
; #define PG8_LDA(dst, b, h) do { _Pragma("unroll") for (int m = 0; m < 4; ++m) _Pragma("unroll") for (int k = 0; k < 2; ++k) dst[m][k] = *(const PG8_LAS bf16x8*)(lds + PG8_SA(b, h) + aoff + m * 2048 + k * 1024); } while (0)
; #define PG8_LDB(dst, b, h) do { _Pragma("unroll") for (int n = 0; n < 2; ++n) _Pragma("unroll") for (int k = 0; k < 2; ++k) dst[n][k] = *(const PG8_LAS bf16x8*)(lds + PG8_SB(b, h) + boff + n * 2048 + k * 1024); } while (0)
; #define PG8_MMA(ai, bj, At, Bt) do { __builtin_amdgcn_s_setprio(1); _Pragma("unroll") for (int m = 0; m < 4; ++m) _Pragma("unroll") for (int n = 0; n < 2; ++n) _Pragma("unroll") for (int k = 0; k < 2; ++k) \
;         acc[ai][bj][m][n] = __builtin_amdgcn_mfma_f32_16x16x32_bf16(Bt[n][k], At[m][k], acc[ai][bj][m][n], 0, 0, 0); __builtin_amdgcn_s_setprio(0); } while (0)
; #define PG8_WAIT_V(n) asm volatile("s_waitcnt vmcnt(" #n ")" ::: "memory")
; #define PG8_WAIT_L(n) asm volatile("s_waitcnt lgkmcnt(" #n ")" ::: "memory")
; #define PG8_BAR __builtin_amdgcn_s_barrier()
; #define PG8_SCHED __builtin_amdgcn_sched_barrier(0)
; template <class Epi, class Sched, bool ALIGN_EPI = false, bool SP2 = false, bool A_TILED = false, bool B_TILED = false>
; __device__ __forceinline__ void gemm_phase(PG8_LAS unsigned char* lds, const Gemm g, const Sched& S, const Epi& E) {
;     ...
;             PG8_WAIT_V(8); PG8_WAIT_L(0); PG8_BAR; PG8_MMA(1, 0, At, B0); PG8_MMA(1, 1, At, B1); PG8_BAR; PG8_SCHED;
;             PG8_LDB(B0, 1, 0); PG8_LDB(B1, 1, 1); PG8_SCHED; PG8_LDA(At, 1, 0); PG8_STAGE(PG8_SA(0, 1), a2 + hstepA, voffA);
;             PG8_WAIT_V(8); PG8_WAIT_L(0); PG8_BAR; PG8_MMA(0, 0, At, B0); PG8_MMA(0, 1, At, B1); PG8_BAR; PG8_SCHED;
	s_setprio 1
	s_waitcnt lgkmcnt(0)
	v_mfma_f32_16x16x32_bf16 v[62:65], v[142:145], v[180:183], v[62:65]
	v_mfma_f32_16x16x32_bf16 v[58:61], v[156:159], v[180:183], v[58:61]
	v_mfma_f32_16x16x32_bf16 v[46:49], v[156:159], v[190:193], v[46:49]
	v_mfma_f32_16x16x32_bf16 v[54:57], v[142:145], v[190:193], v[54:57]
	v_mfma_f32_16x16x32_bf16 v[38:41], v[142:145], v[198:201], v[38:41]
	v_mfma_f32_16x16x32_bf16 v[30:33], v[156:159], v[198:201], v[30:33]
	v_mfma_f32_16x16x32_bf16 v[14:17], v[156:159], v[206:209], v[14:17]
	v_mfma_f32_16x16x32_bf16 v[22:25], v[142:145], v[206:209], v[22:25]
	v_mfma_f32_16x16x32_bf16 v[62:65], v[152:155], v[184:187], v[62:65]
	v_mfma_f32_16x16x32_bf16 v[58:61], v[160:163], v[184:187], v[58:61]
	v_mfma_f32_16x16x32_bf16 v[46:49], v[160:163], v[194:197], v[46:49]
	v_mfma_f32_16x16x32_bf16 v[54:57], v[152:155], v[194:197], v[54:57]
	v_mfma_f32_16x16x32_bf16 v[38:41], v[152:155], v[202:205], v[38:41]
	v_mfma_f32_16x16x32_bf16 v[30:33], v[160:163], v[202:205], v[30:33]
	v_mfma_f32_16x16x32_bf16 v[14:17], v[160:163], v[210:213], v[14:17]
	v_mfma_f32_16x16x32_bf16 v[22:25], v[152:155], v[210:213], v[22:25]
	s_setprio 0
	s_setprio 1
	v_mfma_f32_16x16x32_bf16 v[50:53], v[164:167], v[180:183], v[50:53]
	v_mfma_f32_16x16x32_bf16 v[42:45], v[172:175], v[180:183], v[42:45]
	v_mfma_f32_16x16x32_bf16 v[26:29], v[172:175], v[190:193], v[26:29]
	v_mfma_f32_16x16x32_bf16 v[34:37], v[164:167], v[190:193], v[34:37]
	v_mfma_f32_16x16x32_bf16 v[18:21], v[164:167], v[198:201], v[18:21]
	v_mfma_f32_16x16x32_bf16 v[10:13], v[172:175], v[198:201], v[10:13]
	v_mfma_f32_16x16x32_bf16 v[2:5], v[172:175], v[206:209], v[2:5]
	v_mfma_f32_16x16x32_bf16 v[6:9], v[164:167], v[206:209], v[6:9]
	v_mfma_f32_16x16x32_bf16 v[50:53], v[168:171], v[184:187], v[50:53]
	v_mfma_f32_16x16x32_bf16 v[42:45], v[176:179], v[184:187], v[42:45]
	v_mfma_f32_16x16x32_bf16 v[26:29], v[176:179], v[194:197], v[26:29]
	v_mfma_f32_16x16x32_bf16 v[34:37], v[168:171], v[194:197], v[34:37]
	v_mfma_f32_16x16x32_bf16 v[18:21], v[168:171], v[202:205], v[18:21]
	v_mfma_f32_16x16x32_bf16 v[10:13], v[176:179], v[202:205], v[10:13]
	v_mfma_f32_16x16x32_bf16 v[2:5], v[176:179], v[210:213], v[2:5]
	v_mfma_f32_16x16x32_bf16 v[6:9], v[168:171], v[210:213], v[6:9]
	s_setprio 0
	s_barrier
	s_add_i32 s69, 0, 0x18000
	v_add_u32_e32 v151, s69, v146
	s_add_i32 s70, 0, 0x1c000
	ds_read_b128 v[142:145], v151
	ds_read_b128 v[152:155], v151 offset:1024
	ds_read_b128 v[156:159], v151 offset:2048
	ds_read_b128 v[160:163], v151 offset:3072
	v_add_u32_e32 v151, s70, v146
	ds_read_b128 v[164:167], v151
	ds_read_b128 v[168:171], v151 offset:1024
	ds_read_b128 v[172:175], v151 offset:2048
	ds_read_b128 v[176:179], v151 offset:3072
	s_add_u32 s38, s38, 0x100000
	s_addc_u32 s39, s39, 0
	s_mov_b32 m0, s45
	v_lshl_add_u64 v[222:223], s[38:39], 0, v[130:131]
	ds_read_b128 v[180:183], v150 offset:32768
	ds_read_b128 v[184:187], v150 offset:33792
	ds_read_b128 v[190:193], v150 offset:34816
	ds_read_b128 v[194:197], v150 offset:35840
	ds_read_b128 v[198:201], v150 offset:36864
	ds_read_b128 v[202:205], v150 offset:37888
	ds_read_b128 v[206:209], v150 offset:38912
	ds_read_b128 v[210:213], v150 offset:39936
	global_load_lds_dwordx4 v[222:223], off
	v_lshl_add_u64 v[222:223], s[38:39], 0, v[134:135]
	s_mov_b32 m0, s46
	s_nop 0
	global_load_lds_dwordx4 v[222:223], off
	s_waitcnt vmcnt(8)
	s_waitcnt lgkmcnt(0)
	s_barrier
	s_setprio 1
	s_waitcnt lgkmcnt(0)
	v_mfma_f32_16x16x32_bf16 v[126:129], v[142:145], v[180:183], v[126:129]
	v_mfma_f32_16x16x32_bf16 v[122:125], v[156:159], v[180:183], v[122:125]
	v_mfma_f32_16x16x32_bf16 v[110:113], v[156:159], v[190:193], v[110:113]
	v_mfma_f32_16x16x32_bf16 v[118:121], v[142:145], v[190:193], v[118:121]
	v_mfma_f32_16x16x32_bf16 v[102:105], v[142:145], v[198:201], v[102:105]
	v_mfma_f32_16x16x32_bf16 v[94:97], v[156:159], v[198:201], v[94:97]
	v_mfma_f32_16x16x32_bf16 v[78:81], v[156:159], v[206:209], v[78:81]
	v_mfma_f32_16x16x32_bf16 v[86:89], v[142:145], v[206:209], v[86:89]
	v_mfma_f32_16x16x32_bf16 v[126:129], v[152:155], v[184:187], v[126:129]
	v_mfma_f32_16x16x32_bf16 v[122:125], v[160:163], v[184:187], v[122:125]
	v_mfma_f32_16x16x32_bf16 v[110:113], v[160:163], v[194:197], v[110:113]
	v_mfma_f32_16x16x32_bf16 v[118:121], v[152:155], v[194:197], v[118:121]
	v_mfma_f32_16x16x32_bf16 v[102:105], v[152:155], v[202:205], v[102:105]
	v_mfma_f32_16x16x32_bf16 v[94:97], v[160:163], v[202:205], v[94:97]
	v_mfma_f32_16x16x32_bf16 v[78:81], v[160:163], v[210:213], v[78:81]
	v_mfma_f32_16x16x32_bf16 v[86:89], v[152:155], v[210:213], v[86:89]
	s_setprio 0
	s_setprio 1
	v_mfma_f32_16x16x32_bf16 v[114:117], v[164:167], v[180:183], v[114:117]
	v_mfma_f32_16x16x32_bf16 v[106:109], v[172:175], v[180:183], v[106:109]
	v_mfma_f32_16x16x32_bf16 v[90:93], v[172:175], v[190:193], v[90:93]
	v_mfma_f32_16x16x32_bf16 v[98:101], v[164:167], v[190:193], v[98:101]
	v_mfma_f32_16x16x32_bf16 v[82:85], v[164:167], v[198:201], v[82:85]
	v_mfma_f32_16x16x32_bf16 v[74:77], v[172:175], v[198:201], v[74:77]
	v_mfma_f32_16x16x32_bf16 v[66:69], v[172:175], v[206:209], v[66:69]
	v_mfma_f32_16x16x32_bf16 v[70:73], v[164:167], v[206:209], v[70:73]
	v_mfma_f32_16x16x32_bf16 v[114:117], v[168:171], v[184:187], v[114:117]
	v_mfma_f32_16x16x32_bf16 v[106:109], v[176:179], v[184:187], v[106:109]
	v_mfma_f32_16x16x32_bf16 v[90:93], v[176:179], v[194:197], v[90:93]
	v_mfma_f32_16x16x32_bf16 v[98:101], v[168:171], v[194:197], v[98:101]
	v_mfma_f32_16x16x32_bf16 v[82:85], v[168:171], v[202:205], v[82:85]
	v_mfma_f32_16x16x32_bf16 v[74:77], v[176:179], v[202:205], v[74:77]
	v_mfma_f32_16x16x32_bf16 v[66:69], v[176:179], v[210:213], v[66:69]
	v_mfma_f32_16x16x32_bf16 v[70:73], v[168:171], v[210:213], v[70:73]
	s_setprio 0
	s_barrier
; #define PG8_STAGE(bufoff, gbase, voff) do { _Pragma("unroll") for (int _i = 0; _i < 2; ++_i) \
;         __builtin_amdgcn_global_load_lds((const unsigned*)((const char*)(gbase) + (voff)[_i]), (PG8_LAS unsigned*)(lds + (bufoff) + ldsw + _i * 8192), 16, 0, 0); } while (0)
; #define PG8_LDA(dst, b, h) do { _Pragma("unroll") for (int m = 0; m < 4; ++m) _Pragma("unroll") for (int k = 0; k < 2; ++k) dst[m][k] = *(const PG8_LAS bf16x8*)(lds + PG8_SA(b, h) + aoff + m * 2048 + k * 1024); } while (0)
; #define PG8_MMA(ai, bj, At, Bt) do { __builtin_amdgcn_s_setprio(1); _Pragma("unroll") for (int m = 0; m < 4; ++m) _Pragma("unroll") for (int n = 0; n < 2; ++n) _Pragma("unroll") for (int k = 0; k < 2; ++k) \
;         acc[ai][bj][m][n] = __builtin_amdgcn_mfma_f32_16x16x32_bf16(Bt[n][k], At[m][k], acc[ai][bj][m][n], 0, 0, 0); __builtin_amdgcn_s_setprio(0); } while (0)
; #define PG8_WAIT_V(n) asm volatile("s_waitcnt vmcnt(" #n ")" ::: "memory")
; #define PG8_WAIT_L(n) asm volatile("s_waitcnt lgkmcnt(" #n ")" ::: "memory")
; #define PG8_BAR __builtin_amdgcn_s_barrier()
; #define PG8_SCHED __builtin_amdgcn_sched_barrier(0)
; template <class Epi, class Sched, bool ALIGN_EPI = false, bool SP2 = false, bool A_TILED = false, bool B_TILED = false>
; __device__ __forceinline__ void gemm_phase(PG8_LAS unsigned char* lds, const Gemm g, const Sched& S, const Epi& E) {
;     ...
;             PG8_LDA(At, 1, 1); PG8_STAGE(PG8_SB(1, 0), b3, voffB); PG8_STAGE(PG8_SB(1, 1), b3 + hstepB, voffB); PG8_STAGE(PG8_SA(1, 0), a3, voffA);
;             PG8_WAIT_V(8); PG8_WAIT_L(0); PG8_BAR; PG8_MMA(1, 0, At, B0); PG8_MMA(1, 1, At, B1); PG8_BAR; PG8_SCHED;
	s_add_i32 s38, s69, s43
	v_lshl_add_u64 v[214:215], v[214:215], 0, s[12:13]
	s_mov_b32 m0, s38
	ds_read_b128 v[180:183], v150 offset:49152
	ds_read_b128 v[184:187], v150 offset:50176
	ds_read_b128 v[190:193], v150 offset:51200
	ds_read_b128 v[194:197], v150 offset:52224
	ds_read_b128 v[198:201], v150 offset:53248
	ds_read_b128 v[202:205], v150 offset:54272
	ds_read_b128 v[206:209], v150 offset:55296
	ds_read_b128 v[210:213], v150 offset:56320
	global_load_lds_dwordx4 v[214:215], off
	s_add_i32 m0, s38, 0x2000
	s_add_u32 s36, s36, 0x100080
	v_lshl_add_u64 v[214:215], v[216:217], 0, s[12:13]
	s_addc_u32 s37, s37, 0
	s_add_i32 s38, s70, s43
	global_load_lds_dwordx4 v[214:215], off
	v_lshl_add_u64 v[214:215], s[36:37], 0, v[132:133]
	s_mov_b32 m0, s38
	s_nop 0
	global_load_lds_dwordx4 v[214:215], off
	v_lshl_add_u64 v[214:215], s[36:37], 0, v[136:137]
	s_add_i32 m0, s38, 0x2000
	s_nop 0
	global_load_lds_dwordx4 v[214:215], off
	v_lshl_add_u64 v[214:215], v[218:219], 0, s[12:13]
	s_mov_b32 m0, s47
	s_nop 0
	global_load_lds_dwordx4 v[214:215], off
	v_lshl_add_u64 v[214:215], v[220:221], 0, s[12:13]
	s_mov_b32 m0, s52
	s_nop 0
	global_load_lds_dwordx4 v[214:215], off
	s_waitcnt vmcnt(8)
	s_waitcnt lgkmcnt(0)
	s_barrier
	s_setprio 1
	s_waitcnt lgkmcnt(0)
	v_mfma_f32_16x16x32_bf16 v[62:65], v[142:145], v[180:183], v[62:65]
	v_mfma_f32_16x16x32_bf16 v[58:61], v[156:159], v[180:183], v[58:61]
	v_mfma_f32_16x16x32_bf16 v[46:49], v[156:159], v[190:193], v[46:49]
	v_mfma_f32_16x16x32_bf16 v[54:57], v[142:145], v[190:193], v[54:57]
	v_mfma_f32_16x16x32_bf16 v[38:41], v[142:145], v[198:201], v[38:41]
	v_mfma_f32_16x16x32_bf16 v[30:33], v[156:159], v[198:201], v[30:33]
	v_mfma_f32_16x16x32_bf16 v[14:17], v[156:159], v[206:209], v[14:17]
	v_mfma_f32_16x16x32_bf16 v[22:25], v[142:145], v[206:209], v[22:25]
	v_mfma_f32_16x16x32_bf16 v[62:65], v[152:155], v[184:187], v[62:65]
	v_mfma_f32_16x16x32_bf16 v[58:61], v[160:163], v[184:187], v[58:61]
	v_mfma_f32_16x16x32_bf16 v[46:49], v[160:163], v[194:197], v[46:49]
	v_mfma_f32_16x16x32_bf16 v[54:57], v[152:155], v[194:197], v[54:57]
	v_mfma_f32_16x16x32_bf16 v[38:41], v[152:155], v[202:205], v[38:41]
	v_mfma_f32_16x16x32_bf16 v[30:33], v[160:163], v[202:205], v[30:33]
	v_mfma_f32_16x16x32_bf16 v[14:17], v[160:163], v[210:213], v[14:17]
	v_mfma_f32_16x16x32_bf16 v[22:25], v[152:155], v[210:213], v[22:25]
	s_setprio 0
	s_setprio 1
	v_mfma_f32_16x16x32_bf16 v[50:53], v[164:167], v[180:183], v[50:53]
	v_mfma_f32_16x16x32_bf16 v[42:45], v[172:175], v[180:183], v[42:45]
	v_mfma_f32_16x16x32_bf16 v[26:29], v[172:175], v[190:193], v[26:29]
	v_mfma_f32_16x16x32_bf16 v[34:37], v[164:167], v[190:193], v[34:37]
	v_mfma_f32_16x16x32_bf16 v[18:21], v[164:167], v[198:201], v[18:21]
	v_mfma_f32_16x16x32_bf16 v[10:13], v[172:175], v[198:201], v[10:13]
	v_mfma_f32_16x16x32_bf16 v[2:5], v[172:175], v[206:209], v[2:5]
	v_mfma_f32_16x16x32_bf16 v[6:9], v[164:167], v[206:209], v[6:9]
	v_mfma_f32_16x16x32_bf16 v[50:53], v[168:171], v[184:187], v[50:53]
	v_mfma_f32_16x16x32_bf16 v[42:45], v[176:179], v[184:187], v[42:45]
	v_mfma_f32_16x16x32_bf16 v[26:29], v[176:179], v[194:197], v[26:29]
	v_mfma_f32_16x16x32_bf16 v[34:37], v[168:171], v[194:197], v[34:37]
	v_mfma_f32_16x16x32_bf16 v[18:21], v[168:171], v[202:205], v[18:21]
	v_mfma_f32_16x16x32_bf16 v[10:13], v[176:179], v[202:205], v[10:13]
	v_mfma_f32_16x16x32_bf16 v[2:5], v[176:179], v[210:213], v[2:5]
	v_mfma_f32_16x16x32_bf16 v[6:9], v[168:171], v[210:213], v[6:9]
	s_setprio 0
	s_barrier
	s_add_i32 s68, s68, 2
	s_add_u32 s34, s34, 0x100
	s_addc_u32 s35, s35, 0
	s_add_u32 s66, s66, 0x100
	s_addc_u32 s67, s67, 0
	s_cmp_gt_u32 s68, 61
	s_cbranch_scc0 .LBB0_102
	s_and_b64 vcc, exec, s[14:15]
	s_cbranch_vccz .LBB0_105
	s_barrier

; #define PG8_STAGE(bufoff, gbase, voff) do { _Pragma("unroll") for (int _i = 0; _i < 2; ++_i) \
;         __builtin_amdgcn_global_load_lds((const unsigned*)((const char*)(gbase) + (voff)[_i]), (PG8_LAS unsigned*)(lds + (bufoff) + ldsw + _i * 8192), 16, 0, 0); } while (0)
; #define PG8_LDA(dst, b, h) do { _Pragma("unroll") for (int m = 0; m < 4; ++m) _Pragma("unroll") for (int k = 0; k < 2; ++k) dst[m][k] = *(const PG8_LAS bf16x8*)(lds + PG8_SA(b, h) + aoff + m * 2048 + k * 1024); } while (0)
; #define PG8_LDB(dst, b, h) do { _Pragma("unroll") for (int n = 0; n < 2; ++n) _Pragma("unroll") for (int k = 0; k < 2; ++k) dst[n][k] = *(const PG8_LAS bf16x8*)(lds + PG8_SB(b, h) + boff + n * 2048 + k * 1024); } while (0)
; #define PG8_MMA(ai, bj, At, Bt) do { __builtin_amdgcn_s_setprio(1); _Pragma("unroll") for (int m = 0; m < 4; ++m) _Pragma("unroll") for (int n = 0; n < 2; ++n) _Pragma("unroll") for (int k = 0; k < 2; ++k) \
;         acc[ai][bj][m][n] = __builtin_amdgcn_mfma_f32_16x16x32_bf16(Bt[n][k], At[m][k], acc[ai][bj][m][n], 0, 0, 0); __builtin_amdgcn_s_setprio(0); } while (0)
; #define PG8_WAIT_V(n) asm volatile("s_waitcnt vmcnt(" #n ")" ::: "memory")
; #define PG8_WAIT_L(n) asm volatile("s_waitcnt lgkmcnt(" #n ")" ::: "memory")
; #define PG8_BAR __builtin_amdgcn_s_barrier()
; #define PG8_SCHED __builtin_amdgcn_sched_barrier(0)
; template <class Epi, class Sched, bool ALIGN_EPI = false, bool SP2 = false, bool A_TILED = false, bool B_TILED = false>
; __device__ __forceinline__ void gemm_phase(PG8_LAS unsigned char* lds, const Gemm g, const Sched& S, const Epi& E) {
;     ...
;             PG8_LDB(B0, 0, 0); PG8_LDB(B1, 0, 1); PG8_SCHED; PG8_LDA(At, 0, 0); PG8_STAGE(PG8_SA(1, 1), a1 + hstepA, voffA);
;             PG8_WAIT_V(8); PG8_WAIT_L(0); PG8_BAR; PG8_MMA(0, 0, At, B0); PG8_MMA(0, 1, At, B1); PG8_BAR; PG8_SCHED;
;             PG8_LDA(At, 0, 1); PG8_STAGE(PG8_SB(0, 0), b2, voffB); PG8_STAGE(PG8_SB(0, 1), b2 + hstepB, voffB); PG8_STAGE(PG8_SA(0, 0), a2, voffA);
.LBB0_513:
	v_add_u32_e32 v3, s62, v161
	s_waitcnt lgkmcnt(0)
	ds_read_b128 v[152:155], v3
	ds_read_b128 v[174:177], v3 offset:1024
	ds_read_b128 v[178:181], v3 offset:2048
	ds_read_b128 v[182:185], v3 offset:3072
	v_add_u32_e32 v3, s63, v161
	ds_read_b128 v[190:193], v3
	ds_read_b128 v[196:199], v3 offset:1024
	ds_read_b128 v[200:203], v3 offset:2048
	ds_read_b128 v[204:207], v3 offset:3072
	s_add_u32 s42, s12, 0xfff00080
	s_addc_u32 s43, s13, -1
	s_cmp_eq_u32 s68, 28
	s_cselect_b32 s45, s11, s43
	s_cselect_b32 s44, s35, s42
	s_cselect_b32 s43, s31, s67
	s_cselect_b32 s42, s37, s66
	v_lshl_add_u64 v[4:5], s[12:13], 0, v[144:145]
	s_add_i32 m0, s54, 0xc000
	ds_read_b128 v[208:211], v170
	ds_read_b128 v[212:215], v170 offset:1024
	ds_read_b128 v[216:219], v170 offset:2048
	ds_read_b128 v[220:223], v170 offset:3072
	ds_read_b128 v[224:227], v170 offset:4096
	ds_read_b128 v[228:231], v170 offset:5120
	ds_read_b128 v[232:235], v170 offset:6144
	ds_read_b128 v[236:239], v170 offset:7168
	global_load_lds_dwordx4 v[4:5], off
	v_lshl_add_u64 v[4:5], s[12:13], 0, v[146:147]
	s_add_i32 m0, s54, 0xe000
	s_nop 0
	global_load_lds_dwordx4 v[4:5], off
	s_waitcnt vmcnt(8)
	s_waitcnt lgkmcnt(0)
	s_barrier
	s_setprio 1
	s_waitcnt lgkmcnt(0)
	v_mfma_f32_16x16x32_bf16 v[130:133], v[152:155], v[208:211], v[130:133]
	v_mfma_f32_16x16x32_bf16 v[126:129], v[178:181], v[208:211], v[126:129]
	v_mfma_f32_16x16x32_bf16 v[118:121], v[178:181], v[216:219], v[118:121]
	v_mfma_f32_16x16x32_bf16 v[122:125], v[152:155], v[216:219], v[122:125]
	v_mfma_f32_16x16x32_bf16 v[114:117], v[152:155], v[224:227], v[114:117]
	v_mfma_f32_16x16x32_bf16 v[110:113], v[178:181], v[224:227], v[110:113]
	v_mfma_f32_16x16x32_bf16 v[102:105], v[178:181], v[232:235], v[102:105]
	v_mfma_f32_16x16x32_bf16 v[106:109], v[152:155], v[232:235], v[106:109]
	v_mfma_f32_16x16x32_bf16 v[130:133], v[174:177], v[212:215], v[130:133]
	v_mfma_f32_16x16x32_bf16 v[126:129], v[182:185], v[212:215], v[126:129]
	v_mfma_f32_16x16x32_bf16 v[118:121], v[182:185], v[220:223], v[118:121]
	v_mfma_f32_16x16x32_bf16 v[122:125], v[174:177], v[220:223], v[122:125]
	v_mfma_f32_16x16x32_bf16 v[114:117], v[174:177], v[228:231], v[114:117]
	v_mfma_f32_16x16x32_bf16 v[110:113], v[182:185], v[228:231], v[110:113]
	v_mfma_f32_16x16x32_bf16 v[102:105], v[182:185], v[236:239], v[102:105]
	v_mfma_f32_16x16x32_bf16 v[106:109], v[174:177], v[236:239], v[106:109]
	s_setprio 0
	s_setprio 1
	v_mfma_f32_16x16x32_bf16 v[98:101], v[190:193], v[208:211], v[98:101]
	v_mfma_f32_16x16x32_bf16 v[94:97], v[200:203], v[208:211], v[94:97]
	v_mfma_f32_16x16x32_bf16 v[86:89], v[200:203], v[216:219], v[86:89]
	v_mfma_f32_16x16x32_bf16 v[90:93], v[190:193], v[216:219], v[90:93]
	v_mfma_f32_16x16x32_bf16 v[82:85], v[190:193], v[224:227], v[82:85]
	v_mfma_f32_16x16x32_bf16 v[78:81], v[200:203], v[224:227], v[78:81]
	v_mfma_f32_16x16x32_bf16 v[70:73], v[200:203], v[232:235], v[70:73]
	v_mfma_f32_16x16x32_bf16 v[74:77], v[190:193], v[232:235], v[74:77]
	v_mfma_f32_16x16x32_bf16 v[98:101], v[196:199], v[212:215], v[98:101]
	v_mfma_f32_16x16x32_bf16 v[94:97], v[204:207], v[212:215], v[94:97]
	v_mfma_f32_16x16x32_bf16 v[86:89], v[204:207], v[220:223], v[86:89]
	v_mfma_f32_16x16x32_bf16 v[90:93], v[196:199], v[220:223], v[90:93]
	v_mfma_f32_16x16x32_bf16 v[82:85], v[196:199], v[228:231], v[82:85]
	v_mfma_f32_16x16x32_bf16 v[78:81], v[204:207], v[228:231], v[78:81]
	v_mfma_f32_16x16x32_bf16 v[70:73], v[204:207], v[236:239], v[70:73]
	v_mfma_f32_16x16x32_bf16 v[74:77], v[196:199], v[236:239], v[74:77]
	s_setprio 0
	s_barrier
	s_add_i32 s69, s62, s53
	v_lshl_add_u64 v[186:187], s[42:43], 0, v[140:141]
	s_mov_b32 m0, s69
	ds_read_b128 v[208:211], v170 offset:16384
	ds_read_b128 v[212:215], v170 offset:17408
	ds_read_b128 v[216:219], v170 offset:18432
	ds_read_b128 v[220:223], v170 offset:19456
	ds_read_b128 v[224:227], v170 offset:20480
	ds_read_b128 v[228:231], v170 offset:21504
	ds_read_b128 v[232:235], v170 offset:22528
	ds_read_b128 v[236:239], v170 offset:23552
	global_load_lds_dwordx4 v[186:187], off
	s_add_i32 m0, s69, 0x2000
	s_add_u32 s70, s42, 0x100000
	v_lshl_add_u64 v[240:241], s[42:43], 0, v[142:143]
	s_addc_u32 s71, s43, 0
	s_add_i32 s69, s63, s53
	global_load_lds_dwordx4 v[240:241], off
	v_lshl_add_u64 v[4:5], s[70:71], 0, v[140:141]
	s_mov_b32 m0, s69
	v_lshl_add_u64 v[242:243], s[44:45], 0, v[134:135]
	global_load_lds_dwordx4 v[4:5], off
	v_lshl_add_u64 v[4:5], s[70:71], 0, v[142:143]
	s_add_i32 m0, s69, 0x2000
	v_lshl_add_u64 v[244:245], s[44:45], 0, v[136:137]
	global_load_lds_dwordx4 v[4:5], off
	s_mov_b32 m0, s54
	s_nop 0
	global_load_lds_dwordx4 v[242:243], off
	s_mov_b32 m0, s55
	s_nop 0
	global_load_lds_dwordx4 v[244:245], off
	s_waitcnt vmcnt(8)
	s_waitcnt lgkmcnt(0)
	s_barrier
; #define PG8_STAGE(bufoff, gbase, voff) do { _Pragma("unroll") for (int _i = 0; _i < 2; ++_i) \
;         __builtin_amdgcn_global_load_lds((const unsigned*)((const char*)(gbase) + (voff)[_i]), (PG8_LAS unsigned*)(lds + (bufoff) + ldsw + _i * 8192), 16, 0, 0); } while (0)
; #define PG8_LDA(dst, b, h) do { _Pragma("unroll") for (int m = 0; m < 4; ++m) _Pragma("unroll") for (int k = 0; k < 2; ++k) dst[m][k] = *(const PG8_LAS bf16x8*)(lds + PG8_SA(b, h) + aoff + m * 2048 + k * 1024); } while (0)
; #define PG8_LDB(dst, b, h) do { _Pragma("unroll") for (int n = 0; n < 2; ++n) _Pragma("unroll") for (int k = 0; k < 2; ++k) dst[n][k] = *(const PG8_LAS bf16x8*)(lds + PG8_SB(b, h) + boff + n * 2048 + k * 1024); } while (0)
; #define PG8_MMA(ai, bj, At, Bt) do { __builtin_amdgcn_s_setprio(1); _Pragma("unroll") for (int m = 0; m < 4; ++m) _Pragma("unroll") for (int n = 0; n < 2; ++n) _Pragma("unroll") for (int k = 0; k < 2; ++k) \
;         acc[ai][bj][m][n] = __builtin_amdgcn_mfma_f32_16x16x32_bf16(Bt[n][k], At[m][k], acc[ai][bj][m][n], 0, 0, 0); __builtin_amdgcn_s_setprio(0); } while (0)
; #define PG8_WAIT_V(n) asm volatile("s_waitcnt vmcnt(" #n ")" ::: "memory")
; #define PG8_WAIT_L(n) asm volatile("s_waitcnt lgkmcnt(" #n ")" ::: "memory")
; #define PG8_BAR __builtin_amdgcn_s_barrier()
; #define PG8_SCHED __builtin_amdgcn_sched_barrier(0)
; template <class Epi, class Sched, bool ALIGN_EPI = false, bool SP2 = false, bool A_TILED = false, bool B_TILED = false>
; __device__ __forceinline__ void gemm_phase(PG8_LAS unsigned char* lds, const Gemm g, const Sched& S, const Epi& E) {
;     ...
;             PG8_WAIT_V(8); PG8_WAIT_L(0); PG8_BAR; PG8_MMA(1, 0, At, B0); PG8_MMA(1, 1, At, B1); PG8_BAR; PG8_SCHED;
;             PG8_LDB(B0, 1, 0); PG8_LDB(B1, 1, 1); PG8_SCHED; PG8_LDA(At, 1, 0); PG8_STAGE(PG8_SA(0, 1), a2 + hstepA, voffA);
;             PG8_WAIT_V(8); PG8_WAIT_L(0); PG8_BAR; PG8_MMA(0, 0, At, B0); PG8_MMA(0, 1, At, B1); PG8_BAR; PG8_SCHED;
	s_setprio 1
	s_waitcnt lgkmcnt(0)
	v_mfma_f32_16x16x32_bf16 v[66:69], v[152:155], v[208:211], v[66:69]
	v_mfma_f32_16x16x32_bf16 v[62:65], v[178:181], v[208:211], v[62:65]
	v_mfma_f32_16x16x32_bf16 v[54:57], v[178:181], v[216:219], v[54:57]
	v_mfma_f32_16x16x32_bf16 v[58:61], v[152:155], v[216:219], v[58:61]
	v_mfma_f32_16x16x32_bf16 v[50:53], v[152:155], v[224:227], v[50:53]
	v_mfma_f32_16x16x32_bf16 v[46:49], v[178:181], v[224:227], v[46:49]
	v_mfma_f32_16x16x32_bf16 v[38:41], v[178:181], v[232:235], v[38:41]
	v_mfma_f32_16x16x32_bf16 v[42:45], v[152:155], v[232:235], v[42:45]
	v_mfma_f32_16x16x32_bf16 v[66:69], v[174:177], v[212:215], v[66:69]
	v_mfma_f32_16x16x32_bf16 v[62:65], v[182:185], v[212:215], v[62:65]
	v_mfma_f32_16x16x32_bf16 v[54:57], v[182:185], v[220:223], v[54:57]
	v_mfma_f32_16x16x32_bf16 v[58:61], v[174:177], v[220:223], v[58:61]
	v_mfma_f32_16x16x32_bf16 v[50:53], v[174:177], v[228:231], v[50:53]
	v_mfma_f32_16x16x32_bf16 v[46:49], v[182:185], v[228:231], v[46:49]
	v_mfma_f32_16x16x32_bf16 v[38:41], v[182:185], v[236:239], v[38:41]
	v_mfma_f32_16x16x32_bf16 v[42:45], v[174:177], v[236:239], v[42:45]
	s_setprio 0
	s_setprio 1
	v_mfma_f32_16x16x32_bf16 v[34:37], v[190:193], v[208:211], v[34:37]
	v_mfma_f32_16x16x32_bf16 v[30:33], v[200:203], v[208:211], v[30:33]
	v_mfma_f32_16x16x32_bf16 v[22:25], v[200:203], v[216:219], v[22:25]
	v_mfma_f32_16x16x32_bf16 v[26:29], v[190:193], v[216:219], v[26:29]
	v_mfma_f32_16x16x32_bf16 v[18:21], v[190:193], v[224:227], v[18:21]
	v_mfma_f32_16x16x32_bf16 v[14:17], v[200:203], v[224:227], v[14:17]
	v_mfma_f32_16x16x32_bf16 v[4:7], v[200:203], v[232:235], v[6:9]
	v_mfma_f32_16x16x32_bf16 v[10:13], v[190:193], v[232:235], v[10:13]
	v_mfma_f32_16x16x32_bf16 v[34:37], v[196:199], v[212:215], v[34:37]
	v_mfma_f32_16x16x32_bf16 v[30:33], v[204:207], v[212:215], v[30:33]
	v_mfma_f32_16x16x32_bf16 v[22:25], v[204:207], v[220:223], v[22:25]
	v_mfma_f32_16x16x32_bf16 v[26:29], v[196:199], v[220:223], v[26:29]
	v_mfma_f32_16x16x32_bf16 v[18:21], v[196:199], v[228:231], v[18:21]
	v_mfma_f32_16x16x32_bf16 v[14:17], v[204:207], v[228:231], v[14:17]
	v_mfma_f32_16x16x32_bf16 v[4:7], v[204:207], v[236:239], v[4:7]
	v_mfma_f32_16x16x32_bf16 v[10:13], v[196:199], v[236:239], v[10:13]
	s_setprio 0
	s_barrier
	s_add_i32 s69, 0, 0x18000
	v_add_u32_e32 v3, s69, v161
	s_add_i32 s70, 0, 0x1c000
	ds_read_b128 v[152:155], v3
	ds_read_b128 v[174:177], v3 offset:1024
	ds_read_b128 v[178:181], v3 offset:2048
	ds_read_b128 v[182:185], v3 offset:3072
	v_add_u32_e32 v3, s70, v161
	ds_read_b128 v[190:193], v3
	ds_read_b128 v[196:199], v3 offset:1024
	ds_read_b128 v[200:203], v3 offset:2048
	ds_read_b128 v[204:207], v3 offset:3072
	s_add_u32 s44, s44, 0x100000
	s_addc_u32 s45, s45, 0
	s_mov_b32 m0, s56
	v_lshl_add_u64 v[8:9], s[44:45], 0, v[134:135]
	ds_read_b128 v[208:211], v170 offset:32768
	ds_read_b128 v[212:215], v170 offset:33792
	ds_read_b128 v[216:219], v170 offset:34816
	ds_read_b128 v[220:223], v170 offset:35840
	ds_read_b128 v[224:227], v170 offset:36864
	ds_read_b128 v[228:231], v170 offset:37888
	ds_read_b128 v[232:235], v170 offset:38912
	ds_read_b128 v[236:239], v170 offset:39936
	global_load_lds_dwordx4 v[8:9], off
	v_lshl_add_u64 v[8:9], s[44:45], 0, v[136:137]
	s_mov_b32 m0, s57
	s_nop 0
	global_load_lds_dwordx4 v[8:9], off
	s_waitcnt vmcnt(8)
	s_waitcnt lgkmcnt(0)
	s_barrier
	s_setprio 1
	s_waitcnt lgkmcnt(0)
	v_mfma_f32_16x16x32_bf16 v[130:133], v[152:155], v[208:211], v[130:133]
	v_mfma_f32_16x16x32_bf16 v[126:129], v[178:181], v[208:211], v[126:129]
	v_mfma_f32_16x16x32_bf16 v[118:121], v[178:181], v[216:219], v[118:121]
	v_mfma_f32_16x16x32_bf16 v[122:125], v[152:155], v[216:219], v[122:125]
	v_mfma_f32_16x16x32_bf16 v[114:117], v[152:155], v[224:227], v[114:117]
	v_mfma_f32_16x16x32_bf16 v[110:113], v[178:181], v[224:227], v[110:113]
	v_mfma_f32_16x16x32_bf16 v[102:105], v[178:181], v[232:235], v[102:105]
	v_mfma_f32_16x16x32_bf16 v[106:109], v[152:155], v[232:235], v[106:109]
	v_mfma_f32_16x16x32_bf16 v[130:133], v[174:177], v[212:215], v[130:133]
	v_mfma_f32_16x16x32_bf16 v[126:129], v[182:185], v[212:215], v[126:129]
	v_mfma_f32_16x16x32_bf16 v[118:121], v[182:185], v[220:223], v[118:121]
	v_mfma_f32_16x16x32_bf16 v[122:125], v[174:177], v[220:223], v[122:125]
	v_mfma_f32_16x16x32_bf16 v[114:117], v[174:177], v[228:231], v[114:117]
	v_mfma_f32_16x16x32_bf16 v[110:113], v[182:185], v[228:231], v[110:113]
	v_mfma_f32_16x16x32_bf16 v[102:105], v[182:185], v[236:239], v[102:105]
	v_mfma_f32_16x16x32_bf16 v[106:109], v[174:177], v[236:239], v[106:109]
	s_setprio 0
	s_setprio 1
	v_mfma_f32_16x16x32_bf16 v[98:101], v[190:193], v[208:211], v[98:101]
	v_mfma_f32_16x16x32_bf16 v[94:97], v[200:203], v[208:211], v[94:97]
	v_mfma_f32_16x16x32_bf16 v[86:89], v[200:203], v[216:219], v[86:89]
	v_mfma_f32_16x16x32_bf16 v[90:93], v[190:193], v[216:219], v[90:93]
	v_mfma_f32_16x16x32_bf16 v[82:85], v[190:193], v[224:227], v[82:85]
	v_mfma_f32_16x16x32_bf16 v[78:81], v[200:203], v[224:227], v[78:81]
	v_mfma_f32_16x16x32_bf16 v[70:73], v[200:203], v[232:235], v[70:73]
	v_mfma_f32_16x16x32_bf16 v[74:77], v[190:193], v[232:235], v[74:77]
	v_mfma_f32_16x16x32_bf16 v[98:101], v[196:199], v[212:215], v[98:101]
	v_mfma_f32_16x16x32_bf16 v[94:97], v[204:207], v[212:215], v[94:97]
	v_mfma_f32_16x16x32_bf16 v[86:89], v[204:207], v[220:223], v[86:89]
	v_mfma_f32_16x16x32_bf16 v[90:93], v[196:199], v[220:223], v[90:93]
	v_mfma_f32_16x16x32_bf16 v[82:85], v[196:199], v[228:231], v[82:85]
	v_mfma_f32_16x16x32_bf16 v[78:81], v[204:207], v[228:231], v[78:81]
	v_mfma_f32_16x16x32_bf16 v[70:73], v[204:207], v[236:239], v[70:73]
	v_mfma_f32_16x16x32_bf16 v[74:77], v[196:199], v[236:239], v[74:77]
	s_setprio 0
	s_barrier
; #define PG8_STAGE(bufoff, gbase, voff) do { _Pragma("unroll") for (int _i = 0; _i < 2; ++_i) \
;         __builtin_amdgcn_global_load_lds((const unsigned*)((const char*)(gbase) + (voff)[_i]), (PG8_LAS unsigned*)(lds + (bufoff) + ldsw + _i * 8192), 16, 0, 0); } while (0)
; #define PG8_LDA(dst, b, h) do { _Pragma("unroll") for (int m = 0; m < 4; ++m) _Pragma("unroll") for (int k = 0; k < 2; ++k) dst[m][k] = *(const PG8_LAS bf16x8*)(lds + PG8_SA(b, h) + aoff + m * 2048 + k * 1024); } while (0)
; #define PG8_MMA(ai, bj, At, Bt) do { __builtin_amdgcn_s_setprio(1); _Pragma("unroll") for (int m = 0; m < 4; ++m) _Pragma("unroll") for (int n = 0; n < 2; ++n) _Pragma("unroll") for (int k = 0; k < 2; ++k) \
;         acc[ai][bj][m][n] = __builtin_amdgcn_mfma_f32_16x16x32_bf16(Bt[n][k], At[m][k], acc[ai][bj][m][n], 0, 0, 0); __builtin_amdgcn_s_setprio(0); } while (0)
; #define PG8_WAIT_V(n) asm volatile("s_waitcnt vmcnt(" #n ")" ::: "memory")
; #define PG8_WAIT_L(n) asm volatile("s_waitcnt lgkmcnt(" #n ")" ::: "memory")
; #define PG8_BAR __builtin_amdgcn_s_barrier()
; #define PG8_SCHED __builtin_amdgcn_sched_barrier(0)
; template <class Epi, class Sched, bool ALIGN_EPI = false, bool SP2 = false, bool A_TILED = false, bool B_TILED = false>
; __device__ __forceinline__ void gemm_phase(PG8_LAS unsigned char* lds, const Gemm g, const Sched& S, const Epi& E) {
;     ...
;             PG8_LDA(At, 1, 1); PG8_STAGE(PG8_SB(1, 0), b3, voffB); PG8_STAGE(PG8_SB(1, 1), b3 + hstepB, voffB); PG8_STAGE(PG8_SA(1, 0), a3, voffA);
;             PG8_WAIT_V(8); PG8_WAIT_L(0); PG8_BAR; PG8_MMA(1, 0, At, B0); PG8_MMA(1, 1, At, B1); PG8_BAR; PG8_SCHED;
	s_add_i32 s44, s69, s53
	v_lshl_add_u64 v[8:9], v[186:187], 0, s[26:27]
	s_mov_b32 m0, s44
	ds_read_b128 v[208:211], v170 offset:49152
	ds_read_b128 v[212:215], v170 offset:50176
	ds_read_b128 v[216:219], v170 offset:51200
	ds_read_b128 v[220:223], v170 offset:52224
	ds_read_b128 v[224:227], v170 offset:53248
	ds_read_b128 v[228:231], v170 offset:54272
	ds_read_b128 v[232:235], v170 offset:55296
	ds_read_b128 v[236:239], v170 offset:56320
	global_load_lds_dwordx4 v[8:9], off
	s_add_i32 m0, s44, 0x2000
	s_add_u32 s42, s42, 0x100080
	v_lshl_add_u64 v[8:9], v[240:241], 0, s[26:27]
	s_addc_u32 s43, s43, 0
	s_add_i32 s44, s70, s53
	global_load_lds_dwordx4 v[8:9], off
	v_lshl_add_u64 v[8:9], s[42:43], 0, v[140:141]
	s_mov_b32 m0, s44
	s_nop 0
	global_load_lds_dwordx4 v[8:9], off
	v_lshl_add_u64 v[8:9], s[42:43], 0, v[142:143]
	s_add_i32 m0, s44, 0x2000
	s_nop 0
	global_load_lds_dwordx4 v[8:9], off
	v_lshl_add_u64 v[8:9], v[242:243], 0, s[26:27]
	s_mov_b32 m0, s59
	s_nop 0
	global_load_lds_dwordx4 v[8:9], off
	v_lshl_add_u64 v[8:9], v[244:245], 0, s[26:27]
	s_mov_b32 m0, s60
	s_nop 0
	global_load_lds_dwordx4 v[8:9], off
	s_waitcnt vmcnt(8)
	s_waitcnt lgkmcnt(0)
	s_barrier
	s_setprio 1
	s_waitcnt lgkmcnt(0)
	v_mfma_f32_16x16x32_bf16 v[66:69], v[152:155], v[208:211], v[66:69]
	v_mfma_f32_16x16x32_bf16 v[62:65], v[178:181], v[208:211], v[62:65]
	v_mfma_f32_16x16x32_bf16 v[54:57], v[178:181], v[216:219], v[54:57]
	v_mfma_f32_16x16x32_bf16 v[58:61], v[152:155], v[216:219], v[58:61]
	v_mfma_f32_16x16x32_bf16 v[50:53], v[152:155], v[224:227], v[50:53]
	v_mfma_f32_16x16x32_bf16 v[46:49], v[178:181], v[224:227], v[46:49]
	v_mfma_f32_16x16x32_bf16 v[38:41], v[178:181], v[232:235], v[38:41]
	v_mfma_f32_16x16x32_bf16 v[42:45], v[152:155], v[232:235], v[42:45]
	v_mfma_f32_16x16x32_bf16 v[66:69], v[174:177], v[212:215], v[66:69]
	v_mfma_f32_16x16x32_bf16 v[62:65], v[182:185], v[212:215], v[62:65]
	v_mfma_f32_16x16x32_bf16 v[54:57], v[182:185], v[220:223], v[54:57]
	v_mfma_f32_16x16x32_bf16 v[58:61], v[174:177], v[220:223], v[58:61]
	v_mfma_f32_16x16x32_bf16 v[50:53], v[174:177], v[228:231], v[50:53]
	v_mfma_f32_16x16x32_bf16 v[46:49], v[182:185], v[228:231], v[46:49]
	v_mfma_f32_16x16x32_bf16 v[38:41], v[182:185], v[236:239], v[38:41]
	v_mfma_f32_16x16x32_bf16 v[42:45], v[174:177], v[236:239], v[42:45]
	s_setprio 0
	s_setprio 1
	v_mfma_f32_16x16x32_bf16 v[34:37], v[190:193], v[208:211], v[34:37]
	v_mfma_f32_16x16x32_bf16 v[30:33], v[200:203], v[208:211], v[30:33]
	v_mfma_f32_16x16x32_bf16 v[22:25], v[200:203], v[216:219], v[22:25]
	v_mfma_f32_16x16x32_bf16 v[26:29], v[190:193], v[216:219], v[26:29]
	v_mfma_f32_16x16x32_bf16 v[18:21], v[190:193], v[224:227], v[18:21]
	v_mfma_f32_16x16x32_bf16 v[14:17], v[200:203], v[224:227], v[14:17]
	v_mfma_f32_16x16x32_bf16 v[4:7], v[200:203], v[232:235], v[4:7]
	v_mfma_f32_16x16x32_bf16 v[8:11], v[190:193], v[232:235], v[10:13]
	v_mfma_f32_16x16x32_bf16 v[34:37], v[196:199], v[212:215], v[34:37]
	v_mfma_f32_16x16x32_bf16 v[30:33], v[204:207], v[212:215], v[30:33]
	v_mfma_f32_16x16x32_bf16 v[22:25], v[204:207], v[220:223], v[22:25]
	v_mfma_f32_16x16x32_bf16 v[26:29], v[196:199], v[220:223], v[26:29]
	v_mfma_f32_16x16x32_bf16 v[18:21], v[196:199], v[228:231], v[18:21]
	v_mfma_f32_16x16x32_bf16 v[14:17], v[204:207], v[228:231], v[14:17]
	v_mfma_f32_16x16x32_bf16 v[6:9], v[204:207], v[236:239], v[4:7]
	v_mfma_f32_16x16x32_bf16 v[10:13], v[196:199], v[236:239], v[8:11]
	s_setprio 0
	s_barrier
	s_add_i32 s68, s68, 2
	s_add_u32 s12, s12, 0x100
	s_addc_u32 s13, s13, 0
	s_add_u32 s66, s66, 0x100
	s_addc_u32 s67, s67, 0
	s_cmp_gt_u32 s68, 29
	s_cbranch_scc0 .LBB0_513
	s_and_b64 vcc, exec, s[28:29]
	s_cbranch_vccz .LBB0_516
	s_barrier

; #define PG8_STAGE(bufoff, gbase, voff) do { _Pragma("unroll") for (int _i = 0; _i < 2; ++_i) \
;         __builtin_amdgcn_global_load_lds((const unsigned*)((const char*)(gbase) + (voff)[_i]), (PG8_LAS unsigned*)(lds + (bufoff) + ldsw + _i * 8192), 16, 0, 0); } while (0)
; #define PG8_LDA(dst, b, h) do { _Pragma("unroll") for (int m = 0; m < 4; ++m) _Pragma("unroll") for (int k = 0; k < 2; ++k) dst[m][k] = *(const PG8_LAS bf16x8*)(lds + PG8_SA(b, h) + aoff + m * 2048 + k * 1024); } while (0)
; #define PG8_LDB(dst, b, h) do { _Pragma("unroll") for (int n = 0; n < 2; ++n) _Pragma("unroll") for (int k = 0; k < 2; ++k) dst[n][k] = *(const PG8_LAS bf16x8*)(lds + PG8_SB(b, h) + boff + n * 2048 + k * 1024); } while (0)
; #define PG8_MMA(ai, bj, At, Bt) do { __builtin_amdgcn_s_setprio(1); _Pragma("unroll") for (int m = 0; m < 4; ++m) _Pragma("unroll") for (int n = 0; n < 2; ++n) _Pragma("unroll") for (int k = 0; k < 2; ++k) \
;         acc[ai][bj][m][n] = __builtin_amdgcn_mfma_f32_16x16x32_bf16(Bt[n][k], At[m][k], acc[ai][bj][m][n], 0, 0, 0); __builtin_amdgcn_s_setprio(0); } while (0)
; #define PG8_WAIT_V(n) asm volatile("s_waitcnt vmcnt(" #n ")" ::: "memory")
; #define PG8_WAIT_L(n) asm volatile("s_waitcnt lgkmcnt(" #n ")" ::: "memory")
; #define PG8_BAR __builtin_amdgcn_s_barrier()
; #define PG8_SCHED __builtin_amdgcn_sched_barrier(0)
; template <class Epi, class Sched, bool ALIGN_EPI = false, bool SP2 = false, bool A_TILED = false, bool B_TILED = false>
; __device__ __forceinline__ void gemm_phase(PG8_LAS unsigned char* lds, const Gemm g, const Sched& S, const Epi& E) {
;     ...
;             PG8_LDB(B0, 0, 0); PG8_LDB(B1, 0, 1); PG8_SCHED; PG8_LDA(At, 0, 0); PG8_STAGE(PG8_SA(1, 1), a1 + hstepA, voffA);
;             PG8_WAIT_V(8); PG8_WAIT_L(0); PG8_BAR; PG8_MMA(0, 0, At, B0); PG8_MMA(0, 1, At, B1); PG8_BAR; PG8_SCHED;
;             PG8_LDA(At, 0, 1); PG8_STAGE(PG8_SB(0, 0), b2, voffB); PG8_STAGE(PG8_SB(0, 1), b2 + hstepB, voffB); PG8_STAGE(PG8_SA(0, 0), a2, voffA);
.LBB0_553:
	ds_read_b128 v[158:161], v1
	ds_read_b128 v[162:165], v1 offset:1024
	ds_read_b128 v[166:169], v1 offset:2048
	ds_read_b128 v[170:173], v1 offset:3072
	ds_read_b128 v[174:177], v153
	ds_read_b128 v[178:181], v153 offset:1024
	ds_read_b128 v[182:185], v153 offset:2048
	ds_read_b128 v[190:193], v153 offset:3072
	s_add_u32 s38, s36, 0xfff00080
	s_addc_u32 s39, s37, -1
	s_cmp_eq_u32 s59, 12
	s_cselect_b32 s41, s5, s39
	s_cselect_b32 s40, s7, s38
	s_cselect_b32 s39, s23, s58
	s_cselect_b32 s38, s25, s27
	v_lshl_add_u64 v[140:141], s[36:37], 0, v[132:133]
	s_add_i32 m0, s19, 0xc000
	ds_read_b128 v[196:199], v154
	ds_read_b128 v[200:203], v154 offset:1024
	ds_read_b128 v[204:207], v154 offset:2048
	ds_read_b128 v[208:211], v154 offset:3072
	ds_read_b128 v[212:215], v154 offset:4096
	ds_read_b128 v[216:219], v154 offset:5120
	ds_read_b128 v[220:223], v154 offset:6144
	ds_read_b128 v[224:227], v154 offset:7168
	global_load_lds_dwordx4 v[140:141], off
	v_lshl_add_u64 v[140:141], s[36:37], 0, v[138:139]
	s_add_i32 m0, s19, 0xe000
	s_nop 0
	global_load_lds_dwordx4 v[140:141], off
	s_waitcnt vmcnt(8)
	s_waitcnt lgkmcnt(0)
	s_barrier
	s_setprio 1
	s_waitcnt lgkmcnt(0)
	v_mfma_f32_16x16x32_bf16 v[126:129], v[158:161], v[196:199], v[126:129]
	v_mfma_f32_16x16x32_bf16 v[122:125], v[166:169], v[196:199], v[122:125]
	v_mfma_f32_16x16x32_bf16 v[106:109], v[166:169], v[204:207], v[106:109]
	v_mfma_f32_16x16x32_bf16 v[110:113], v[158:161], v[204:207], v[110:113]
	v_mfma_f32_16x16x32_bf16 v[94:97], v[158:161], v[212:215], v[94:97]
	v_mfma_f32_16x16x32_bf16 v[90:93], v[166:169], v[212:215], v[90:93]
	v_mfma_f32_16x16x32_bf16 v[74:77], v[166:169], v[220:223], v[74:77]
	v_mfma_f32_16x16x32_bf16 v[78:81], v[158:161], v[220:223], v[78:81]
	v_mfma_f32_16x16x32_bf16 v[126:129], v[162:165], v[200:203], v[126:129]
	v_mfma_f32_16x16x32_bf16 v[122:125], v[170:173], v[200:203], v[122:125]
	v_mfma_f32_16x16x32_bf16 v[106:109], v[170:173], v[208:211], v[106:109]
	v_mfma_f32_16x16x32_bf16 v[110:113], v[162:165], v[208:211], v[110:113]
	v_mfma_f32_16x16x32_bf16 v[94:97], v[162:165], v[216:219], v[94:97]
	v_mfma_f32_16x16x32_bf16 v[90:93], v[170:173], v[216:219], v[90:93]
	v_mfma_f32_16x16x32_bf16 v[74:77], v[170:173], v[224:227], v[74:77]
	v_mfma_f32_16x16x32_bf16 v[78:81], v[162:165], v[224:227], v[78:81]
	s_setprio 0
	s_setprio 1
	v_mfma_f32_16x16x32_bf16 v[118:121], v[174:177], v[196:199], v[118:121]
	v_mfma_f32_16x16x32_bf16 v[114:117], v[182:185], v[196:199], v[114:117]
	v_mfma_f32_16x16x32_bf16 v[98:101], v[182:185], v[204:207], v[98:101]
	v_mfma_f32_16x16x32_bf16 v[102:105], v[174:177], v[204:207], v[102:105]
	v_mfma_f32_16x16x32_bf16 v[86:89], v[174:177], v[212:215], v[86:89]
	v_mfma_f32_16x16x32_bf16 v[82:85], v[182:185], v[212:215], v[82:85]
	v_mfma_f32_16x16x32_bf16 v[66:69], v[182:185], v[220:223], v[66:69]
	v_mfma_f32_16x16x32_bf16 v[70:73], v[174:177], v[220:223], v[70:73]
	v_mfma_f32_16x16x32_bf16 v[118:121], v[178:181], v[200:203], v[118:121]
	v_mfma_f32_16x16x32_bf16 v[114:117], v[190:193], v[200:203], v[114:117]
	v_mfma_f32_16x16x32_bf16 v[98:101], v[190:193], v[208:211], v[98:101]
	v_mfma_f32_16x16x32_bf16 v[102:105], v[178:181], v[208:211], v[102:105]
	v_mfma_f32_16x16x32_bf16 v[86:89], v[178:181], v[216:219], v[86:89]
	v_mfma_f32_16x16x32_bf16 v[82:85], v[190:193], v[216:219], v[82:85]
	v_mfma_f32_16x16x32_bf16 v[66:69], v[190:193], v[224:227], v[66:69]
	v_mfma_f32_16x16x32_bf16 v[70:73], v[178:181], v[224:227], v[70:73]
	s_setprio 0
	s_barrier
	s_add_i32 s60, s8, s42
	v_lshl_add_u64 v[140:141], s[38:39], 0, v[134:135]
	s_mov_b32 m0, s60
	ds_read_b128 v[196:199], v154 offset:16384
	ds_read_b128 v[200:203], v154 offset:17408
	ds_read_b128 v[204:207], v154 offset:18432
	ds_read_b128 v[208:211], v154 offset:19456
	ds_read_b128 v[212:215], v154 offset:20480
	ds_read_b128 v[216:219], v154 offset:21504
	ds_read_b128 v[220:223], v154 offset:22528
	ds_read_b128 v[224:227], v154 offset:23552
	global_load_lds_dwordx4 v[140:141], off
	s_add_i32 m0, s60, 0x2000
	s_add_u32 s60, s38, 0x100000
	v_lshl_add_u64 v[186:187], s[38:39], 0, v[136:137]
	s_addc_u32 s61, s39, 0
	s_add_i32 s62, s55, s42
	global_load_lds_dwordx4 v[186:187], off
	v_lshl_add_u64 v[228:229], s[60:61], 0, v[134:135]
	s_mov_b32 m0, s62
	v_lshl_add_u64 v[230:231], s[40:41], 0, v[136:137]
	global_load_lds_dwordx4 v[228:229], off
	v_lshl_add_u64 v[228:229], s[60:61], 0, v[136:137]
	s_add_i32 m0, s62, 0x2000
	s_nop 0
	global_load_lds_dwordx4 v[228:229], off
	v_lshl_add_u64 v[228:229], s[40:41], 0, v[134:135]
	s_mov_b32 m0, s19
	s_nop 0
	global_load_lds_dwordx4 v[228:229], off
	s_mov_b32 m0, s43
	s_nop 0
	global_load_lds_dwordx4 v[230:231], off
	s_waitcnt vmcnt(8)
	s_waitcnt lgkmcnt(0)
	s_barrier
; #define PG8_STAGE(bufoff, gbase, voff) do { _Pragma("unroll") for (int _i = 0; _i < 2; ++_i) \
;         __builtin_amdgcn_global_load_lds((const unsigned*)((const char*)(gbase) + (voff)[_i]), (PG8_LAS unsigned*)(lds + (bufoff) + ldsw + _i * 8192), 16, 0, 0); } while (0)
; #define PG8_LDA(dst, b, h) do { _Pragma("unroll") for (int m = 0; m < 4; ++m) _Pragma("unroll") for (int k = 0; k < 2; ++k) dst[m][k] = *(const PG8_LAS bf16x8*)(lds + PG8_SA(b, h) + aoff + m * 2048 + k * 1024); } while (0)
; #define PG8_LDB(dst, b, h) do { _Pragma("unroll") for (int n = 0; n < 2; ++n) _Pragma("unroll") for (int k = 0; k < 2; ++k) dst[n][k] = *(const PG8_LAS bf16x8*)(lds + PG8_SB(b, h) + boff + n * 2048 + k * 1024); } while (0)
; #define PG8_MMA(ai, bj, At, Bt) do { __builtin_amdgcn_s_setprio(1); _Pragma("unroll") for (int m = 0; m < 4; ++m) _Pragma("unroll") for (int n = 0; n < 2; ++n) _Pragma("unroll") for (int k = 0; k < 2; ++k) \
;         acc[ai][bj][m][n] = __builtin_amdgcn_mfma_f32_16x16x32_bf16(Bt[n][k], At[m][k], acc[ai][bj][m][n], 0, 0, 0); __builtin_amdgcn_s_setprio(0); } while (0)
; #define PG8_WAIT_V(n) asm volatile("s_waitcnt vmcnt(" #n ")" ::: "memory")
; #define PG8_WAIT_L(n) asm volatile("s_waitcnt lgkmcnt(" #n ")" ::: "memory")
; #define PG8_BAR __builtin_amdgcn_s_barrier()
; #define PG8_SCHED __builtin_amdgcn_sched_barrier(0)
; template <class Epi, class Sched, bool ALIGN_EPI = false, bool SP2 = false, bool A_TILED = false, bool B_TILED = false>
; __device__ __forceinline__ void gemm_phase(PG8_LAS unsigned char* lds, const Gemm g, const Sched& S, const Epi& E) {
;     ...
;             PG8_WAIT_V(8); PG8_WAIT_L(0); PG8_BAR; PG8_MMA(1, 0, At, B0); PG8_MMA(1, 1, At, B1); PG8_BAR; PG8_SCHED;
;             PG8_LDB(B0, 1, 0); PG8_LDB(B1, 1, 1); PG8_SCHED; PG8_LDA(At, 1, 0); PG8_STAGE(PG8_SA(0, 1), a2 + hstepA, voffA);
;             PG8_WAIT_V(8); PG8_WAIT_L(0); PG8_BAR; PG8_MMA(0, 0, At, B0); PG8_MMA(0, 1, At, B1); PG8_BAR; PG8_SCHED;
	s_setprio 1
	s_waitcnt lgkmcnt(0)
	v_mfma_f32_16x16x32_bf16 v[62:65], v[158:161], v[196:199], v[62:65]
	v_mfma_f32_16x16x32_bf16 v[58:61], v[166:169], v[196:199], v[58:61]
	v_mfma_f32_16x16x32_bf16 v[42:45], v[166:169], v[204:207], v[42:45]
	v_mfma_f32_16x16x32_bf16 v[46:49], v[158:161], v[204:207], v[46:49]
	v_mfma_f32_16x16x32_bf16 v[30:33], v[158:161], v[212:215], v[30:33]
	v_mfma_f32_16x16x32_bf16 v[26:29], v[166:169], v[212:215], v[26:29]
	v_mfma_f32_16x16x32_bf16 v[10:13], v[166:169], v[220:223], v[10:13]
	v_mfma_f32_16x16x32_bf16 v[14:17], v[158:161], v[220:223], v[14:17]
	v_mfma_f32_16x16x32_bf16 v[62:65], v[162:165], v[200:203], v[62:65]
	v_mfma_f32_16x16x32_bf16 v[58:61], v[170:173], v[200:203], v[58:61]
	v_mfma_f32_16x16x32_bf16 v[42:45], v[170:173], v[208:211], v[42:45]
	v_mfma_f32_16x16x32_bf16 v[46:49], v[162:165], v[208:211], v[46:49]
	v_mfma_f32_16x16x32_bf16 v[30:33], v[162:165], v[216:219], v[30:33]
	v_mfma_f32_16x16x32_bf16 v[26:29], v[170:173], v[216:219], v[26:29]
	v_mfma_f32_16x16x32_bf16 v[10:13], v[170:173], v[224:227], v[10:13]
	v_mfma_f32_16x16x32_bf16 v[14:17], v[162:165], v[224:227], v[14:17]
	s_setprio 0
	s_setprio 1
	v_mfma_f32_16x16x32_bf16 v[54:57], v[174:177], v[196:199], v[54:57]
	v_mfma_f32_16x16x32_bf16 v[50:53], v[182:185], v[196:199], v[50:53]
	v_mfma_f32_16x16x32_bf16 v[34:37], v[182:185], v[204:207], v[34:37]
	v_mfma_f32_16x16x32_bf16 v[38:41], v[174:177], v[204:207], v[38:41]
	v_mfma_f32_16x16x32_bf16 v[22:25], v[174:177], v[212:215], v[22:25]
	v_mfma_f32_16x16x32_bf16 v[18:21], v[182:185], v[212:215], v[18:21]
	v_mfma_f32_16x16x32_bf16 v[2:5], v[182:185], v[220:223], v[2:5]
	v_mfma_f32_16x16x32_bf16 v[6:9], v[174:177], v[220:223], v[6:9]
	v_mfma_f32_16x16x32_bf16 v[54:57], v[178:181], v[200:203], v[54:57]
	v_mfma_f32_16x16x32_bf16 v[50:53], v[190:193], v[200:203], v[50:53]
	v_mfma_f32_16x16x32_bf16 v[34:37], v[190:193], v[208:211], v[34:37]
	v_mfma_f32_16x16x32_bf16 v[38:41], v[178:181], v[208:211], v[38:41]
	v_mfma_f32_16x16x32_bf16 v[22:25], v[178:181], v[216:219], v[22:25]
	v_mfma_f32_16x16x32_bf16 v[18:21], v[190:193], v[216:219], v[18:21]
	v_mfma_f32_16x16x32_bf16 v[2:5], v[190:193], v[224:227], v[2:5]
	v_mfma_f32_16x16x32_bf16 v[6:9], v[178:181], v[224:227], v[6:9]
	s_setprio 0
	s_barrier
	s_add_i32 s60, 0, 0x18000
	v_add_u32_e32 v142, s60, v145
	s_add_i32 s61, 0, 0x1c000
	ds_read_b128 v[158:161], v142
	ds_read_b128 v[162:165], v142 offset:1024
	ds_read_b128 v[166:169], v142 offset:2048
	ds_read_b128 v[170:173], v142 offset:3072
	v_add_u32_e32 v142, s61, v145
	ds_read_b128 v[174:177], v142
	ds_read_b128 v[178:181], v142 offset:1024
	ds_read_b128 v[182:185], v142 offset:2048
	ds_read_b128 v[190:193], v142 offset:3072
	s_add_u32 s40, s40, 0x100000
	s_addc_u32 s41, s41, 0
	s_mov_b32 m0, s44
	v_lshl_add_u64 v[232:233], s[40:41], 0, v[134:135]
	ds_read_b128 v[196:199], v154 offset:32768
	ds_read_b128 v[200:203], v154 offset:33792
	ds_read_b128 v[204:207], v154 offset:34816
	ds_read_b128 v[208:211], v154 offset:35840
	ds_read_b128 v[212:215], v154 offset:36864
	ds_read_b128 v[216:219], v154 offset:37888
	ds_read_b128 v[220:223], v154 offset:38912
	ds_read_b128 v[224:227], v154 offset:39936
	global_load_lds_dwordx4 v[232:233], off
	v_lshl_add_u64 v[232:233], s[40:41], 0, v[136:137]
	s_mov_b32 m0, s45
	s_nop 0
	global_load_lds_dwordx4 v[232:233], off
	s_waitcnt vmcnt(8)
	s_waitcnt lgkmcnt(0)
	s_barrier
	s_setprio 1
	s_waitcnt lgkmcnt(0)
	v_mfma_f32_16x16x32_bf16 v[126:129], v[158:161], v[196:199], v[126:129]
	v_mfma_f32_16x16x32_bf16 v[122:125], v[166:169], v[196:199], v[122:125]
	v_mfma_f32_16x16x32_bf16 v[106:109], v[166:169], v[204:207], v[106:109]
	v_mfma_f32_16x16x32_bf16 v[110:113], v[158:161], v[204:207], v[110:113]
	v_mfma_f32_16x16x32_bf16 v[94:97], v[158:161], v[212:215], v[94:97]
	v_mfma_f32_16x16x32_bf16 v[90:93], v[166:169], v[212:215], v[90:93]
	v_mfma_f32_16x16x32_bf16 v[74:77], v[166:169], v[220:223], v[74:77]
	v_mfma_f32_16x16x32_bf16 v[78:81], v[158:161], v[220:223], v[78:81]
	v_mfma_f32_16x16x32_bf16 v[126:129], v[162:165], v[200:203], v[126:129]
	v_mfma_f32_16x16x32_bf16 v[122:125], v[170:173], v[200:203], v[122:125]
	v_mfma_f32_16x16x32_bf16 v[106:109], v[170:173], v[208:211], v[106:109]
	v_mfma_f32_16x16x32_bf16 v[110:113], v[162:165], v[208:211], v[110:113]
	v_mfma_f32_16x16x32_bf16 v[94:97], v[162:165], v[216:219], v[94:97]
	v_mfma_f32_16x16x32_bf16 v[90:93], v[170:173], v[216:219], v[90:93]
	v_mfma_f32_16x16x32_bf16 v[74:77], v[170:173], v[224:227], v[74:77]
	v_mfma_f32_16x16x32_bf16 v[78:81], v[162:165], v[224:227], v[78:81]
	s_setprio 0
	s_setprio 1
	v_mfma_f32_16x16x32_bf16 v[118:121], v[174:177], v[196:199], v[118:121]
	v_mfma_f32_16x16x32_bf16 v[114:117], v[182:185], v[196:199], v[114:117]
	v_mfma_f32_16x16x32_bf16 v[98:101], v[182:185], v[204:207], v[98:101]
	v_mfma_f32_16x16x32_bf16 v[102:105], v[174:177], v[204:207], v[102:105]
	v_mfma_f32_16x16x32_bf16 v[86:89], v[174:177], v[212:215], v[86:89]
	v_mfma_f32_16x16x32_bf16 v[82:85], v[182:185], v[212:215], v[82:85]
	v_mfma_f32_16x16x32_bf16 v[66:69], v[182:185], v[220:223], v[66:69]
	v_mfma_f32_16x16x32_bf16 v[70:73], v[174:177], v[220:223], v[70:73]
	v_mfma_f32_16x16x32_bf16 v[118:121], v[178:181], v[200:203], v[118:121]
	v_mfma_f32_16x16x32_bf16 v[114:117], v[190:193], v[200:203], v[114:117]
	v_mfma_f32_16x16x32_bf16 v[98:101], v[190:193], v[208:211], v[98:101]
	v_mfma_f32_16x16x32_bf16 v[102:105], v[178:181], v[208:211], v[102:105]
	v_mfma_f32_16x16x32_bf16 v[86:89], v[178:181], v[216:219], v[86:89]
	v_mfma_f32_16x16x32_bf16 v[82:85], v[190:193], v[216:219], v[82:85]
	v_mfma_f32_16x16x32_bf16 v[66:69], v[190:193], v[224:227], v[66:69]
	v_mfma_f32_16x16x32_bf16 v[70:73], v[178:181], v[224:227], v[70:73]
	s_setprio 0
	s_barrier
; #define PG8_STAGE(bufoff, gbase, voff) do { _Pragma("unroll") for (int _i = 0; _i < 2; ++_i) \
;         __builtin_amdgcn_global_load_lds((const unsigned*)((const char*)(gbase) + (voff)[_i]), (PG8_LAS unsigned*)(lds + (bufoff) + ldsw + _i * 8192), 16, 0, 0); } while (0)
; #define PG8_LDA(dst, b, h) do { _Pragma("unroll") for (int m = 0; m < 4; ++m) _Pragma("unroll") for (int k = 0; k < 2; ++k) dst[m][k] = *(const PG8_LAS bf16x8*)(lds + PG8_SA(b, h) + aoff + m * 2048 + k * 1024); } while (0)
; #define PG8_MMA(ai, bj, At, Bt) do { __builtin_amdgcn_s_setprio(1); _Pragma("unroll") for (int m = 0; m < 4; ++m) _Pragma("unroll") for (int n = 0; n < 2; ++n) _Pragma("unroll") for (int k = 0; k < 2; ++k) \
;         acc[ai][bj][m][n] = __builtin_amdgcn_mfma_f32_16x16x32_bf16(Bt[n][k], At[m][k], acc[ai][bj][m][n], 0, 0, 0); __builtin_amdgcn_s_setprio(0); } while (0)
; #define PG8_WAIT_V(n) asm volatile("s_waitcnt vmcnt(" #n ")" ::: "memory")
; #define PG8_WAIT_L(n) asm volatile("s_waitcnt lgkmcnt(" #n ")" ::: "memory")
; #define PG8_BAR __builtin_amdgcn_s_barrier()
; #define PG8_SCHED __builtin_amdgcn_sched_barrier(0)
; template <class Epi, class Sched, bool ALIGN_EPI = false, bool SP2 = false, bool A_TILED = false, bool B_TILED = false>
; __device__ __forceinline__ void gemm_phase(PG8_LAS unsigned char* lds, const Gemm g, const Sched& S, const Epi& E) {
;     ...
;             PG8_LDA(At, 1, 1); PG8_STAGE(PG8_SB(1, 0), b3, voffB); PG8_STAGE(PG8_SB(1, 1), b3 + hstepB, voffB); PG8_STAGE(PG8_SA(1, 0), a3, voffA);
;             PG8_WAIT_V(8); PG8_WAIT_L(0); PG8_BAR; PG8_MMA(1, 0, At, B0); PG8_MMA(1, 1, At, B1); PG8_BAR; PG8_SCHED;
	s_add_i32 s40, s60, s42
	v_lshl_add_u64 v[140:141], v[140:141], 0, s[12:13]
	s_mov_b32 m0, s40
	ds_read_b128 v[196:199], v154 offset:49152
	ds_read_b128 v[200:203], v154 offset:50176
	ds_read_b128 v[204:207], v154 offset:51200
	ds_read_b128 v[208:211], v154 offset:52224
	ds_read_b128 v[212:215], v154 offset:53248
	ds_read_b128 v[216:219], v154 offset:54272
	ds_read_b128 v[220:223], v154 offset:55296
	ds_read_b128 v[224:227], v154 offset:56320
	global_load_lds_dwordx4 v[140:141], off
	s_add_i32 m0, s40, 0x2000
	s_add_u32 s38, s38, 0x100080
	v_lshl_add_u64 v[140:141], v[186:187], 0, s[12:13]
	s_addc_u32 s39, s39, 0
	s_add_i32 s40, s61, s42
	global_load_lds_dwordx4 v[140:141], off
	v_lshl_add_u64 v[140:141], s[38:39], 0, v[134:135]
	s_mov_b32 m0, s40
	s_nop 0
	global_load_lds_dwordx4 v[140:141], off
	v_lshl_add_u64 v[140:141], s[38:39], 0, v[136:137]
	s_add_i32 m0, s40, 0x2000
	s_nop 0
	global_load_lds_dwordx4 v[140:141], off
	v_lshl_add_u64 v[140:141], v[228:229], 0, s[12:13]
	s_mov_b32 m0, s53
	s_nop 0
	global_load_lds_dwordx4 v[140:141], off
	v_lshl_add_u64 v[140:141], v[230:231], 0, s[12:13]
	s_mov_b32 m0, s54
	s_nop 0
	global_load_lds_dwordx4 v[140:141], off
	s_waitcnt vmcnt(8)
	s_waitcnt lgkmcnt(0)
	s_barrier
	s_setprio 1
	s_waitcnt lgkmcnt(0)
	v_mfma_f32_16x16x32_bf16 v[62:65], v[158:161], v[196:199], v[62:65]
	v_mfma_f32_16x16x32_bf16 v[58:61], v[166:169], v[196:199], v[58:61]
	v_mfma_f32_16x16x32_bf16 v[42:45], v[166:169], v[204:207], v[42:45]
	v_mfma_f32_16x16x32_bf16 v[46:49], v[158:161], v[204:207], v[46:49]
	v_mfma_f32_16x16x32_bf16 v[30:33], v[158:161], v[212:215], v[30:33]
	v_mfma_f32_16x16x32_bf16 v[26:29], v[166:169], v[212:215], v[26:29]
	v_mfma_f32_16x16x32_bf16 v[10:13], v[166:169], v[220:223], v[10:13]
	v_mfma_f32_16x16x32_bf16 v[14:17], v[158:161], v[220:223], v[14:17]
	v_mfma_f32_16x16x32_bf16 v[62:65], v[162:165], v[200:203], v[62:65]
	v_mfma_f32_16x16x32_bf16 v[58:61], v[170:173], v[200:203], v[58:61]
	v_mfma_f32_16x16x32_bf16 v[42:45], v[170:173], v[208:211], v[42:45]
	v_mfma_f32_16x16x32_bf16 v[46:49], v[162:165], v[208:211], v[46:49]
	v_mfma_f32_16x16x32_bf16 v[30:33], v[162:165], v[216:219], v[30:33]
	v_mfma_f32_16x16x32_bf16 v[26:29], v[170:173], v[216:219], v[26:29]
	v_mfma_f32_16x16x32_bf16 v[10:13], v[170:173], v[224:227], v[10:13]
	v_mfma_f32_16x16x32_bf16 v[14:17], v[162:165], v[224:227], v[14:17]
	s_setprio 0
	s_setprio 1
	v_mfma_f32_16x16x32_bf16 v[54:57], v[174:177], v[196:199], v[54:57]
	v_mfma_f32_16x16x32_bf16 v[50:53], v[182:185], v[196:199], v[50:53]
	v_mfma_f32_16x16x32_bf16 v[34:37], v[182:185], v[204:207], v[34:37]
	v_mfma_f32_16x16x32_bf16 v[38:41], v[174:177], v[204:207], v[38:41]
	v_mfma_f32_16x16x32_bf16 v[22:25], v[174:177], v[212:215], v[22:25]
	v_mfma_f32_16x16x32_bf16 v[18:21], v[182:185], v[212:215], v[18:21]
	v_mfma_f32_16x16x32_bf16 v[2:5], v[182:185], v[220:223], v[2:5]
	v_mfma_f32_16x16x32_bf16 v[6:9], v[174:177], v[220:223], v[6:9]
	v_mfma_f32_16x16x32_bf16 v[54:57], v[178:181], v[200:203], v[54:57]
	v_mfma_f32_16x16x32_bf16 v[50:53], v[190:193], v[200:203], v[50:53]
	v_mfma_f32_16x16x32_bf16 v[34:37], v[190:193], v[208:211], v[34:37]
	v_mfma_f32_16x16x32_bf16 v[38:41], v[178:181], v[208:211], v[38:41]
	v_mfma_f32_16x16x32_bf16 v[22:25], v[178:181], v[216:219], v[22:25]
	v_mfma_f32_16x16x32_bf16 v[18:21], v[190:193], v[216:219], v[18:21]
	v_mfma_f32_16x16x32_bf16 v[2:5], v[190:193], v[224:227], v[2:5]
	v_mfma_f32_16x16x32_bf16 v[6:9], v[178:181], v[224:227], v[6:9]
	s_setprio 0
	s_barrier
	s_add_i32 s59, s59, 2
	s_add_u32 s36, s36, 0x100
	s_addc_u32 s37, s37, 0
	s_add_u32 s27, s27, 0x100
	s_addc_u32 s58, s58, 0
	s_cmp_gt_u32 s59, 13
	s_cbranch_scc0 .LBB0_553
	s_and_b64 vcc, exec, s[20:21]
	s_cbranch_vccz .LBB0_556
	s_barrier

; #define PG8_STAGE(bufoff, gbase, voff) do { _Pragma("unroll") for (int _i = 0; _i < 2; ++_i) \
;         __builtin_amdgcn_global_load_lds((const unsigned*)((const char*)(gbase) + (voff)[_i]), (PG8_LAS unsigned*)(lds + (bufoff) + ldsw + _i * 8192), 16, 0, 0); } while (0)
; #define PG8_LDA(dst, b, h) do { _Pragma("unroll") for (int m = 0; m < 4; ++m) _Pragma("unroll") for (int k = 0; k < 2; ++k) dst[m][k] = *(const PG8_LAS bf16x8*)(lds + PG8_SA(b, h) + aoff + m * 2048 + k * 1024); } while (0)
; #define PG8_LDB(dst, b, h) do { _Pragma("unroll") for (int n = 0; n < 2; ++n) _Pragma("unroll") for (int k = 0; k < 2; ++k) dst[n][k] = *(const PG8_LAS bf16x8*)(lds + PG8_SB(b, h) + boff + n * 2048 + k * 1024); } while (0)
; #define PG8_MMA(ai, bj, At, Bt) do { __builtin_amdgcn_s_setprio(1); _Pragma("unroll") for (int m = 0; m < 4; ++m) _Pragma("unroll") for (int n = 0; n < 2; ++n) _Pragma("unroll") for (int k = 0; k < 2; ++k) \
;         acc[ai][bj][m][n] = __builtin_amdgcn_mfma_f32_16x16x32_bf16(Bt[n][k], At[m][k], acc[ai][bj][m][n], 0, 0, 0); __builtin_amdgcn_s_setprio(0); } while (0)
; #define PG8_WAIT_V(n) asm volatile("s_waitcnt vmcnt(" #n ")" ::: "memory")
; #define PG8_WAIT_L(n) asm volatile("s_waitcnt lgkmcnt(" #n ")" ::: "memory")
; #define PG8_BAR __builtin_amdgcn_s_barrier()
; #define PG8_SCHED __builtin_amdgcn_sched_barrier(0)
; template <class Epi, class Sched, bool ALIGN_EPI = false, bool SP2 = false, bool A_TILED = false, bool B_TILED = false>
; __device__ __forceinline__ void gemm_phase(PG8_LAS unsigned char* lds, const Gemm g, const Sched& S, const Epi& E) {
;     ...
;             PG8_LDB(B0, 0, 0); PG8_LDB(B1, 0, 1); PG8_SCHED; PG8_LDA(At, 0, 0); PG8_STAGE(PG8_SA(1, 1), a1 + hstepA, voffA);
;             PG8_WAIT_V(8); PG8_WAIT_L(0); PG8_BAR; PG8_MMA(0, 0, At, B0); PG8_MMA(0, 1, At, B1); PG8_BAR; PG8_SCHED;
;             PG8_LDA(At, 0, 1); PG8_STAGE(PG8_SB(0, 0), b2, voffB); PG8_STAGE(PG8_SB(0, 1), b2 + hstepB, voffB); PG8_STAGE(PG8_SA(0, 0), a2, voffA);
.LBB0_726:
	ds_read_b128 v[126:129], v207
	ds_read_b128 v[130:133], v207 offset:1024
	ds_read_b128 v[134:137], v207 offset:2048
	ds_read_b128 v[138:141], v207 offset:3072
	ds_read_b128 v[150:153], v208
	ds_read_b128 v[154:157], v208 offset:1024
	ds_read_b128 v[158:161], v208 offset:2048
	ds_read_b128 v[162:165], v208 offset:3072
	s_add_u32 s10, s8, 0xfff00080
	s_addc_u32 s11, s9, -1
	s_cmp_eq_u32 s19, 60
	s_cselect_b32 s13, s7, s11
	s_cselect_b32 s12, s14, s10
	s_cselect_b32 s11, s15, s18
	s_cselect_b32 s10, s16, s17
	v_lshl_add_u64 v[236:237], s[8:9], 0, v[180:181]
	s_add_i32 m0, s93, 0xc000
	ds_read_b128 v[166:169], v209
	ds_read_b128 v[184:187], v209 offset:1024
	ds_read_b128 v[190:193], v209 offset:2048
	ds_read_b128 v[216:219], v209 offset:3072
	ds_read_b128 v[220:223], v209 offset:4096
	ds_read_b128 v[224:227], v209 offset:5120
	ds_read_b128 v[228:231], v209 offset:6144
	ds_read_b128 v[232:235], v209 offset:7168
	global_load_lds_dwordx4 v[236:237], off
	v_lshl_add_u64 v[236:237], s[8:9], 0, v[182:183]
	s_add_i32 m0, s93, 0xe000
	s_nop 0
	global_load_lds_dwordx4 v[236:237], off
	s_waitcnt vmcnt(8)
	s_waitcnt lgkmcnt(0)
	s_barrier
	s_setprio 1
	s_waitcnt lgkmcnt(0)
	v_mfma_f32_16x16x32_bf16 v[146:149], v[126:129], v[166:169], v[146:149]
	v_mfma_f32_16x16x32_bf16 v[62:65], v[134:137], v[166:169], v[62:65]
	v_mfma_f32_16x16x32_bf16 v[54:57], v[134:137], v[190:193], v[54:57]
	v_mfma_f32_16x16x32_bf16 v[122:125], v[126:129], v[190:193], v[122:125]
	v_mfma_f32_16x16x32_bf16 v[106:109], v[126:129], v[220:223], v[106:109]
	v_mfma_f32_16x16x32_bf16 v[42:45], v[134:137], v[220:223], v[42:45]
	v_mfma_f32_16x16x32_bf16 v[46:49], v[134:137], v[228:231], v[46:49]
	v_mfma_f32_16x16x32_bf16 v[110:113], v[126:129], v[228:231], v[110:113]
	v_mfma_f32_16x16x32_bf16 v[146:149], v[130:133], v[184:187], v[146:149]
	v_mfma_f32_16x16x32_bf16 v[62:65], v[138:141], v[184:187], v[62:65]
	v_mfma_f32_16x16x32_bf16 v[54:57], v[138:141], v[216:219], v[54:57]
	v_mfma_f32_16x16x32_bf16 v[122:125], v[130:133], v[216:219], v[122:125]
	v_mfma_f32_16x16x32_bf16 v[106:109], v[130:133], v[224:227], v[106:109]
	v_mfma_f32_16x16x32_bf16 v[42:45], v[138:141], v[224:227], v[42:45]
	v_mfma_f32_16x16x32_bf16 v[46:49], v[138:141], v[232:235], v[46:49]
	v_mfma_f32_16x16x32_bf16 v[110:113], v[130:133], v[232:235], v[110:113]
	s_setprio 0
	s_setprio 1
	v_mfma_f32_16x16x32_bf16 v[118:121], v[150:153], v[166:169], v[118:121]
	v_mfma_f32_16x16x32_bf16 v[66:69], v[158:161], v[166:169], v[66:69]
	v_mfma_f32_16x16x32_bf16 v[58:61], v[158:161], v[190:193], v[58:61]
	v_mfma_f32_16x16x32_bf16 v[142:145], v[150:153], v[190:193], v[142:145]
	v_mfma_f32_16x16x32_bf16 v[114:117], v[150:153], v[220:223], v[114:117]
	v_mfma_f32_16x16x32_bf16 v[50:53], v[158:161], v[220:223], v[50:53]
	v_mfma_f32_16x16x32_bf16 v[38:41], v[158:161], v[228:231], v[38:41]
	v_mfma_f32_16x16x32_bf16 v[102:105], v[150:153], v[228:231], v[102:105]
	v_mfma_f32_16x16x32_bf16 v[118:121], v[154:157], v[184:187], v[118:121]
	v_mfma_f32_16x16x32_bf16 v[66:69], v[162:165], v[184:187], v[66:69]
	v_mfma_f32_16x16x32_bf16 v[58:61], v[162:165], v[216:219], v[58:61]
	v_mfma_f32_16x16x32_bf16 v[142:145], v[154:157], v[216:219], v[142:145]
	v_mfma_f32_16x16x32_bf16 v[114:117], v[154:157], v[224:227], v[114:117]
	v_mfma_f32_16x16x32_bf16 v[50:53], v[162:165], v[224:227], v[50:53]
	v_mfma_f32_16x16x32_bf16 v[38:41], v[162:165], v[232:235], v[38:41]
	v_mfma_f32_16x16x32_bf16 v[102:105], v[154:157], v[232:235], v[102:105]
	s_setprio 0
	s_barrier
	s_add_i32 s20, s24, s92
	v_lshl_add_u64 v[236:237], s[10:11], 0, v[172:173]
	s_mov_b32 m0, s20
	ds_read_b128 v[166:169], v209 offset:16384
	ds_read_b128 v[184:187], v209 offset:17408
	ds_read_b128 v[190:193], v209 offset:18432
	ds_read_b128 v[216:219], v209 offset:19456
	ds_read_b128 v[220:223], v209 offset:20480
	ds_read_b128 v[224:227], v209 offset:21504
	ds_read_b128 v[228:231], v209 offset:22528
	ds_read_b128 v[232:235], v209 offset:23552
	global_load_lds_dwordx4 v[236:237], off
	s_add_i32 m0, s20, 0x2000
	s_add_u32 s20, s10, 0x100000
	v_lshl_add_u64 v[238:239], s[10:11], 0, v[176:177]
	s_addc_u32 s21, s11, 0
	s_add_i32 s22, s25, s92
	global_load_lds_dwordx4 v[238:239], off
	v_lshl_add_u64 v[240:241], s[20:21], 0, v[172:173]
	s_mov_b32 m0, s22
	v_lshl_add_u64 v[242:243], s[12:13], 0, v[174:175]
	global_load_lds_dwordx4 v[240:241], off
	v_lshl_add_u64 v[240:241], s[20:21], 0, v[176:177]
	s_add_i32 m0, s22, 0x2000
	s_nop 0
	global_load_lds_dwordx4 v[240:241], off
	v_lshl_add_u64 v[240:241], s[12:13], 0, v[170:171]
	s_mov_b32 m0, s93
	s_nop 0
	global_load_lds_dwordx4 v[240:241], off
	s_mov_b32 m0, s94
	s_nop 0
	global_load_lds_dwordx4 v[242:243], off
	s_waitcnt vmcnt(8)
	s_waitcnt lgkmcnt(0)
	s_barrier
; #define PG8_STAGE(bufoff, gbase, voff) do { _Pragma("unroll") for (int _i = 0; _i < 2; ++_i) \
;         __builtin_amdgcn_global_load_lds((const unsigned*)((const char*)(gbase) + (voff)[_i]), (PG8_LAS unsigned*)(lds + (bufoff) + ldsw + _i * 8192), 16, 0, 0); } while (0)
; #define PG8_LDA(dst, b, h) do { _Pragma("unroll") for (int m = 0; m < 4; ++m) _Pragma("unroll") for (int k = 0; k < 2; ++k) dst[m][k] = *(const PG8_LAS bf16x8*)(lds + PG8_SA(b, h) + aoff + m * 2048 + k * 1024); } while (0)
; #define PG8_LDB(dst, b, h) do { _Pragma("unroll") for (int n = 0; n < 2; ++n) _Pragma("unroll") for (int k = 0; k < 2; ++k) dst[n][k] = *(const PG8_LAS bf16x8*)(lds + PG8_SB(b, h) + boff + n * 2048 + k * 1024); } while (0)
; #define PG8_MMA(ai, bj, At, Bt) do { __builtin_amdgcn_s_setprio(1); _Pragma("unroll") for (int m = 0; m < 4; ++m) _Pragma("unroll") for (int n = 0; n < 2; ++n) _Pragma("unroll") for (int k = 0; k < 2; ++k) \
;         acc[ai][bj][m][n] = __builtin_amdgcn_mfma_f32_16x16x32_bf16(Bt[n][k], At[m][k], acc[ai][bj][m][n], 0, 0, 0); __builtin_amdgcn_s_setprio(0); } while (0)
; #define PG8_WAIT_V(n) asm volatile("s_waitcnt vmcnt(" #n ")" ::: "memory")
; #define PG8_WAIT_L(n) asm volatile("s_waitcnt lgkmcnt(" #n ")" ::: "memory")
; #define PG8_BAR __builtin_amdgcn_s_barrier()
; #define PG8_SCHED __builtin_amdgcn_sched_barrier(0)
; template <class Epi, class Sched, bool ALIGN_EPI = false, bool SP2 = false, bool A_TILED = false, bool B_TILED = false>
; __device__ __forceinline__ void gemm_phase(PG8_LAS unsigned char* lds, const Gemm g, const Sched& S, const Epi& E) {
;     ...
;             PG8_WAIT_V(8); PG8_WAIT_L(0); PG8_BAR; PG8_MMA(1, 0, At, B0); PG8_MMA(1, 1, At, B1); PG8_BAR; PG8_SCHED;
;             PG8_LDB(B0, 1, 0); PG8_LDB(B1, 1, 1); PG8_SCHED; PG8_LDA(At, 1, 0); PG8_STAGE(PG8_SA(0, 1), a2 + hstepA, voffA);
;             PG8_WAIT_V(8); PG8_WAIT_L(0); PG8_BAR; PG8_MMA(0, 0, At, B0); PG8_MMA(0, 1, At, B1); PG8_BAR; PG8_SCHED;
	s_setprio 1
	s_waitcnt lgkmcnt(0)
	v_mfma_f32_16x16x32_bf16 v[94:97], v[126:129], v[166:169], v[94:97]
	v_mfma_f32_16x16x32_bf16 v[30:33], v[134:137], v[166:169], v[30:33]
	v_mfma_f32_16x16x32_bf16 v[22:25], v[134:137], v[190:193], v[22:25]
	v_mfma_f32_16x16x32_bf16 v[86:89], v[126:129], v[190:193], v[86:89]
	v_mfma_f32_16x16x32_bf16 v[74:77], v[126:129], v[220:223], v[74:77]
	v_mfma_f32_16x16x32_bf16 v[10:13], v[134:137], v[220:223], v[10:13]
	v_mfma_f32_16x16x32_bf16 v[14:17], v[134:137], v[228:231], v[14:17]
	v_mfma_f32_16x16x32_bf16 v[78:81], v[126:129], v[228:231], v[78:81]
	v_mfma_f32_16x16x32_bf16 v[94:97], v[130:133], v[184:187], v[94:97]
	v_mfma_f32_16x16x32_bf16 v[30:33], v[138:141], v[184:187], v[30:33]
	v_mfma_f32_16x16x32_bf16 v[22:25], v[138:141], v[216:219], v[22:25]
	v_mfma_f32_16x16x32_bf16 v[86:89], v[130:133], v[216:219], v[86:89]
	v_mfma_f32_16x16x32_bf16 v[74:77], v[130:133], v[224:227], v[74:77]
	v_mfma_f32_16x16x32_bf16 v[10:13], v[138:141], v[224:227], v[10:13]
	v_mfma_f32_16x16x32_bf16 v[14:17], v[138:141], v[232:235], v[14:17]
	v_mfma_f32_16x16x32_bf16 v[78:81], v[130:133], v[232:235], v[78:81]
	s_setprio 0
	s_setprio 1
	v_mfma_f32_16x16x32_bf16 v[98:101], v[150:153], v[166:169], v[98:101]
	v_mfma_f32_16x16x32_bf16 v[34:37], v[158:161], v[166:169], v[34:37]
	v_mfma_f32_16x16x32_bf16 v[26:29], v[158:161], v[190:193], v[26:29]
	v_mfma_f32_16x16x32_bf16 v[90:93], v[150:153], v[190:193], v[90:93]
	v_mfma_f32_16x16x32_bf16 v[82:85], v[150:153], v[220:223], v[82:85]
	v_mfma_f32_16x16x32_bf16 v[18:21], v[158:161], v[220:223], v[18:21]
	v_mfma_f32_16x16x32_bf16 v[6:9], v[158:161], v[228:231], v[6:9]
	v_mfma_f32_16x16x32_bf16 v[70:73], v[150:153], v[228:231], v[70:73]
	v_mfma_f32_16x16x32_bf16 v[98:101], v[154:157], v[184:187], v[98:101]
	v_mfma_f32_16x16x32_bf16 v[34:37], v[162:165], v[184:187], v[34:37]
	v_mfma_f32_16x16x32_bf16 v[26:29], v[162:165], v[216:219], v[26:29]
	v_mfma_f32_16x16x32_bf16 v[90:93], v[154:157], v[216:219], v[90:93]
	v_mfma_f32_16x16x32_bf16 v[82:85], v[154:157], v[224:227], v[82:85]
	v_mfma_f32_16x16x32_bf16 v[18:21], v[162:165], v[224:227], v[18:21]
	v_mfma_f32_16x16x32_bf16 v[6:9], v[162:165], v[232:235], v[6:9]
	v_mfma_f32_16x16x32_bf16 v[70:73], v[154:157], v[232:235], v[70:73]
	s_setprio 0
	s_barrier
	s_add_i32 s20, 0, 0x18000
	s_add_i32 s21, 0, 0x1c000
	v_add_u32_e32 v138, s20, v203
	v_add_u32_e32 v162, s21, v203
	ds_read_b128 v[126:129], v138
	ds_read_b128 v[130:133], v138 offset:1024
	ds_read_b128 v[134:137], v138 offset:2048
	ds_read_b128 v[138:141], v138 offset:3072
	ds_read_b128 v[150:153], v162
	ds_read_b128 v[154:157], v162 offset:1024
	ds_read_b128 v[158:161], v162 offset:2048
	ds_read_b128 v[162:165], v162 offset:3072
	s_add_u32 s12, s12, 0x100000
	s_addc_u32 s13, s13, 0
	s_mov_b32 m0, s95
	v_lshl_add_u64 v[244:245], s[12:13], 0, v[170:171]
	ds_read_b128 v[166:169], v209 offset:32768
	ds_read_b128 v[184:187], v209 offset:33792
	ds_read_b128 v[190:193], v209 offset:34816
	ds_read_b128 v[216:219], v209 offset:35840
	ds_read_b128 v[220:223], v209 offset:36864
	ds_read_b128 v[224:227], v209 offset:37888
	ds_read_b128 v[228:231], v209 offset:38912
	ds_read_b128 v[232:235], v209 offset:39936
	global_load_lds_dwordx4 v[244:245], off
	v_lshl_add_u64 v[244:245], s[12:13], 0, v[174:175]
	s_mov_b32 m0, s96
	s_nop 0
	global_load_lds_dwordx4 v[244:245], off
	s_waitcnt vmcnt(8)
	s_waitcnt lgkmcnt(0)
	s_barrier
	s_setprio 1
	s_waitcnt lgkmcnt(0)
	v_mfma_f32_16x16x32_bf16 v[146:149], v[126:129], v[166:169], v[146:149]
	v_mfma_f32_16x16x32_bf16 v[62:65], v[134:137], v[166:169], v[62:65]
	v_mfma_f32_16x16x32_bf16 v[54:57], v[134:137], v[190:193], v[54:57]
	v_mfma_f32_16x16x32_bf16 v[122:125], v[126:129], v[190:193], v[122:125]
	v_mfma_f32_16x16x32_bf16 v[106:109], v[126:129], v[220:223], v[106:109]
	v_mfma_f32_16x16x32_bf16 v[42:45], v[134:137], v[220:223], v[42:45]
	v_mfma_f32_16x16x32_bf16 v[46:49], v[134:137], v[228:231], v[46:49]
	v_mfma_f32_16x16x32_bf16 v[110:113], v[126:129], v[228:231], v[110:113]
	v_mfma_f32_16x16x32_bf16 v[146:149], v[130:133], v[184:187], v[146:149]
	v_mfma_f32_16x16x32_bf16 v[62:65], v[138:141], v[184:187], v[62:65]
	v_mfma_f32_16x16x32_bf16 v[54:57], v[138:141], v[216:219], v[54:57]
	v_mfma_f32_16x16x32_bf16 v[122:125], v[130:133], v[216:219], v[122:125]
	v_mfma_f32_16x16x32_bf16 v[106:109], v[130:133], v[224:227], v[106:109]
	v_mfma_f32_16x16x32_bf16 v[42:45], v[138:141], v[224:227], v[42:45]
	v_mfma_f32_16x16x32_bf16 v[46:49], v[138:141], v[232:235], v[46:49]
	v_mfma_f32_16x16x32_bf16 v[110:113], v[130:133], v[232:235], v[110:113]
	s_setprio 0
	s_setprio 1
	v_mfma_f32_16x16x32_bf16 v[118:121], v[150:153], v[166:169], v[118:121]
	v_mfma_f32_16x16x32_bf16 v[66:69], v[158:161], v[166:169], v[66:69]
	v_mfma_f32_16x16x32_bf16 v[58:61], v[158:161], v[190:193], v[58:61]
	v_mfma_f32_16x16x32_bf16 v[142:145], v[150:153], v[190:193], v[142:145]
	v_mfma_f32_16x16x32_bf16 v[114:117], v[150:153], v[220:223], v[114:117]
	v_mfma_f32_16x16x32_bf16 v[50:53], v[158:161], v[220:223], v[50:53]
	v_mfma_f32_16x16x32_bf16 v[38:41], v[158:161], v[228:231], v[38:41]
	v_mfma_f32_16x16x32_bf16 v[102:105], v[150:153], v[228:231], v[102:105]
	v_mfma_f32_16x16x32_bf16 v[118:121], v[154:157], v[184:187], v[118:121]
	v_mfma_f32_16x16x32_bf16 v[66:69], v[162:165], v[184:187], v[66:69]
	v_mfma_f32_16x16x32_bf16 v[58:61], v[162:165], v[216:219], v[58:61]
	v_mfma_f32_16x16x32_bf16 v[142:145], v[154:157], v[216:219], v[142:145]
	v_mfma_f32_16x16x32_bf16 v[114:117], v[154:157], v[224:227], v[114:117]
	v_mfma_f32_16x16x32_bf16 v[50:53], v[162:165], v[224:227], v[50:53]
	v_mfma_f32_16x16x32_bf16 v[38:41], v[162:165], v[232:235], v[38:41]
	v_mfma_f32_16x16x32_bf16 v[102:105], v[154:157], v[232:235], v[102:105]
	s_setprio 0
	s_barrier
; #define PG8_STAGE(bufoff, gbase, voff) do { _Pragma("unroll") for (int _i = 0; _i < 2; ++_i) \
;         __builtin_amdgcn_global_load_lds((const unsigned*)((const char*)(gbase) + (voff)[_i]), (PG8_LAS unsigned*)(lds + (bufoff) + ldsw + _i * 8192), 16, 0, 0); } while (0)
; #define PG8_LDA(dst, b, h) do { _Pragma("unroll") for (int m = 0; m < 4; ++m) _Pragma("unroll") for (int k = 0; k < 2; ++k) dst[m][k] = *(const PG8_LAS bf16x8*)(lds + PG8_SA(b, h) + aoff + m * 2048 + k * 1024); } while (0)
; #define PG8_MMA(ai, bj, At, Bt) do { __builtin_amdgcn_s_setprio(1); _Pragma("unroll") for (int m = 0; m < 4; ++m) _Pragma("unroll") for (int n = 0; n < 2; ++n) _Pragma("unroll") for (int k = 0; k < 2; ++k) \
;         acc[ai][bj][m][n] = __builtin_amdgcn_mfma_f32_16x16x32_bf16(Bt[n][k], At[m][k], acc[ai][bj][m][n], 0, 0, 0); __builtin_amdgcn_s_setprio(0); } while (0)
; #define PG8_WAIT_V(n) asm volatile("s_waitcnt vmcnt(" #n ")" ::: "memory")
; #define PG8_WAIT_L(n) asm volatile("s_waitcnt lgkmcnt(" #n ")" ::: "memory")
; #define PG8_BAR __builtin_amdgcn_s_barrier()
; #define PG8_SCHED __builtin_amdgcn_sched_barrier(0)
; template <class Epi, class Sched, bool ALIGN_EPI = false, bool SP2 = false, bool A_TILED = false, bool B_TILED = false>
; __device__ __forceinline__ void gemm_phase(PG8_LAS unsigned char* lds, const Gemm g, const Sched& S, const Epi& E) {
;     ...
;             PG8_LDA(At, 1, 1); PG8_STAGE(PG8_SB(1, 0), b3, voffB); PG8_STAGE(PG8_SB(1, 1), b3 + hstepB, voffB); PG8_STAGE(PG8_SA(1, 0), a3, voffA);
;             PG8_WAIT_V(8); PG8_WAIT_L(0); PG8_BAR; PG8_MMA(1, 0, At, B0); PG8_MMA(1, 1, At, B1); PG8_BAR; PG8_SCHED;
	s_add_i32 s12, s20, s92
	v_lshl_add_u64 v[236:237], v[236:237], 0, s[46:47]
	s_mov_b32 m0, s12
	ds_read_b128 v[166:169], v209 offset:49152
	ds_read_b128 v[184:187], v209 offset:50176
	ds_read_b128 v[190:193], v209 offset:51200
	ds_read_b128 v[216:219], v209 offset:52224
	ds_read_b128 v[220:223], v209 offset:53248
	ds_read_b128 v[224:227], v209 offset:54272
	ds_read_b128 v[228:231], v209 offset:55296
	ds_read_b128 v[232:235], v209 offset:56320
	global_load_lds_dwordx4 v[236:237], off
	s_add_i32 m0, s12, 0x2000
	s_add_u32 s10, s10, 0x100080
	v_lshl_add_u64 v[236:237], v[238:239], 0, s[46:47]
	s_addc_u32 s11, s11, 0
	s_add_i32 s12, s21, s92
	global_load_lds_dwordx4 v[236:237], off
	v_lshl_add_u64 v[236:237], s[10:11], 0, v[172:173]
	s_mov_b32 m0, s12
	s_nop 0
	global_load_lds_dwordx4 v[236:237], off
	v_lshl_add_u64 v[236:237], s[10:11], 0, v[176:177]
	s_add_i32 m0, s12, 0x2000
	s_nop 0
	global_load_lds_dwordx4 v[236:237], off
	v_lshl_add_u64 v[236:237], v[240:241], 0, s[46:47]
	s_mov_b32 m0, s54
	s_nop 0
	global_load_lds_dwordx4 v[236:237], off
	v_lshl_add_u64 v[236:237], v[242:243], 0, s[46:47]
	s_mov_b32 m0, s55
	s_nop 0
	global_load_lds_dwordx4 v[236:237], off
	s_waitcnt vmcnt(8)
	s_waitcnt lgkmcnt(0)
	s_barrier
	s_setprio 1
	s_waitcnt lgkmcnt(0)
	v_mfma_f32_16x16x32_bf16 v[94:97], v[126:129], v[166:169], v[94:97]
	v_mfma_f32_16x16x32_bf16 v[30:33], v[134:137], v[166:169], v[30:33]
	v_mfma_f32_16x16x32_bf16 v[22:25], v[134:137], v[190:193], v[22:25]
	v_mfma_f32_16x16x32_bf16 v[86:89], v[126:129], v[190:193], v[86:89]
	v_mfma_f32_16x16x32_bf16 v[74:77], v[126:129], v[220:223], v[74:77]
	v_mfma_f32_16x16x32_bf16 v[10:13], v[134:137], v[220:223], v[10:13]
	v_mfma_f32_16x16x32_bf16 v[14:17], v[134:137], v[228:231], v[14:17]
	v_mfma_f32_16x16x32_bf16 v[78:81], v[126:129], v[228:231], v[78:81]
	v_mfma_f32_16x16x32_bf16 v[94:97], v[130:133], v[184:187], v[94:97]
	v_mfma_f32_16x16x32_bf16 v[30:33], v[138:141], v[184:187], v[30:33]
	v_mfma_f32_16x16x32_bf16 v[22:25], v[138:141], v[216:219], v[22:25]
	v_mfma_f32_16x16x32_bf16 v[86:89], v[130:133], v[216:219], v[86:89]
	v_mfma_f32_16x16x32_bf16 v[74:77], v[130:133], v[224:227], v[74:77]
	v_mfma_f32_16x16x32_bf16 v[10:13], v[138:141], v[224:227], v[10:13]
	v_mfma_f32_16x16x32_bf16 v[14:17], v[138:141], v[232:235], v[14:17]
	v_mfma_f32_16x16x32_bf16 v[78:81], v[130:133], v[232:235], v[78:81]
	s_setprio 0
	s_setprio 1
	v_mfma_f32_16x16x32_bf16 v[98:101], v[150:153], v[166:169], v[98:101]
	v_mfma_f32_16x16x32_bf16 v[34:37], v[158:161], v[166:169], v[34:37]
	v_mfma_f32_16x16x32_bf16 v[26:29], v[158:161], v[190:193], v[26:29]
	v_mfma_f32_16x16x32_bf16 v[90:93], v[150:153], v[190:193], v[90:93]
	v_mfma_f32_16x16x32_bf16 v[82:85], v[150:153], v[220:223], v[82:85]
	v_mfma_f32_16x16x32_bf16 v[18:21], v[158:161], v[220:223], v[18:21]
	v_mfma_f32_16x16x32_bf16 v[6:9], v[158:161], v[228:231], v[6:9]
	v_mfma_f32_16x16x32_bf16 v[70:73], v[150:153], v[228:231], v[70:73]
	v_mfma_f32_16x16x32_bf16 v[98:101], v[154:157], v[184:187], v[98:101]
	v_mfma_f32_16x16x32_bf16 v[34:37], v[162:165], v[184:187], v[34:37]
	v_mfma_f32_16x16x32_bf16 v[26:29], v[162:165], v[216:219], v[26:29]
	v_mfma_f32_16x16x32_bf16 v[90:93], v[154:157], v[216:219], v[90:93]
	v_mfma_f32_16x16x32_bf16 v[82:85], v[154:157], v[224:227], v[82:85]
	v_mfma_f32_16x16x32_bf16 v[18:21], v[162:165], v[224:227], v[18:21]
	v_mfma_f32_16x16x32_bf16 v[6:9], v[162:165], v[232:235], v[6:9]
	v_mfma_f32_16x16x32_bf16 v[70:73], v[154:157], v[232:235], v[70:73]
	s_setprio 0
	s_barrier
	s_add_i32 s19, s19, 2
	s_add_u32 s8, s8, 0x100
	s_addc_u32 s9, s9, 0
	s_add_u32 s17, s17, 0x100
	s_addc_u32 s18, s18, 0
	s_cmp_gt_u32 s19, 61
	s_cbranch_scc0 .LBB0_726
	s_and_b64 vcc, exec, s[56:57]
	s_cbranch_vccz .LBB0_729
	s_barrier

; #define PG8_STAGE(bufoff, gbase, voff) do { _Pragma("unroll") for (int _i = 0; _i < 2; ++_i) \
;         __builtin_amdgcn_global_load_lds((const unsigned*)((const char*)(gbase) + (voff)[_i]), (PG8_LAS unsigned*)(lds + (bufoff) + ldsw + _i * 8192), 16, 0, 0); } while (0)
; #define PG8_LDA(dst, b, h) do { _Pragma("unroll") for (int m = 0; m < 4; ++m) _Pragma("unroll") for (int k = 0; k < 2; ++k) dst[m][k] = *(const PG8_LAS bf16x8*)(lds + PG8_SA(b, h) + aoff + m * 2048 + k * 1024); } while (0)
; #define PG8_LDB(dst, b, h) do { _Pragma("unroll") for (int n = 0; n < 2; ++n) _Pragma("unroll") for (int k = 0; k < 2; ++k) dst[n][k] = *(const PG8_LAS bf16x8*)(lds + PG8_SB(b, h) + boff + n * 2048 + k * 1024); } while (0)
; #define PG8_MMA(ai, bj, At, Bt) do { __builtin_amdgcn_s_setprio(1); _Pragma("unroll") for (int m = 0; m < 4; ++m) _Pragma("unroll") for (int n = 0; n < 2; ++n) _Pragma("unroll") for (int k = 0; k < 2; ++k) \
;         acc[ai][bj][m][n] = __builtin_amdgcn_mfma_f32_16x16x32_bf16(Bt[n][k], At[m][k], acc[ai][bj][m][n], 0, 0, 0); __builtin_amdgcn_s_setprio(0); } while (0)
; #define PG8_WAIT_V(n) asm volatile("s_waitcnt vmcnt(" #n ")" ::: "memory")
; #define PG8_WAIT_L(n) asm volatile("s_waitcnt lgkmcnt(" #n ")" ::: "memory")
; #define PG8_BAR __builtin_amdgcn_s_barrier()
; #define PG8_SCHED __builtin_amdgcn_sched_barrier(0)
; template <class Epi, class Sched, bool ALIGN_EPI = false, bool SP2 = false, bool A_TILED = false, bool B_TILED = false>
; __device__ __forceinline__ void gemm_phase(PG8_LAS unsigned char* lds, const Gemm g, const Sched& S, const Epi& E) {
;     ...
;             PG8_LDB(B0, 0, 0); PG8_LDB(B1, 0, 1); PG8_SCHED; PG8_LDA(At, 0, 0); PG8_STAGE(PG8_SA(1, 1), a1 + hstepA, voffA);
;             PG8_WAIT_V(8); PG8_WAIT_L(0); PG8_BAR; PG8_MMA(0, 0, At, B0); PG8_MMA(0, 1, At, B1); PG8_BAR; PG8_SCHED;
;             PG8_LDA(At, 0, 1); PG8_STAGE(PG8_SB(0, 0), b2, voffB); PG8_STAGE(PG8_SB(0, 1), b2 + hstepB, voffB); PG8_STAGE(PG8_SA(0, 0), a2, voffA);
.LBB0_905:
	ds_read_b128 v[140:143], v1
	ds_read_b128 v[144:147], v1 offset:1024
	ds_read_b128 v[148:151], v1 offset:2048
	ds_read_b128 v[152:155], v1 offset:3072
	ds_read_b128 v[156:159], v137
	ds_read_b128 v[160:163], v137 offset:1024
	ds_read_b128 v[164:167], v137 offset:2048
	ds_read_b128 v[178:181], v137 offset:3072
	s_add_u32 s30, s26, 0xfff00080
	s_addc_u32 s31, s27, -1
	s_cmp_eq_u32 s44, 4
	s_cselect_b32 s35, s13, s31
	s_cselect_b32 s34, s17, s30
	s_cselect_b32 s31, s15, s43
	s_cselect_b32 s30, s25, s42
	v_lshl_add_u64 v[168:169], s[26:27], 0, v[132:133]
	s_add_i32 m0, s29, 0xc000
	ds_read_b128 v[182:185], v138
	ds_read_b128 v[190:193], v138 offset:1024
	ds_read_b128 v[196:199], v138 offset:2048
	ds_read_b128 v[200:203], v138 offset:3072
	ds_read_b128 v[204:207], v138 offset:4096
	ds_read_b128 v[208:211], v138 offset:5120
	ds_read_b128 v[212:215], v138 offset:6144
	ds_read_b128 v[216:219], v138 offset:7168
	global_load_lds_dwordx4 v[168:169], off
	v_lshl_add_u64 v[168:169], s[26:27], 0, v[134:135]
	s_add_i32 m0, s29, 0xe000
	s_nop 0
	global_load_lds_dwordx4 v[168:169], off
	s_waitcnt vmcnt(8)
	s_waitcnt lgkmcnt(0)
	s_barrier
	s_setprio 1
	s_waitcnt lgkmcnt(0)
	v_mfma_f32_16x16x32_bf16 v[126:129], v[140:143], v[182:185], v[126:129]
	v_mfma_f32_16x16x32_bf16 v[122:125], v[148:151], v[182:185], v[122:125]
	v_mfma_f32_16x16x32_bf16 v[114:117], v[148:151], v[196:199], v[114:117]
	v_mfma_f32_16x16x32_bf16 v[118:121], v[140:143], v[196:199], v[118:121]
	v_mfma_f32_16x16x32_bf16 v[110:113], v[140:143], v[204:207], v[110:113]
	v_mfma_f32_16x16x32_bf16 v[102:105], v[148:151], v[204:207], v[102:105]
	v_mfma_f32_16x16x32_bf16 v[86:89], v[148:151], v[212:215], v[86:89]
	v_mfma_f32_16x16x32_bf16 v[94:97], v[140:143], v[212:215], v[94:97]
	v_mfma_f32_16x16x32_bf16 v[126:129], v[144:147], v[190:193], v[126:129]
	v_mfma_f32_16x16x32_bf16 v[122:125], v[152:155], v[190:193], v[122:125]
	v_mfma_f32_16x16x32_bf16 v[114:117], v[152:155], v[200:203], v[114:117]
	v_mfma_f32_16x16x32_bf16 v[118:121], v[144:147], v[200:203], v[118:121]
	v_mfma_f32_16x16x32_bf16 v[110:113], v[144:147], v[208:211], v[110:113]
	v_mfma_f32_16x16x32_bf16 v[102:105], v[152:155], v[208:211], v[102:105]
	v_mfma_f32_16x16x32_bf16 v[86:89], v[152:155], v[216:219], v[86:89]
	v_mfma_f32_16x16x32_bf16 v[94:97], v[144:147], v[216:219], v[94:97]
	s_setprio 0
	s_setprio 1
	v_mfma_f32_16x16x32_bf16 v[106:109], v[156:159], v[182:185], v[106:109]
	v_mfma_f32_16x16x32_bf16 v[98:101], v[164:167], v[182:185], v[98:101]
	v_mfma_f32_16x16x32_bf16 v[82:85], v[164:167], v[196:199], v[82:85]
	v_mfma_f32_16x16x32_bf16 v[90:93], v[156:159], v[196:199], v[90:93]
	v_mfma_f32_16x16x32_bf16 v[78:81], v[156:159], v[204:207], v[78:81]
	v_mfma_f32_16x16x32_bf16 v[74:77], v[164:167], v[204:207], v[74:77]
	v_mfma_f32_16x16x32_bf16 v[66:69], v[164:167], v[212:215], v[66:69]
	v_mfma_f32_16x16x32_bf16 v[70:73], v[156:159], v[212:215], v[70:73]
	v_mfma_f32_16x16x32_bf16 v[106:109], v[160:163], v[190:193], v[106:109]
	v_mfma_f32_16x16x32_bf16 v[98:101], v[178:181], v[190:193], v[98:101]
	v_mfma_f32_16x16x32_bf16 v[82:85], v[178:181], v[200:203], v[82:85]
	v_mfma_f32_16x16x32_bf16 v[90:93], v[160:163], v[200:203], v[90:93]
	v_mfma_f32_16x16x32_bf16 v[78:81], v[160:163], v[208:211], v[78:81]
	v_mfma_f32_16x16x32_bf16 v[74:77], v[178:181], v[208:211], v[74:77]
	v_mfma_f32_16x16x32_bf16 v[66:69], v[178:181], v[216:219], v[66:69]
	v_mfma_f32_16x16x32_bf16 v[70:73], v[160:163], v[216:219], v[70:73]
	s_setprio 0
	s_barrier
	s_add_i32 s45, s4, s28
	v_lshl_add_u64 v[168:169], s[30:31], 0, v[172:173]
	s_mov_b32 m0, s45
	ds_read_b128 v[182:185], v138 offset:16384
	ds_read_b128 v[190:193], v138 offset:17408
	ds_read_b128 v[196:199], v138 offset:18432
	ds_read_b128 v[200:203], v138 offset:19456
	ds_read_b128 v[204:207], v138 offset:20480
	ds_read_b128 v[208:211], v138 offset:21504
	ds_read_b128 v[212:215], v138 offset:22528
	ds_read_b128 v[216:219], v138 offset:23552
	global_load_lds_dwordx4 v[168:169], off
	s_add_i32 m0, s45, 0x2000
	s_add_u32 s46, s30, 0x100000
	v_lshl_add_u64 v[186:187], s[30:31], 0, v[176:177]
	s_addc_u32 s47, s31, 0
	s_add_i32 s45, s40, s28
	global_load_lds_dwordx4 v[186:187], off
	v_lshl_add_u64 v[220:221], s[46:47], 0, v[172:173]
	s_mov_b32 m0, s45
	v_lshl_add_u64 v[222:223], s[34:35], 0, v[174:175]
	global_load_lds_dwordx4 v[220:221], off
	v_lshl_add_u64 v[220:221], s[46:47], 0, v[176:177]
	s_add_i32 m0, s45, 0x2000
	s_nop 0
	global_load_lds_dwordx4 v[220:221], off
	v_lshl_add_u64 v[220:221], s[34:35], 0, v[170:171]
	s_mov_b32 m0, s29
	s_nop 0
	global_load_lds_dwordx4 v[220:221], off
	s_mov_b32 m0, s33
	s_nop 0
	global_load_lds_dwordx4 v[222:223], off
	s_waitcnt vmcnt(8)
	s_waitcnt lgkmcnt(0)
	s_barrier
; #define PG8_STAGE(bufoff, gbase, voff) do { _Pragma("unroll") for (int _i = 0; _i < 2; ++_i) \
;         __builtin_amdgcn_global_load_lds((const unsigned*)((const char*)(gbase) + (voff)[_i]), (PG8_LAS unsigned*)(lds + (bufoff) + ldsw + _i * 8192), 16, 0, 0); } while (0)
; #define PG8_LDA(dst, b, h) do { _Pragma("unroll") for (int m = 0; m < 4; ++m) _Pragma("unroll") for (int k = 0; k < 2; ++k) dst[m][k] = *(const PG8_LAS bf16x8*)(lds + PG8_SA(b, h) + aoff + m * 2048 + k * 1024); } while (0)
; #define PG8_LDB(dst, b, h) do { _Pragma("unroll") for (int n = 0; n < 2; ++n) _Pragma("unroll") for (int k = 0; k < 2; ++k) dst[n][k] = *(const PG8_LAS bf16x8*)(lds + PG8_SB(b, h) + boff + n * 2048 + k * 1024); } while (0)
; #define PG8_MMA(ai, bj, At, Bt) do { __builtin_amdgcn_s_setprio(1); _Pragma("unroll") for (int m = 0; m < 4; ++m) _Pragma("unroll") for (int n = 0; n < 2; ++n) _Pragma("unroll") for (int k = 0; k < 2; ++k) \
;         acc[ai][bj][m][n] = __builtin_amdgcn_mfma_f32_16x16x32_bf16(Bt[n][k], At[m][k], acc[ai][bj][m][n], 0, 0, 0); __builtin_amdgcn_s_setprio(0); } while (0)
; #define PG8_WAIT_V(n) asm volatile("s_waitcnt vmcnt(" #n ")" ::: "memory")
; #define PG8_WAIT_L(n) asm volatile("s_waitcnt lgkmcnt(" #n ")" ::: "memory")
; #define PG8_BAR __builtin_amdgcn_s_barrier()
; #define PG8_SCHED __builtin_amdgcn_sched_barrier(0)
; template <class Epi, class Sched, bool ALIGN_EPI = false, bool SP2 = false, bool A_TILED = false, bool B_TILED = false>
; __device__ __forceinline__ void gemm_phase(PG8_LAS unsigned char* lds, const Gemm g, const Sched& S, const Epi& E) {
;     ...
;             PG8_WAIT_V(8); PG8_WAIT_L(0); PG8_BAR; PG8_MMA(1, 0, At, B0); PG8_MMA(1, 1, At, B1); PG8_BAR; PG8_SCHED;
;             PG8_LDB(B0, 1, 0); PG8_LDB(B1, 1, 1); PG8_SCHED; PG8_LDA(At, 1, 0); PG8_STAGE(PG8_SA(0, 1), a2 + hstepA, voffA);
;             PG8_WAIT_V(8); PG8_WAIT_L(0); PG8_BAR; PG8_MMA(0, 0, At, B0); PG8_MMA(0, 1, At, B1); PG8_BAR; PG8_SCHED;
	s_setprio 1
	s_waitcnt lgkmcnt(0)
	v_mfma_f32_16x16x32_bf16 v[62:65], v[140:143], v[182:185], v[62:65]
	v_mfma_f32_16x16x32_bf16 v[58:61], v[148:151], v[182:185], v[58:61]
	v_mfma_f32_16x16x32_bf16 v[50:53], v[148:151], v[196:199], v[50:53]
	v_mfma_f32_16x16x32_bf16 v[54:57], v[140:143], v[196:199], v[54:57]
	v_mfma_f32_16x16x32_bf16 v[46:49], v[140:143], v[204:207], v[46:49]
	v_mfma_f32_16x16x32_bf16 v[38:41], v[148:151], v[204:207], v[38:41]
	v_mfma_f32_16x16x32_bf16 v[22:25], v[148:151], v[212:215], v[22:25]
	v_mfma_f32_16x16x32_bf16 v[30:33], v[140:143], v[212:215], v[30:33]
	v_mfma_f32_16x16x32_bf16 v[62:65], v[144:147], v[190:193], v[62:65]
	v_mfma_f32_16x16x32_bf16 v[58:61], v[152:155], v[190:193], v[58:61]
	v_mfma_f32_16x16x32_bf16 v[50:53], v[152:155], v[200:203], v[50:53]
	v_mfma_f32_16x16x32_bf16 v[54:57], v[144:147], v[200:203], v[54:57]
	v_mfma_f32_16x16x32_bf16 v[46:49], v[144:147], v[208:211], v[46:49]
	v_mfma_f32_16x16x32_bf16 v[38:41], v[152:155], v[208:211], v[38:41]
	v_mfma_f32_16x16x32_bf16 v[22:25], v[152:155], v[216:219], v[22:25]
	v_mfma_f32_16x16x32_bf16 v[30:33], v[144:147], v[216:219], v[30:33]
	s_setprio 0
	s_setprio 1
	v_mfma_f32_16x16x32_bf16 v[42:45], v[156:159], v[182:185], v[42:45]
	v_mfma_f32_16x16x32_bf16 v[34:37], v[164:167], v[182:185], v[34:37]
	v_mfma_f32_16x16x32_bf16 v[18:21], v[164:167], v[196:199], v[18:21]
	v_mfma_f32_16x16x32_bf16 v[26:29], v[156:159], v[196:199], v[26:29]
	v_mfma_f32_16x16x32_bf16 v[14:17], v[156:159], v[204:207], v[14:17]
	v_mfma_f32_16x16x32_bf16 v[10:13], v[164:167], v[204:207], v[10:13]
	v_mfma_f32_16x16x32_bf16 v[2:5], v[164:167], v[212:215], v[2:5]
	v_mfma_f32_16x16x32_bf16 v[6:9], v[156:159], v[212:215], v[6:9]
	v_mfma_f32_16x16x32_bf16 v[42:45], v[160:163], v[190:193], v[42:45]
	v_mfma_f32_16x16x32_bf16 v[34:37], v[178:181], v[190:193], v[34:37]
	v_mfma_f32_16x16x32_bf16 v[18:21], v[178:181], v[200:203], v[18:21]
	v_mfma_f32_16x16x32_bf16 v[26:29], v[160:163], v[200:203], v[26:29]
	v_mfma_f32_16x16x32_bf16 v[14:17], v[160:163], v[208:211], v[14:17]
	v_mfma_f32_16x16x32_bf16 v[10:13], v[178:181], v[208:211], v[10:13]
	v_mfma_f32_16x16x32_bf16 v[2:5], v[178:181], v[216:219], v[2:5]
	v_mfma_f32_16x16x32_bf16 v[6:9], v[160:163], v[216:219], v[6:9]
	s_setprio 0
	s_barrier
	s_add_i32 s45, 0, 0x18000
	v_add_u32_e32 v139, s45, v136
	s_add_i32 s46, 0, 0x1c000
	ds_read_b128 v[140:143], v139
	ds_read_b128 v[144:147], v139 offset:1024
	ds_read_b128 v[148:151], v139 offset:2048
	ds_read_b128 v[152:155], v139 offset:3072
	v_add_u32_e32 v139, s46, v136
	ds_read_b128 v[156:159], v139
	ds_read_b128 v[160:163], v139 offset:1024
	ds_read_b128 v[164:167], v139 offset:2048
	ds_read_b128 v[178:181], v139 offset:3072
	s_add_u32 s34, s34, 0x100000
	s_addc_u32 s35, s35, 0
	s_mov_b32 m0, s36
	v_lshl_add_u64 v[224:225], s[34:35], 0, v[170:171]
	ds_read_b128 v[182:185], v138 offset:32768
	ds_read_b128 v[190:193], v138 offset:33792
	ds_read_b128 v[196:199], v138 offset:34816
	ds_read_b128 v[200:203], v138 offset:35840
	ds_read_b128 v[204:207], v138 offset:36864
	ds_read_b128 v[208:211], v138 offset:37888
	ds_read_b128 v[212:215], v138 offset:38912
	ds_read_b128 v[216:219], v138 offset:39936
	global_load_lds_dwordx4 v[224:225], off
	v_lshl_add_u64 v[224:225], s[34:35], 0, v[174:175]
	s_mov_b32 m0, s37
	s_nop 0
	global_load_lds_dwordx4 v[224:225], off
	s_waitcnt vmcnt(8)
	s_waitcnt lgkmcnt(0)
	s_barrier
	s_setprio 1
	s_waitcnt lgkmcnt(0)
	v_mfma_f32_16x16x32_bf16 v[126:129], v[140:143], v[182:185], v[126:129]
	v_mfma_f32_16x16x32_bf16 v[122:125], v[148:151], v[182:185], v[122:125]
	v_mfma_f32_16x16x32_bf16 v[114:117], v[148:151], v[196:199], v[114:117]
	v_mfma_f32_16x16x32_bf16 v[118:121], v[140:143], v[196:199], v[118:121]
	v_mfma_f32_16x16x32_bf16 v[110:113], v[140:143], v[204:207], v[110:113]
	v_mfma_f32_16x16x32_bf16 v[102:105], v[148:151], v[204:207], v[102:105]
	v_mfma_f32_16x16x32_bf16 v[86:89], v[148:151], v[212:215], v[86:89]
	v_mfma_f32_16x16x32_bf16 v[94:97], v[140:143], v[212:215], v[94:97]
	v_mfma_f32_16x16x32_bf16 v[126:129], v[144:147], v[190:193], v[126:129]
	v_mfma_f32_16x16x32_bf16 v[122:125], v[152:155], v[190:193], v[122:125]
	v_mfma_f32_16x16x32_bf16 v[114:117], v[152:155], v[200:203], v[114:117]
	v_mfma_f32_16x16x32_bf16 v[118:121], v[144:147], v[200:203], v[118:121]
	v_mfma_f32_16x16x32_bf16 v[110:113], v[144:147], v[208:211], v[110:113]
	v_mfma_f32_16x16x32_bf16 v[102:105], v[152:155], v[208:211], v[102:105]
	v_mfma_f32_16x16x32_bf16 v[86:89], v[152:155], v[216:219], v[86:89]
	v_mfma_f32_16x16x32_bf16 v[94:97], v[144:147], v[216:219], v[94:97]
	s_setprio 0
	s_setprio 1
	v_mfma_f32_16x16x32_bf16 v[106:109], v[156:159], v[182:185], v[106:109]
	v_mfma_f32_16x16x32_bf16 v[98:101], v[164:167], v[182:185], v[98:101]
	v_mfma_f32_16x16x32_bf16 v[82:85], v[164:167], v[196:199], v[82:85]
	v_mfma_f32_16x16x32_bf16 v[90:93], v[156:159], v[196:199], v[90:93]
	v_mfma_f32_16x16x32_bf16 v[78:81], v[156:159], v[204:207], v[78:81]
	v_mfma_f32_16x16x32_bf16 v[74:77], v[164:167], v[204:207], v[74:77]
	v_mfma_f32_16x16x32_bf16 v[66:69], v[164:167], v[212:215], v[66:69]
	v_mfma_f32_16x16x32_bf16 v[70:73], v[156:159], v[212:215], v[70:73]
	v_mfma_f32_16x16x32_bf16 v[106:109], v[160:163], v[190:193], v[106:109]
	v_mfma_f32_16x16x32_bf16 v[98:101], v[178:181], v[190:193], v[98:101]
	v_mfma_f32_16x16x32_bf16 v[82:85], v[178:181], v[200:203], v[82:85]
	v_mfma_f32_16x16x32_bf16 v[90:93], v[160:163], v[200:203], v[90:93]
	v_mfma_f32_16x16x32_bf16 v[78:81], v[160:163], v[208:211], v[78:81]
	v_mfma_f32_16x16x32_bf16 v[74:77], v[178:181], v[208:211], v[74:77]
	v_mfma_f32_16x16x32_bf16 v[66:69], v[178:181], v[216:219], v[66:69]
	v_mfma_f32_16x16x32_bf16 v[70:73], v[160:163], v[216:219], v[70:73]
	s_setprio 0
	s_barrier
; #define PG8_STAGE(bufoff, gbase, voff) do { _Pragma("unroll") for (int _i = 0; _i < 2; ++_i) \
;         __builtin_amdgcn_global_load_lds((const unsigned*)((const char*)(gbase) + (voff)[_i]), (PG8_LAS unsigned*)(lds + (bufoff) + ldsw + _i * 8192), 16, 0, 0); } while (0)
; #define PG8_LDA(dst, b, h) do { _Pragma("unroll") for (int m = 0; m < 4; ++m) _Pragma("unroll") for (int k = 0; k < 2; ++k) dst[m][k] = *(const PG8_LAS bf16x8*)(lds + PG8_SA(b, h) + aoff + m * 2048 + k * 1024); } while (0)
; #define PG8_MMA(ai, bj, At, Bt) do { __builtin_amdgcn_s_setprio(1); _Pragma("unroll") for (int m = 0; m < 4; ++m) _Pragma("unroll") for (int n = 0; n < 2; ++n) _Pragma("unroll") for (int k = 0; k < 2; ++k) \
;         acc[ai][bj][m][n] = __builtin_amdgcn_mfma_f32_16x16x32_bf16(Bt[n][k], At[m][k], acc[ai][bj][m][n], 0, 0, 0); __builtin_amdgcn_s_setprio(0); } while (0)
; #define PG8_WAIT_V(n) asm volatile("s_waitcnt vmcnt(" #n ")" ::: "memory")
; #define PG8_WAIT_L(n) asm volatile("s_waitcnt lgkmcnt(" #n ")" ::: "memory")
; #define PG8_BAR __builtin_amdgcn_s_barrier()
; #define PG8_SCHED __builtin_amdgcn_sched_barrier(0)
; template <class Epi, class Sched, bool ALIGN_EPI = false, bool SP2 = false, bool A_TILED = false, bool B_TILED = false>
; __device__ __forceinline__ void gemm_phase(PG8_LAS unsigned char* lds, const Gemm g, const Sched& S, const Epi& E) {
;     ...
;             PG8_LDA(At, 1, 1); PG8_STAGE(PG8_SB(1, 0), b3, voffB); PG8_STAGE(PG8_SB(1, 1), b3 + hstepB, voffB); PG8_STAGE(PG8_SA(1, 0), a3, voffA);
;             PG8_WAIT_V(8); PG8_WAIT_L(0); PG8_BAR; PG8_MMA(1, 0, At, B0); PG8_MMA(1, 1, At, B1); PG8_BAR; PG8_SCHED;
	s_add_i32 s34, s45, s28
	v_lshl_add_u64 v[168:169], v[168:169], 0, s[8:9]
	s_mov_b32 m0, s34
	ds_read_b128 v[182:185], v138 offset:49152
	ds_read_b128 v[190:193], v138 offset:50176
	ds_read_b128 v[196:199], v138 offset:51200
	ds_read_b128 v[200:203], v138 offset:52224
	ds_read_b128 v[204:207], v138 offset:53248
	ds_read_b128 v[208:211], v138 offset:54272
	ds_read_b128 v[212:215], v138 offset:55296
	ds_read_b128 v[216:219], v138 offset:56320
	global_load_lds_dwordx4 v[168:169], off
	s_add_i32 m0, s34, 0x2000
	s_add_u32 s30, s30, 0x100080
	v_lshl_add_u64 v[168:169], v[186:187], 0, s[8:9]
	s_addc_u32 s31, s31, 0
	s_add_i32 s34, s46, s28
	global_load_lds_dwordx4 v[168:169], off
	v_lshl_add_u64 v[168:169], s[30:31], 0, v[172:173]
	s_mov_b32 m0, s34
	s_nop 0
	global_load_lds_dwordx4 v[168:169], off
	v_lshl_add_u64 v[168:169], s[30:31], 0, v[176:177]
	s_add_i32 m0, s34, 0x2000
	s_nop 0
	global_load_lds_dwordx4 v[168:169], off
	v_lshl_add_u64 v[168:169], v[220:221], 0, s[8:9]
	s_mov_b32 m0, s38
	s_nop 0
	global_load_lds_dwordx4 v[168:169], off
	v_lshl_add_u64 v[168:169], v[222:223], 0, s[8:9]
	s_mov_b32 m0, s39
	s_nop 0
	global_load_lds_dwordx4 v[168:169], off
	s_waitcnt vmcnt(8)
	s_waitcnt lgkmcnt(0)
	s_barrier
	s_setprio 1
	s_waitcnt lgkmcnt(0)
	v_mfma_f32_16x16x32_bf16 v[62:65], v[140:143], v[182:185], v[62:65]
	v_mfma_f32_16x16x32_bf16 v[58:61], v[148:151], v[182:185], v[58:61]
	v_mfma_f32_16x16x32_bf16 v[50:53], v[148:151], v[196:199], v[50:53]
	v_mfma_f32_16x16x32_bf16 v[54:57], v[140:143], v[196:199], v[54:57]
	v_mfma_f32_16x16x32_bf16 v[46:49], v[140:143], v[204:207], v[46:49]
	v_mfma_f32_16x16x32_bf16 v[38:41], v[148:151], v[204:207], v[38:41]
	v_mfma_f32_16x16x32_bf16 v[22:25], v[148:151], v[212:215], v[22:25]
	v_mfma_f32_16x16x32_bf16 v[30:33], v[140:143], v[212:215], v[30:33]
	v_mfma_f32_16x16x32_bf16 v[62:65], v[144:147], v[190:193], v[62:65]
	v_mfma_f32_16x16x32_bf16 v[58:61], v[152:155], v[190:193], v[58:61]
	v_mfma_f32_16x16x32_bf16 v[50:53], v[152:155], v[200:203], v[50:53]
	v_mfma_f32_16x16x32_bf16 v[54:57], v[144:147], v[200:203], v[54:57]
	v_mfma_f32_16x16x32_bf16 v[46:49], v[144:147], v[208:211], v[46:49]
	v_mfma_f32_16x16x32_bf16 v[38:41], v[152:155], v[208:211], v[38:41]
	v_mfma_f32_16x16x32_bf16 v[22:25], v[152:155], v[216:219], v[22:25]
	v_mfma_f32_16x16x32_bf16 v[30:33], v[144:147], v[216:219], v[30:33]
	s_setprio 0
	s_setprio 1
	v_mfma_f32_16x16x32_bf16 v[42:45], v[156:159], v[182:185], v[42:45]
	v_mfma_f32_16x16x32_bf16 v[34:37], v[164:167], v[182:185], v[34:37]
	v_mfma_f32_16x16x32_bf16 v[18:21], v[164:167], v[196:199], v[18:21]
	v_mfma_f32_16x16x32_bf16 v[26:29], v[156:159], v[196:199], v[26:29]
	v_mfma_f32_16x16x32_bf16 v[14:17], v[156:159], v[204:207], v[14:17]
	v_mfma_f32_16x16x32_bf16 v[10:13], v[164:167], v[204:207], v[10:13]
	v_mfma_f32_16x16x32_bf16 v[2:5], v[164:167], v[212:215], v[2:5]
	v_mfma_f32_16x16x32_bf16 v[6:9], v[156:159], v[212:215], v[6:9]
	v_mfma_f32_16x16x32_bf16 v[42:45], v[160:163], v[190:193], v[42:45]
	v_mfma_f32_16x16x32_bf16 v[34:37], v[178:181], v[190:193], v[34:37]
	v_mfma_f32_16x16x32_bf16 v[18:21], v[178:181], v[200:203], v[18:21]
	v_mfma_f32_16x16x32_bf16 v[26:29], v[160:163], v[200:203], v[26:29]
	v_mfma_f32_16x16x32_bf16 v[14:17], v[160:163], v[208:211], v[14:17]
	v_mfma_f32_16x16x32_bf16 v[10:13], v[178:181], v[208:211], v[10:13]
	v_mfma_f32_16x16x32_bf16 v[2:5], v[178:181], v[216:219], v[2:5]
	v_mfma_f32_16x16x32_bf16 v[6:9], v[160:163], v[216:219], v[6:9]
	s_setprio 0
	s_barrier
	s_add_i32 s44, s44, 2
	s_add_u32 s26, s26, 0x100
	s_addc_u32 s27, s27, 0
	s_add_u32 s42, s42, 0x100
	s_addc_u32 s43, s43, 0
	s_cmp_gt_u32 s44, 5
	s_cbranch_scc0 .LBB0_905
	s_and_b64 vcc, exec, s[10:11]
	s_cbranch_vccz .LBB0_908
	s_barrier

; #define PG8_STAGE(bufoff, gbase, voff) do { _Pragma("unroll") for (int _i = 0; _i < 2; ++_i) \
;         __builtin_amdgcn_global_load_lds((const unsigned*)((const char*)(gbase) + (voff)[_i]), (PG8_LAS unsigned*)(lds + (bufoff) + ldsw + _i * 8192), 16, 0, 0); } while (0)
; #define PG8_LDA(dst, b, h) do { _Pragma("unroll") for (int m = 0; m < 4; ++m) _Pragma("unroll") for (int k = 0; k < 2; ++k) dst[m][k] = *(const PG8_LAS bf16x8*)(lds + PG8_SA(b, h) + aoff + m * 2048 + k * 1024); } while (0)
; #define PG8_LDB(dst, b, h) do { _Pragma("unroll") for (int n = 0; n < 2; ++n) _Pragma("unroll") for (int k = 0; k < 2; ++k) dst[n][k] = *(const PG8_LAS bf16x8*)(lds + PG8_SB(b, h) + boff + n * 2048 + k * 1024); } while (0)
; #define PG8_MMA(ai, bj, At, Bt) do { __builtin_amdgcn_s_setprio(1); _Pragma("unroll") for (int m = 0; m < 4; ++m) _Pragma("unroll") for (int n = 0; n < 2; ++n) _Pragma("unroll") for (int k = 0; k < 2; ++k) \
;         acc[ai][bj][m][n] = __builtin_amdgcn_mfma_f32_16x16x32_bf16(Bt[n][k], At[m][k], acc[ai][bj][m][n], 0, 0, 0); __builtin_amdgcn_s_setprio(0); } while (0)
; #define PG8_WAIT_V(n) asm volatile("s_waitcnt vmcnt(" #n ")" ::: "memory")
; #define PG8_WAIT_L(n) asm volatile("s_waitcnt lgkmcnt(" #n ")" ::: "memory")
; #define PG8_BAR __builtin_amdgcn_s_barrier()
; #define PG8_SCHED __builtin_amdgcn_sched_barrier(0)
; template <class Epi, class Sched, bool ALIGN_EPI = false, bool SP2 = false, bool A_TILED = false, bool B_TILED = false>
; __device__ __forceinline__ void gemm_phase(PG8_LAS unsigned char* lds, const Gemm g, const Sched& S, const Epi& E) {
;     ...
;             PG8_LDB(B0, 0, 0); PG8_LDB(B1, 0, 1); PG8_SCHED; PG8_LDA(At, 0, 0); PG8_STAGE(PG8_SA(1, 1), a1 + hstepA, voffA);
;             PG8_WAIT_V(8); PG8_WAIT_L(0); PG8_BAR; PG8_MMA(0, 0, At, B0); PG8_MMA(0, 1, At, B1); PG8_BAR; PG8_SCHED;
;             PG8_LDA(At, 0, 1); PG8_STAGE(PG8_SB(0, 0), b2, voffB); PG8_STAGE(PG8_SB(0, 1), b2 + hstepB, voffB); PG8_STAGE(PG8_SA(0, 0), a2, voffA);
.LBB0_1069:
	ds_read_b128 v[142:145], v161
	ds_read_b128 v[164:167], v161 offset:1024
	ds_read_b128 v[168:171], v161 offset:2048
	ds_read_b128 v[172:175], v161 offset:3072
	ds_read_b128 v[176:179], v162
	ds_read_b128 v[180:183], v162 offset:1024
	ds_read_b128 v[184:187], v162 offset:2048
	ds_read_b128 v[190:193], v162 offset:3072
	s_add_u32 s36, s34, 0x4000
	s_addc_u32 s37, s35, 0
	s_cmpk_eq_i32 s67, 0xa8
	s_cselect_b32 s40, s28, s36
	s_cselect_b32 s41, s29, s37
	s_cselect_b32 s38, s30, s65
	s_cselect_b32 s39, s31, s66
	s_add_u32 s36, s40, 0x8000
	s_addc_u32 s37, s41, 0
	v_lshl_add_u64 v[146:147], s[34:35], 0, v[138:139]
	s_add_i32 m0, s46, 0xc000
	ds_read_b128 v[194:197], v163
	ds_read_b128 v[198:201], v163 offset:1024
	ds_read_b128 v[202:205], v163 offset:2048
	ds_read_b128 v[206:209], v163 offset:3072
	ds_read_b128 v[210:213], v163 offset:4096
	ds_read_b128 v[214:217], v163 offset:5120
	ds_read_b128 v[218:221], v163 offset:6144
	ds_read_b128 v[222:225], v163 offset:7168
	global_load_lds_dwordx4 v[146:147], off
	v_lshl_add_u64 v[146:147], s[34:35], 0, v[140:141]
	s_add_i32 m0, s46, 0xe000
	s_nop 0
	global_load_lds_dwordx4 v[146:147], off
	s_waitcnt vmcnt(8)
	s_waitcnt lgkmcnt(0)
	s_barrier
	s_setprio 1
	s_waitcnt lgkmcnt(0)
	v_mfma_f32_16x16x32_bf16 v[126:129], v[142:145], v[194:197], v[126:129]
	v_mfma_f32_16x16x32_bf16 v[122:125], v[168:171], v[194:197], v[122:125]
	v_mfma_f32_16x16x32_bf16 v[106:109], v[168:171], v[202:205], v[106:109]
	v_mfma_f32_16x16x32_bf16 v[110:113], v[142:145], v[202:205], v[110:113]
	v_mfma_f32_16x16x32_bf16 v[94:97], v[142:145], v[210:213], v[94:97]
	v_mfma_f32_16x16x32_bf16 v[90:93], v[168:171], v[210:213], v[90:93]
	v_mfma_f32_16x16x32_bf16 v[74:77], v[168:171], v[218:221], v[74:77]
	v_mfma_f32_16x16x32_bf16 v[78:81], v[142:145], v[218:221], v[78:81]
	v_mfma_f32_16x16x32_bf16 v[126:129], v[164:167], v[198:201], v[126:129]
	v_mfma_f32_16x16x32_bf16 v[122:125], v[172:175], v[198:201], v[122:125]
	v_mfma_f32_16x16x32_bf16 v[106:109], v[172:175], v[206:209], v[106:109]
	v_mfma_f32_16x16x32_bf16 v[110:113], v[164:167], v[206:209], v[110:113]
	v_mfma_f32_16x16x32_bf16 v[94:97], v[164:167], v[214:217], v[94:97]
	v_mfma_f32_16x16x32_bf16 v[90:93], v[172:175], v[214:217], v[90:93]
	v_mfma_f32_16x16x32_bf16 v[74:77], v[172:175], v[222:225], v[74:77]
	v_mfma_f32_16x16x32_bf16 v[78:81], v[164:167], v[222:225], v[78:81]
	s_setprio 0
	s_setprio 1
	v_mfma_f32_16x16x32_bf16 v[118:121], v[176:179], v[194:197], v[118:121]
	v_mfma_f32_16x16x32_bf16 v[114:117], v[184:187], v[194:197], v[114:117]
	v_mfma_f32_16x16x32_bf16 v[98:101], v[184:187], v[202:205], v[98:101]
	v_mfma_f32_16x16x32_bf16 v[102:105], v[176:179], v[202:205], v[102:105]
	v_mfma_f32_16x16x32_bf16 v[86:89], v[176:179], v[210:213], v[86:89]
	v_mfma_f32_16x16x32_bf16 v[82:85], v[184:187], v[210:213], v[82:85]
	v_mfma_f32_16x16x32_bf16 v[66:69], v[184:187], v[218:221], v[66:69]
	v_mfma_f32_16x16x32_bf16 v[70:73], v[176:179], v[218:221], v[70:73]
	v_mfma_f32_16x16x32_bf16 v[118:121], v[180:183], v[198:201], v[118:121]
	v_mfma_f32_16x16x32_bf16 v[114:117], v[190:193], v[198:201], v[114:117]
	v_mfma_f32_16x16x32_bf16 v[98:101], v[190:193], v[206:209], v[98:101]
	v_mfma_f32_16x16x32_bf16 v[102:105], v[180:183], v[206:209], v[102:105]
	v_mfma_f32_16x16x32_bf16 v[86:89], v[180:183], v[214:217], v[86:89]
	v_mfma_f32_16x16x32_bf16 v[82:85], v[190:193], v[214:217], v[82:85]
	v_mfma_f32_16x16x32_bf16 v[66:69], v[190:193], v[222:225], v[66:69]
	v_mfma_f32_16x16x32_bf16 v[70:73], v[180:183], v[222:225], v[70:73]
	s_setprio 0
	s_barrier
	s_add_i32 s68, s58, s45
	v_lshl_add_u64 v[146:147], s[38:39], 0, v[134:135]
	s_mov_b32 m0, s68
	ds_read_b128 v[194:197], v163 offset:16384
	ds_read_b128 v[198:201], v163 offset:17408
	ds_read_b128 v[202:205], v163 offset:18432
	ds_read_b128 v[206:209], v163 offset:19456
	ds_read_b128 v[210:213], v163 offset:20480
	ds_read_b128 v[214:217], v163 offset:21504
	ds_read_b128 v[218:221], v163 offset:22528
	ds_read_b128 v[222:225], v163 offset:23552
	global_load_lds_dwordx4 v[146:147], off
	s_add_i32 m0, s68, 0x2000
	s_add_u32 s68, s38, 0x2b0000
	v_lshl_add_u64 v[226:227], s[38:39], 0, v[136:137]
	s_addc_u32 s69, s39, 0
	s_add_i32 s70, s59, s45
	global_load_lds_dwordx4 v[226:227], off
	v_lshl_add_u64 v[228:229], s[68:69], 0, v[134:135]
	s_mov_b32 m0, s70
	s_nop 0
	global_load_lds_dwordx4 v[228:229], off
	v_lshl_add_u64 v[228:229], s[68:69], 0, v[136:137]
	s_add_i32 m0, s70, 0x2000
	s_nop 0
	global_load_lds_dwordx4 v[228:229], off
	v_lshl_add_u64 v[228:229], s[40:41], 0, v[130:131]
	s_mov_b32 m0, s46
	s_nop 0
	global_load_lds_dwordx4 v[228:229], off
	v_lshl_add_u64 v[228:229], s[40:41], 0, v[132:133]
	s_mov_b32 m0, s47
	s_nop 0
	global_load_lds_dwordx4 v[228:229], off
	s_waitcnt vmcnt(8)
	s_waitcnt lgkmcnt(0)
	s_barrier
; #define PG8_STAGE(bufoff, gbase, voff) do { _Pragma("unroll") for (int _i = 0; _i < 2; ++_i) \
;         __builtin_amdgcn_global_load_lds((const unsigned*)((const char*)(gbase) + (voff)[_i]), (PG8_LAS unsigned*)(lds + (bufoff) + ldsw + _i * 8192), 16, 0, 0); } while (0)
; #define PG8_LDA(dst, b, h) do { _Pragma("unroll") for (int m = 0; m < 4; ++m) _Pragma("unroll") for (int k = 0; k < 2; ++k) dst[m][k] = *(const PG8_LAS bf16x8*)(lds + PG8_SA(b, h) + aoff + m * 2048 + k * 1024); } while (0)
; #define PG8_LDB(dst, b, h) do { _Pragma("unroll") for (int n = 0; n < 2; ++n) _Pragma("unroll") for (int k = 0; k < 2; ++k) dst[n][k] = *(const PG8_LAS bf16x8*)(lds + PG8_SB(b, h) + boff + n * 2048 + k * 1024); } while (0)
; #define PG8_MMA(ai, bj, At, Bt) do { __builtin_amdgcn_s_setprio(1); _Pragma("unroll") for (int m = 0; m < 4; ++m) _Pragma("unroll") for (int n = 0; n < 2; ++n) _Pragma("unroll") for (int k = 0; k < 2; ++k) \
;         acc[ai][bj][m][n] = __builtin_amdgcn_mfma_f32_16x16x32_bf16(Bt[n][k], At[m][k], acc[ai][bj][m][n], 0, 0, 0); __builtin_amdgcn_s_setprio(0); } while (0)
; #define PG8_WAIT_V(n) asm volatile("s_waitcnt vmcnt(" #n ")" ::: "memory")
; #define PG8_WAIT_L(n) asm volatile("s_waitcnt lgkmcnt(" #n ")" ::: "memory")
; #define PG8_BAR __builtin_amdgcn_s_barrier()
; #define PG8_SCHED __builtin_amdgcn_sched_barrier(0)
; template <class Epi, class Sched, bool ALIGN_EPI = false, bool SP2 = false, bool A_TILED = false, bool B_TILED = false>
; __device__ __forceinline__ void gemm_phase(PG8_LAS unsigned char* lds, const Gemm g, const Sched& S, const Epi& E) {
;     ...
;             PG8_WAIT_V(8); PG8_WAIT_L(0); PG8_BAR; PG8_MMA(1, 0, At, B0); PG8_MMA(1, 1, At, B1); PG8_BAR; PG8_SCHED;
;             PG8_LDB(B0, 1, 0); PG8_LDB(B1, 1, 1); PG8_SCHED; PG8_LDA(At, 1, 0); PG8_STAGE(PG8_SA(0, 1), a2 + hstepA, voffA);
;             PG8_WAIT_V(8); PG8_WAIT_L(0); PG8_BAR; PG8_MMA(0, 0, At, B0); PG8_MMA(0, 1, At, B1); PG8_BAR; PG8_SCHED;
	s_setprio 1
	s_waitcnt lgkmcnt(0)
	v_mfma_f32_16x16x32_bf16 v[62:65], v[142:145], v[194:197], v[62:65]
	v_mfma_f32_16x16x32_bf16 v[58:61], v[168:171], v[194:197], v[58:61]
	v_mfma_f32_16x16x32_bf16 v[42:45], v[168:171], v[202:205], v[42:45]
	v_mfma_f32_16x16x32_bf16 v[46:49], v[142:145], v[202:205], v[46:49]
	v_mfma_f32_16x16x32_bf16 v[30:33], v[142:145], v[210:213], v[30:33]
	v_mfma_f32_16x16x32_bf16 v[26:29], v[168:171], v[210:213], v[26:29]
	v_mfma_f32_16x16x32_bf16 v[10:13], v[168:171], v[218:221], v[10:13]
	v_mfma_f32_16x16x32_bf16 v[14:17], v[142:145], v[218:221], v[14:17]
	v_mfma_f32_16x16x32_bf16 v[62:65], v[164:167], v[198:201], v[62:65]
	v_mfma_f32_16x16x32_bf16 v[58:61], v[172:175], v[198:201], v[58:61]
	v_mfma_f32_16x16x32_bf16 v[42:45], v[172:175], v[206:209], v[42:45]
	v_mfma_f32_16x16x32_bf16 v[46:49], v[164:167], v[206:209], v[46:49]
	v_mfma_f32_16x16x32_bf16 v[30:33], v[164:167], v[214:217], v[30:33]
	v_mfma_f32_16x16x32_bf16 v[26:29], v[172:175], v[214:217], v[26:29]
	v_mfma_f32_16x16x32_bf16 v[10:13], v[172:175], v[222:225], v[10:13]
	v_mfma_f32_16x16x32_bf16 v[14:17], v[164:167], v[222:225], v[14:17]
	s_setprio 0
	s_setprio 1
	v_mfma_f32_16x16x32_bf16 v[54:57], v[176:179], v[194:197], v[54:57]
	v_mfma_f32_16x16x32_bf16 v[50:53], v[184:187], v[194:197], v[50:53]
	v_mfma_f32_16x16x32_bf16 v[34:37], v[184:187], v[202:205], v[34:37]
	v_mfma_f32_16x16x32_bf16 v[38:41], v[176:179], v[202:205], v[38:41]
	v_mfma_f32_16x16x32_bf16 v[22:25], v[176:179], v[210:213], v[22:25]
	v_mfma_f32_16x16x32_bf16 v[18:21], v[184:187], v[210:213], v[18:21]
	v_mfma_f32_16x16x32_bf16 v[2:5], v[184:187], v[218:221], v[2:5]
	v_mfma_f32_16x16x32_bf16 v[6:9], v[176:179], v[218:221], v[6:9]
	v_mfma_f32_16x16x32_bf16 v[54:57], v[180:183], v[198:201], v[54:57]
	v_mfma_f32_16x16x32_bf16 v[50:53], v[190:193], v[198:201], v[50:53]
	v_mfma_f32_16x16x32_bf16 v[34:37], v[190:193], v[206:209], v[34:37]
	v_mfma_f32_16x16x32_bf16 v[38:41], v[180:183], v[206:209], v[38:41]
	v_mfma_f32_16x16x32_bf16 v[22:25], v[180:183], v[214:217], v[22:25]
	v_mfma_f32_16x16x32_bf16 v[18:21], v[190:193], v[214:217], v[18:21]
	v_mfma_f32_16x16x32_bf16 v[2:5], v[190:193], v[222:225], v[2:5]
	v_mfma_f32_16x16x32_bf16 v[6:9], v[180:183], v[222:225], v[6:9]
	s_setprio 0
	s_barrier
	s_add_i32 s68, 0, 0x18000
	s_add_i32 s69, 0, 0x1c000
	v_add_u32_e32 v172, s68, v159
	v_add_u32_e32 v188, s69, v159
	ds_read_b128 v[142:145], v172
	ds_read_b128 v[164:167], v172 offset:1024
	ds_read_b128 v[168:171], v172 offset:2048
	ds_read_b128 v[172:175], v172 offset:3072
	ds_read_b128 v[176:179], v188
	ds_read_b128 v[180:183], v188 offset:1024
	ds_read_b128 v[184:187], v188 offset:2048
	ds_read_b128 v[190:193], v188 offset:3072
	s_add_u32 s40, s40, 0x4000
	s_addc_u32 s41, s41, 0
	s_mov_b32 m0, s52
	v_lshl_add_u64 v[228:229], s[40:41], 0, v[130:131]
	ds_read_b128 v[194:197], v163 offset:32768
	ds_read_b128 v[198:201], v163 offset:33792
	ds_read_b128 v[202:205], v163 offset:34816
	ds_read_b128 v[206:209], v163 offset:35840
	ds_read_b128 v[210:213], v163 offset:36864
	ds_read_b128 v[214:217], v163 offset:37888
	ds_read_b128 v[218:221], v163 offset:38912
	ds_read_b128 v[222:225], v163 offset:39936
	global_load_lds_dwordx4 v[228:229], off
	v_lshl_add_u64 v[228:229], s[40:41], 0, v[132:133]
	s_mov_b32 m0, s53
	s_nop 0
	global_load_lds_dwordx4 v[228:229], off
	s_waitcnt vmcnt(8)
	s_waitcnt lgkmcnt(0)
	s_barrier
	s_setprio 1
	s_waitcnt lgkmcnt(0)
	v_mfma_f32_16x16x32_bf16 v[126:129], v[142:145], v[194:197], v[126:129]
	v_mfma_f32_16x16x32_bf16 v[122:125], v[168:171], v[194:197], v[122:125]
	v_mfma_f32_16x16x32_bf16 v[106:109], v[168:171], v[202:205], v[106:109]
	v_mfma_f32_16x16x32_bf16 v[110:113], v[142:145], v[202:205], v[110:113]
	v_mfma_f32_16x16x32_bf16 v[94:97], v[142:145], v[210:213], v[94:97]
	v_mfma_f32_16x16x32_bf16 v[90:93], v[168:171], v[210:213], v[90:93]
	v_mfma_f32_16x16x32_bf16 v[74:77], v[168:171], v[218:221], v[74:77]
	v_mfma_f32_16x16x32_bf16 v[78:81], v[142:145], v[218:221], v[78:81]
	v_mfma_f32_16x16x32_bf16 v[126:129], v[164:167], v[198:201], v[126:129]
	v_mfma_f32_16x16x32_bf16 v[122:125], v[172:175], v[198:201], v[122:125]
	v_mfma_f32_16x16x32_bf16 v[106:109], v[172:175], v[206:209], v[106:109]
	v_mfma_f32_16x16x32_bf16 v[110:113], v[164:167], v[206:209], v[110:113]
	v_mfma_f32_16x16x32_bf16 v[94:97], v[164:167], v[214:217], v[94:97]
	v_mfma_f32_16x16x32_bf16 v[90:93], v[172:175], v[214:217], v[90:93]
	v_mfma_f32_16x16x32_bf16 v[74:77], v[172:175], v[222:225], v[74:77]
	v_mfma_f32_16x16x32_bf16 v[78:81], v[164:167], v[222:225], v[78:81]
	s_setprio 0
	s_setprio 1
	v_mfma_f32_16x16x32_bf16 v[118:121], v[176:179], v[194:197], v[118:121]
	v_mfma_f32_16x16x32_bf16 v[114:117], v[184:187], v[194:197], v[114:117]
	v_mfma_f32_16x16x32_bf16 v[98:101], v[184:187], v[202:205], v[98:101]
	v_mfma_f32_16x16x32_bf16 v[102:105], v[176:179], v[202:205], v[102:105]
	v_mfma_f32_16x16x32_bf16 v[86:89], v[176:179], v[210:213], v[86:89]
	v_mfma_f32_16x16x32_bf16 v[82:85], v[184:187], v[210:213], v[82:85]
	v_mfma_f32_16x16x32_bf16 v[66:69], v[184:187], v[218:221], v[66:69]
	v_mfma_f32_16x16x32_bf16 v[70:73], v[176:179], v[218:221], v[70:73]
	v_mfma_f32_16x16x32_bf16 v[118:121], v[180:183], v[198:201], v[118:121]
	v_mfma_f32_16x16x32_bf16 v[114:117], v[190:193], v[198:201], v[114:117]
	v_mfma_f32_16x16x32_bf16 v[98:101], v[190:193], v[206:209], v[98:101]
	v_mfma_f32_16x16x32_bf16 v[102:105], v[180:183], v[206:209], v[102:105]
	v_mfma_f32_16x16x32_bf16 v[86:89], v[180:183], v[214:217], v[86:89]
	v_mfma_f32_16x16x32_bf16 v[82:85], v[190:193], v[214:217], v[82:85]
	v_mfma_f32_16x16x32_bf16 v[66:69], v[190:193], v[222:225], v[66:69]
	v_mfma_f32_16x16x32_bf16 v[70:73], v[180:183], v[222:225], v[70:73]
	s_setprio 0
	s_barrier
; #define PG8_STAGE(bufoff, gbase, voff) do { _Pragma("unroll") for (int _i = 0; _i < 2; ++_i) \
;         __builtin_amdgcn_global_load_lds((const unsigned*)((const char*)(gbase) + (voff)[_i]), (PG8_LAS unsigned*)(lds + (bufoff) + ldsw + _i * 8192), 16, 0, 0); } while (0)
; #define PG8_LDA(dst, b, h) do { _Pragma("unroll") for (int m = 0; m < 4; ++m) _Pragma("unroll") for (int k = 0; k < 2; ++k) dst[m][k] = *(const PG8_LAS bf16x8*)(lds + PG8_SA(b, h) + aoff + m * 2048 + k * 1024); } while (0)
; #define PG8_MMA(ai, bj, At, Bt) do { __builtin_amdgcn_s_setprio(1); _Pragma("unroll") for (int m = 0; m < 4; ++m) _Pragma("unroll") for (int n = 0; n < 2; ++n) _Pragma("unroll") for (int k = 0; k < 2; ++k) \
;         acc[ai][bj][m][n] = __builtin_amdgcn_mfma_f32_16x16x32_bf16(Bt[n][k], At[m][k], acc[ai][bj][m][n], 0, 0, 0); __builtin_amdgcn_s_setprio(0); } while (0)
; #define PG8_WAIT_V(n) asm volatile("s_waitcnt vmcnt(" #n ")" ::: "memory")
; #define PG8_WAIT_L(n) asm volatile("s_waitcnt lgkmcnt(" #n ")" ::: "memory")
; #define PG8_BAR __builtin_amdgcn_s_barrier()
; #define PG8_SCHED __builtin_amdgcn_sched_barrier(0)
; template <class Epi, class Sched, bool ALIGN_EPI = false, bool SP2 = false, bool A_TILED = false, bool B_TILED = false>
; __device__ __forceinline__ void gemm_phase(PG8_LAS unsigned char* lds, const Gemm g, const Sched& S, const Epi& E) {
;     ...
;             PG8_LDA(At, 1, 1); PG8_STAGE(PG8_SB(1, 0), b3, voffB); PG8_STAGE(PG8_SB(1, 1), b3 + hstepB, voffB); PG8_STAGE(PG8_SA(1, 0), a3, voffA);
;             PG8_WAIT_V(8); PG8_WAIT_L(0); PG8_BAR; PG8_MMA(1, 0, At, B0); PG8_MMA(1, 1, At, B1); PG8_BAR; PG8_SCHED;
	s_add_i32 s40, s68, s45
	v_lshl_add_u64 v[146:147], v[146:147], 0, s[16:17]
	s_mov_b32 m0, s40
	ds_read_b128 v[194:197], v163 offset:49152
	ds_read_b128 v[198:201], v163 offset:50176
	ds_read_b128 v[202:205], v163 offset:51200
	ds_read_b128 v[206:209], v163 offset:52224
	ds_read_b128 v[210:213], v163 offset:53248
	ds_read_b128 v[214:217], v163 offset:54272
	ds_read_b128 v[218:221], v163 offset:55296
	ds_read_b128 v[222:225], v163 offset:56320
	global_load_lds_dwordx4 v[146:147], off
	s_add_i32 m0, s40, 0x2000
	s_add_u32 s38, s38, 0x2b0080
	v_lshl_add_u64 v[146:147], v[226:227], 0, s[16:17]
	s_addc_u32 s39, s39, 0
	s_add_i32 s40, s69, s45
	global_load_lds_dwordx4 v[146:147], off
	v_lshl_add_u64 v[146:147], s[38:39], 0, v[134:135]
	s_mov_b32 m0, s40
	s_nop 0
	global_load_lds_dwordx4 v[146:147], off
	v_lshl_add_u64 v[146:147], s[38:39], 0, v[136:137]
	s_add_i32 m0, s40, 0x2000
	s_nop 0
	global_load_lds_dwordx4 v[146:147], off
	v_lshl_add_u64 v[146:147], s[36:37], 0, v[130:131]
	s_mov_b32 m0, s54
	s_nop 0
	global_load_lds_dwordx4 v[146:147], off
	v_lshl_add_u64 v[146:147], s[36:37], 0, v[132:133]
	s_mov_b32 m0, s55
	s_nop 0
	global_load_lds_dwordx4 v[146:147], off
	s_waitcnt vmcnt(8)
	s_waitcnt lgkmcnt(0)
	s_barrier
	s_setprio 1
	s_waitcnt lgkmcnt(0)
	v_mfma_f32_16x16x32_bf16 v[62:65], v[142:145], v[194:197], v[62:65]
	v_mfma_f32_16x16x32_bf16 v[58:61], v[168:171], v[194:197], v[58:61]
	v_mfma_f32_16x16x32_bf16 v[42:45], v[168:171], v[202:205], v[42:45]
	v_mfma_f32_16x16x32_bf16 v[46:49], v[142:145], v[202:205], v[46:49]
	v_mfma_f32_16x16x32_bf16 v[30:33], v[142:145], v[210:213], v[30:33]
	v_mfma_f32_16x16x32_bf16 v[26:29], v[168:171], v[210:213], v[26:29]
	v_mfma_f32_16x16x32_bf16 v[10:13], v[168:171], v[218:221], v[10:13]
	v_mfma_f32_16x16x32_bf16 v[14:17], v[142:145], v[218:221], v[14:17]
	v_mfma_f32_16x16x32_bf16 v[62:65], v[164:167], v[198:201], v[62:65]
	v_mfma_f32_16x16x32_bf16 v[58:61], v[172:175], v[198:201], v[58:61]
	v_mfma_f32_16x16x32_bf16 v[42:45], v[172:175], v[206:209], v[42:45]
	v_mfma_f32_16x16x32_bf16 v[46:49], v[164:167], v[206:209], v[46:49]
	v_mfma_f32_16x16x32_bf16 v[30:33], v[164:167], v[214:217], v[30:33]
	v_mfma_f32_16x16x32_bf16 v[26:29], v[172:175], v[214:217], v[26:29]
	v_mfma_f32_16x16x32_bf16 v[10:13], v[172:175], v[222:225], v[10:13]
	v_mfma_f32_16x16x32_bf16 v[14:17], v[164:167], v[222:225], v[14:17]
	s_setprio 0
	s_setprio 1
	v_mfma_f32_16x16x32_bf16 v[54:57], v[176:179], v[194:197], v[54:57]
	v_mfma_f32_16x16x32_bf16 v[50:53], v[184:187], v[194:197], v[50:53]
	v_mfma_f32_16x16x32_bf16 v[34:37], v[184:187], v[202:205], v[34:37]
	v_mfma_f32_16x16x32_bf16 v[38:41], v[176:179], v[202:205], v[38:41]
	v_mfma_f32_16x16x32_bf16 v[22:25], v[176:179], v[210:213], v[22:25]
	v_mfma_f32_16x16x32_bf16 v[18:21], v[184:187], v[210:213], v[18:21]
	v_mfma_f32_16x16x32_bf16 v[2:5], v[184:187], v[218:221], v[2:5]
	v_mfma_f32_16x16x32_bf16 v[6:9], v[176:179], v[218:221], v[6:9]
	v_mfma_f32_16x16x32_bf16 v[54:57], v[180:183], v[198:201], v[54:57]
	v_mfma_f32_16x16x32_bf16 v[50:53], v[190:193], v[198:201], v[50:53]
	v_mfma_f32_16x16x32_bf16 v[34:37], v[190:193], v[206:209], v[34:37]
	v_mfma_f32_16x16x32_bf16 v[38:41], v[180:183], v[206:209], v[38:41]
	v_mfma_f32_16x16x32_bf16 v[22:25], v[180:183], v[214:217], v[22:25]
	v_mfma_f32_16x16x32_bf16 v[18:21], v[190:193], v[214:217], v[18:21]
	v_mfma_f32_16x16x32_bf16 v[2:5], v[190:193], v[222:225], v[2:5]
	v_mfma_f32_16x16x32_bf16 v[6:9], v[180:183], v[222:225], v[6:9]
	s_setprio 0
	s_barrier
	s_add_i32 s67, s67, 2
	s_add_u32 s65, s65, 0x100
	s_addc_u32 s66, s66, 0
	s_add_u32 s34, s34, 0x10000
	s_addc_u32 s35, s35, 0
	s_cmpk_gt_u32 s67, 0xa9
	s_cbranch_scc0 .LBB0_1069
	s_and_b64 vcc, exec, s[18:19]
	s_cbranch_vccz .LBB0_1072
	s_barrier

; #define PG8_STAGE(bufoff, gbase, voff) do { _Pragma("unroll") for (int _i = 0; _i < 2; ++_i) \
;         __builtin_amdgcn_global_load_lds((const unsigned*)((const char*)(gbase) + (voff)[_i]), (PG8_LAS unsigned*)(lds + (bufoff) + ldsw + _i * 8192), 16, 0, 0); } while (0)
; #define PG8_LDA(dst, b, h) do { _Pragma("unroll") for (int m = 0; m < 4; ++m) _Pragma("unroll") for (int k = 0; k < 2; ++k) dst[m][k] = *(const PG8_LAS bf16x8*)(lds + PG8_SA(b, h) + aoff + m * 2048 + k * 1024); } while (0)
; #define PG8_LDB(dst, b, h) do { _Pragma("unroll") for (int n = 0; n < 2; ++n) _Pragma("unroll") for (int k = 0; k < 2; ++k) dst[n][k] = *(const PG8_LAS bf16x8*)(lds + PG8_SB(b, h) + boff + n * 2048 + k * 1024); } while (0)
; #define PG8_MMA(ai, bj, At, Bt) do { __builtin_amdgcn_s_setprio(1); _Pragma("unroll") for (int m = 0; m < 4; ++m) _Pragma("unroll") for (int n = 0; n < 2; ++n) _Pragma("unroll") for (int k = 0; k < 2; ++k) \
;         acc[ai][bj][m][n] = __builtin_amdgcn_mfma_f32_16x16x32_bf16(Bt[n][k], At[m][k], acc[ai][bj][m][n], 0, 0, 0); __builtin_amdgcn_s_setprio(0); } while (0)
; #define PG8_WAIT_V(n) asm volatile("s_waitcnt vmcnt(" #n ")" ::: "memory")
; #define PG8_WAIT_L(n) asm volatile("s_waitcnt lgkmcnt(" #n ")" ::: "memory")
; #define PG8_BAR __builtin_amdgcn_s_barrier()
; #define PG8_SCHED __builtin_amdgcn_sched_barrier(0)
; template <class Epi, class Sched, bool ALIGN_EPI = false, bool SP2 = false, bool A_TILED = false, bool B_TILED = false>
; __device__ __forceinline__ void gemm_phase(PG8_LAS unsigned char* lds, const Gemm g, const Sched& S, const Epi& E) {
;     ...
;             PG8_LDB(B0, 0, 0); PG8_LDB(B1, 0, 1); PG8_SCHED; PG8_LDA(At, 0, 0); PG8_STAGE(PG8_SA(1, 1), a1 + hstepA, voffA);
;             PG8_WAIT_V(8); PG8_WAIT_L(0); PG8_BAR; PG8_MMA(0, 0, At, B0); PG8_MMA(0, 1, At, B1); PG8_BAR; PG8_SCHED;
;             PG8_LDA(At, 0, 1); PG8_STAGE(PG8_SB(0, 0), b2, voffB); PG8_STAGE(PG8_SB(0, 1), b2 + hstepB, voffB); PG8_STAGE(PG8_SA(0, 0), a2, voffA);
.LBB0_1097:
	ds_read_b128 v[146:149], v143
	ds_read_b128 v[150:153], v143 offset:1024
	ds_read_b128 v[154:157], v143 offset:2048
	ds_read_b128 v[158:161], v143 offset:3072
	ds_read_b128 v[162:165], v144
	ds_read_b128 v[166:169], v144 offset:1024
	ds_read_b128 v[170:173], v144 offset:2048
	ds_read_b128 v[174:177], v144 offset:3072
	s_add_i32 s55, s26, 2
	s_add_u32 s27, s24, 0x4000
	s_addc_u32 s28, s25, 0
	s_cmp_eq_u32 s17, s26
	s_cselect_b32 s30, s20, s27
	s_cselect_b32 s31, s21, s28
	s_cselect_b32 s28, s22, s53
	s_cselect_b32 s29, s23, s54
	s_add_u32 s26, s30, 0x8000
	s_addc_u32 s27, s31, 0
	v_lshl_add_u64 v[186:187], s[24:25], 0, v[138:139]
	s_add_i32 m0, s35, 0xc000
	ds_read_b128 v[178:181], v145
	ds_read_b128 v[182:185], v145 offset:1024
	ds_read_b128 v[190:193], v145 offset:2048
	ds_read_b128 v[194:197], v145 offset:3072
	ds_read_b128 v[198:201], v145 offset:4096
	ds_read_b128 v[202:205], v145 offset:5120
	ds_read_b128 v[206:209], v145 offset:6144
	ds_read_b128 v[210:213], v145 offset:7168
	global_load_lds_dwordx4 v[186:187], off
	v_lshl_add_u64 v[186:187], s[24:25], 0, v[140:141]
	s_add_i32 m0, s35, 0xe000
	s_nop 0
	global_load_lds_dwordx4 v[186:187], off
	s_waitcnt vmcnt(8)
	s_waitcnt lgkmcnt(0)
	s_barrier
	s_setprio 1
	s_waitcnt lgkmcnt(0)
	v_mfma_f32_16x16x32_bf16 v[124:127], v[146:149], v[178:181], v[124:127]
	v_mfma_f32_16x16x32_bf16 v[120:123], v[154:157], v[178:181], v[120:123]
	v_mfma_f32_16x16x32_bf16 v[112:115], v[154:157], v[190:193], v[112:115]
	v_mfma_f32_16x16x32_bf16 v[116:119], v[146:149], v[190:193], v[116:119]
	v_mfma_f32_16x16x32_bf16 v[108:111], v[146:149], v[198:201], v[108:111]
	v_mfma_f32_16x16x32_bf16 v[100:103], v[154:157], v[198:201], v[100:103]
	v_mfma_f32_16x16x32_bf16 v[84:87], v[154:157], v[206:209], v[84:87]
	v_mfma_f32_16x16x32_bf16 v[92:95], v[146:149], v[206:209], v[92:95]
	v_mfma_f32_16x16x32_bf16 v[124:127], v[150:153], v[182:185], v[124:127]
	v_mfma_f32_16x16x32_bf16 v[120:123], v[158:161], v[182:185], v[120:123]
	v_mfma_f32_16x16x32_bf16 v[112:115], v[158:161], v[194:197], v[112:115]
	v_mfma_f32_16x16x32_bf16 v[116:119], v[150:153], v[194:197], v[116:119]
	v_mfma_f32_16x16x32_bf16 v[108:111], v[150:153], v[202:205], v[108:111]
	v_mfma_f32_16x16x32_bf16 v[100:103], v[158:161], v[202:205], v[100:103]
	v_mfma_f32_16x16x32_bf16 v[84:87], v[158:161], v[210:213], v[84:87]
	v_mfma_f32_16x16x32_bf16 v[92:95], v[150:153], v[210:213], v[92:95]
	s_setprio 0
	s_setprio 1
	v_mfma_f32_16x16x32_bf16 v[104:107], v[162:165], v[178:181], v[104:107]
	v_mfma_f32_16x16x32_bf16 v[96:99], v[170:173], v[178:181], v[96:99]
	v_mfma_f32_16x16x32_bf16 v[80:83], v[170:173], v[190:193], v[80:83]
	v_mfma_f32_16x16x32_bf16 v[88:91], v[162:165], v[190:193], v[88:91]
	v_mfma_f32_16x16x32_bf16 v[76:79], v[162:165], v[198:201], v[76:79]
	v_mfma_f32_16x16x32_bf16 v[72:75], v[170:173], v[198:201], v[72:75]
	v_mfma_f32_16x16x32_bf16 v[64:67], v[170:173], v[206:209], v[64:67]
	v_mfma_f32_16x16x32_bf16 v[68:71], v[162:165], v[206:209], v[68:71]
	v_mfma_f32_16x16x32_bf16 v[104:107], v[166:169], v[182:185], v[104:107]
	v_mfma_f32_16x16x32_bf16 v[96:99], v[174:177], v[182:185], v[96:99]
	v_mfma_f32_16x16x32_bf16 v[80:83], v[174:177], v[194:197], v[80:83]
	v_mfma_f32_16x16x32_bf16 v[88:91], v[166:169], v[194:197], v[88:91]
	v_mfma_f32_16x16x32_bf16 v[76:79], v[166:169], v[202:205], v[76:79]
	v_mfma_f32_16x16x32_bf16 v[72:75], v[174:177], v[202:205], v[72:75]
	v_mfma_f32_16x16x32_bf16 v[64:67], v[174:177], v[210:213], v[64:67]
	v_mfma_f32_16x16x32_bf16 v[68:71], v[166:169], v[210:213], v[68:71]
	s_setprio 0
	s_barrier
	s_add_i32 s56, s6, s34
	v_lshl_add_u64 v[186:187], s[28:29], 0, v[128:129]
	s_mov_b32 m0, s56
	ds_read_b128 v[178:181], v145 offset:16384
	ds_read_b128 v[182:185], v145 offset:17408
	ds_read_b128 v[190:193], v145 offset:18432
	ds_read_b128 v[194:197], v145 offset:19456
	ds_read_b128 v[198:201], v145 offset:20480
	ds_read_b128 v[202:205], v145 offset:21504
	ds_read_b128 v[206:209], v145 offset:22528
	ds_read_b128 v[210:213], v145 offset:23552
	global_load_lds_dwordx4 v[186:187], off
	s_add_i32 m0, s56, 0x2000
	s_add_u32 s56, s28, 0x2b0000
	v_lshl_add_u64 v[214:215], s[28:29], 0, v[134:135]
	s_addc_u32 s57, s29, 0
	s_add_i32 s58, s41, s34
	global_load_lds_dwordx4 v[214:215], off
	v_lshl_add_u64 v[216:217], s[56:57], 0, v[128:129]
	s_mov_b32 m0, s58
	s_nop 0
	global_load_lds_dwordx4 v[216:217], off
	v_lshl_add_u64 v[216:217], s[56:57], 0, v[134:135]
	s_add_i32 m0, s58, 0x2000
	s_nop 0
	global_load_lds_dwordx4 v[216:217], off
	v_lshl_add_u64 v[216:217], s[30:31], 0, v[130:131]
	s_mov_b32 m0, s35
	s_nop 0
	global_load_lds_dwordx4 v[216:217], off
	v_lshl_add_u64 v[216:217], s[30:31], 0, v[132:133]
	s_mov_b32 m0, s36
	s_nop 0
	global_load_lds_dwordx4 v[216:217], off
	s_waitcnt vmcnt(8)
	s_waitcnt lgkmcnt(0)
	s_barrier
; #define PG8_STAGE(bufoff, gbase, voff) do { _Pragma("unroll") for (int _i = 0; _i < 2; ++_i) \
;         __builtin_amdgcn_global_load_lds((const unsigned*)((const char*)(gbase) + (voff)[_i]), (PG8_LAS unsigned*)(lds + (bufoff) + ldsw + _i * 8192), 16, 0, 0); } while (0)
; #define PG8_LDA(dst, b, h) do { _Pragma("unroll") for (int m = 0; m < 4; ++m) _Pragma("unroll") for (int k = 0; k < 2; ++k) dst[m][k] = *(const PG8_LAS bf16x8*)(lds + PG8_SA(b, h) + aoff + m * 2048 + k * 1024); } while (0)
; #define PG8_LDB(dst, b, h) do { _Pragma("unroll") for (int n = 0; n < 2; ++n) _Pragma("unroll") for (int k = 0; k < 2; ++k) dst[n][k] = *(const PG8_LAS bf16x8*)(lds + PG8_SB(b, h) + boff + n * 2048 + k * 1024); } while (0)
; #define PG8_MMA(ai, bj, At, Bt) do { __builtin_amdgcn_s_setprio(1); _Pragma("unroll") for (int m = 0; m < 4; ++m) _Pragma("unroll") for (int n = 0; n < 2; ++n) _Pragma("unroll") for (int k = 0; k < 2; ++k) \
;         acc[ai][bj][m][n] = __builtin_amdgcn_mfma_f32_16x16x32_bf16(Bt[n][k], At[m][k], acc[ai][bj][m][n], 0, 0, 0); __builtin_amdgcn_s_setprio(0); } while (0)
; #define PG8_WAIT_V(n) asm volatile("s_waitcnt vmcnt(" #n ")" ::: "memory")
; #define PG8_WAIT_L(n) asm volatile("s_waitcnt lgkmcnt(" #n ")" ::: "memory")
; #define PG8_BAR __builtin_amdgcn_s_barrier()
; #define PG8_SCHED __builtin_amdgcn_sched_barrier(0)
; template <class Epi, class Sched, bool ALIGN_EPI = false, bool SP2 = false, bool A_TILED = false, bool B_TILED = false>
; __device__ __forceinline__ void gemm_phase(PG8_LAS unsigned char* lds, const Gemm g, const Sched& S, const Epi& E) {
;     ...
;             PG8_WAIT_V(8); PG8_WAIT_L(0); PG8_BAR; PG8_MMA(1, 0, At, B0); PG8_MMA(1, 1, At, B1); PG8_BAR; PG8_SCHED;
;             PG8_LDB(B0, 1, 0); PG8_LDB(B1, 1, 1); PG8_SCHED; PG8_LDA(At, 1, 0); PG8_STAGE(PG8_SA(0, 1), a2 + hstepA, voffA);
;             PG8_WAIT_V(8); PG8_WAIT_L(0); PG8_BAR; PG8_MMA(0, 0, At, B0); PG8_MMA(0, 1, At, B1); PG8_BAR; PG8_SCHED;
	s_setprio 1
	s_waitcnt lgkmcnt(0)
	v_mfma_f32_16x16x32_bf16 v[60:63], v[146:149], v[178:181], v[60:63]
	v_mfma_f32_16x16x32_bf16 v[56:59], v[154:157], v[178:181], v[56:59]
	v_mfma_f32_16x16x32_bf16 v[48:51], v[154:157], v[190:193], v[48:51]
	v_mfma_f32_16x16x32_bf16 v[52:55], v[146:149], v[190:193], v[52:55]
	v_mfma_f32_16x16x32_bf16 v[44:47], v[146:149], v[198:201], v[44:47]
	v_mfma_f32_16x16x32_bf16 v[36:39], v[154:157], v[198:201], v[36:39]
	v_mfma_f32_16x16x32_bf16 v[20:23], v[154:157], v[206:209], v[20:23]
	v_mfma_f32_16x16x32_bf16 v[28:31], v[146:149], v[206:209], v[28:31]
	v_mfma_f32_16x16x32_bf16 v[60:63], v[150:153], v[182:185], v[60:63]
	v_mfma_f32_16x16x32_bf16 v[56:59], v[158:161], v[182:185], v[56:59]
	v_mfma_f32_16x16x32_bf16 v[48:51], v[158:161], v[194:197], v[48:51]
	v_mfma_f32_16x16x32_bf16 v[52:55], v[150:153], v[194:197], v[52:55]
	v_mfma_f32_16x16x32_bf16 v[44:47], v[150:153], v[202:205], v[44:47]
	v_mfma_f32_16x16x32_bf16 v[36:39], v[158:161], v[202:205], v[36:39]
	v_mfma_f32_16x16x32_bf16 v[20:23], v[158:161], v[210:213], v[20:23]
	v_mfma_f32_16x16x32_bf16 v[28:31], v[150:153], v[210:213], v[28:31]
	s_setprio 0
	s_setprio 1
	v_mfma_f32_16x16x32_bf16 v[40:43], v[162:165], v[178:181], v[40:43]
	v_mfma_f32_16x16x32_bf16 v[32:35], v[170:173], v[178:181], v[32:35]
	v_mfma_f32_16x16x32_bf16 v[16:19], v[170:173], v[190:193], v[16:19]
	v_mfma_f32_16x16x32_bf16 v[24:27], v[162:165], v[190:193], v[24:27]
	v_mfma_f32_16x16x32_bf16 v[12:15], v[162:165], v[198:201], v[12:15]
	v_mfma_f32_16x16x32_bf16 v[8:11], v[170:173], v[198:201], v[8:11]
	v_mfma_f32_16x16x32_bf16 v[0:3], v[170:173], v[206:209], v[0:3]
	v_mfma_f32_16x16x32_bf16 v[4:7], v[162:165], v[206:209], v[4:7]
	v_mfma_f32_16x16x32_bf16 v[40:43], v[166:169], v[182:185], v[40:43]
	v_mfma_f32_16x16x32_bf16 v[32:35], v[174:177], v[182:185], v[32:35]
	v_mfma_f32_16x16x32_bf16 v[16:19], v[174:177], v[194:197], v[16:19]
	v_mfma_f32_16x16x32_bf16 v[24:27], v[166:169], v[194:197], v[24:27]
	v_mfma_f32_16x16x32_bf16 v[12:15], v[166:169], v[202:205], v[12:15]
	v_mfma_f32_16x16x32_bf16 v[8:11], v[174:177], v[202:205], v[8:11]
	v_mfma_f32_16x16x32_bf16 v[0:3], v[174:177], v[210:213], v[0:3]
	v_mfma_f32_16x16x32_bf16 v[4:7], v[166:169], v[210:213], v[4:7]
	s_setprio 0
	s_barrier
	s_add_i32 s56, 0, 0x18000
	s_add_i32 s57, 0, 0x1c000
	v_add_u32_e32 v158, s56, v142
	v_add_u32_e32 v174, s57, v142
	ds_read_b128 v[146:149], v158
	ds_read_b128 v[150:153], v158 offset:1024
	ds_read_b128 v[154:157], v158 offset:2048
	ds_read_b128 v[158:161], v158 offset:3072
	ds_read_b128 v[162:165], v174
	ds_read_b128 v[166:169], v174 offset:1024
	ds_read_b128 v[170:173], v174 offset:2048
	ds_read_b128 v[174:177], v174 offset:3072
	s_add_u32 s30, s30, 0x4000
	s_addc_u32 s31, s31, 0
	s_mov_b32 m0, s37
	v_lshl_add_u64 v[216:217], s[30:31], 0, v[130:131]
	ds_read_b128 v[178:181], v145 offset:32768
	ds_read_b128 v[182:185], v145 offset:33792
	ds_read_b128 v[190:193], v145 offset:34816
	ds_read_b128 v[194:197], v145 offset:35840
	ds_read_b128 v[198:201], v145 offset:36864
	ds_read_b128 v[202:205], v145 offset:37888
	ds_read_b128 v[206:209], v145 offset:38912
	ds_read_b128 v[210:213], v145 offset:39936
	global_load_lds_dwordx4 v[216:217], off
	v_lshl_add_u64 v[216:217], s[30:31], 0, v[132:133]
	s_mov_b32 m0, s38
	s_nop 0
	global_load_lds_dwordx4 v[216:217], off
	s_waitcnt vmcnt(8)
	s_waitcnt lgkmcnt(0)
	s_barrier
	s_setprio 1
	s_waitcnt lgkmcnt(0)
	v_mfma_f32_16x16x32_bf16 v[124:127], v[146:149], v[178:181], v[124:127]
	v_mfma_f32_16x16x32_bf16 v[120:123], v[154:157], v[178:181], v[120:123]
	v_mfma_f32_16x16x32_bf16 v[112:115], v[154:157], v[190:193], v[112:115]
	v_mfma_f32_16x16x32_bf16 v[116:119], v[146:149], v[190:193], v[116:119]
	v_mfma_f32_16x16x32_bf16 v[108:111], v[146:149], v[198:201], v[108:111]
	v_mfma_f32_16x16x32_bf16 v[100:103], v[154:157], v[198:201], v[100:103]
	v_mfma_f32_16x16x32_bf16 v[84:87], v[154:157], v[206:209], v[84:87]
	v_mfma_f32_16x16x32_bf16 v[92:95], v[146:149], v[206:209], v[92:95]
	v_mfma_f32_16x16x32_bf16 v[124:127], v[150:153], v[182:185], v[124:127]
	v_mfma_f32_16x16x32_bf16 v[120:123], v[158:161], v[182:185], v[120:123]
	v_mfma_f32_16x16x32_bf16 v[112:115], v[158:161], v[194:197], v[112:115]
	v_mfma_f32_16x16x32_bf16 v[116:119], v[150:153], v[194:197], v[116:119]
	v_mfma_f32_16x16x32_bf16 v[108:111], v[150:153], v[202:205], v[108:111]
	v_mfma_f32_16x16x32_bf16 v[100:103], v[158:161], v[202:205], v[100:103]
	v_mfma_f32_16x16x32_bf16 v[84:87], v[158:161], v[210:213], v[84:87]
	v_mfma_f32_16x16x32_bf16 v[92:95], v[150:153], v[210:213], v[92:95]
	s_setprio 0
	s_setprio 1
	v_mfma_f32_16x16x32_bf16 v[104:107], v[162:165], v[178:181], v[104:107]
	v_mfma_f32_16x16x32_bf16 v[96:99], v[170:173], v[178:181], v[96:99]
	v_mfma_f32_16x16x32_bf16 v[80:83], v[170:173], v[190:193], v[80:83]
	v_mfma_f32_16x16x32_bf16 v[88:91], v[162:165], v[190:193], v[88:91]
	v_mfma_f32_16x16x32_bf16 v[76:79], v[162:165], v[198:201], v[76:79]
	v_mfma_f32_16x16x32_bf16 v[72:75], v[170:173], v[198:201], v[72:75]
	v_mfma_f32_16x16x32_bf16 v[64:67], v[170:173], v[206:209], v[64:67]
	v_mfma_f32_16x16x32_bf16 v[68:71], v[162:165], v[206:209], v[68:71]
	v_mfma_f32_16x16x32_bf16 v[104:107], v[166:169], v[182:185], v[104:107]
	v_mfma_f32_16x16x32_bf16 v[96:99], v[174:177], v[182:185], v[96:99]
	v_mfma_f32_16x16x32_bf16 v[80:83], v[174:177], v[194:197], v[80:83]
	v_mfma_f32_16x16x32_bf16 v[88:91], v[166:169], v[194:197], v[88:91]
	v_mfma_f32_16x16x32_bf16 v[76:79], v[166:169], v[202:205], v[76:79]
	v_mfma_f32_16x16x32_bf16 v[72:75], v[174:177], v[202:205], v[72:75]
	v_mfma_f32_16x16x32_bf16 v[64:67], v[174:177], v[210:213], v[64:67]
	v_mfma_f32_16x16x32_bf16 v[68:71], v[166:169], v[210:213], v[68:71]
	s_setprio 0
	s_barrier
; #define PG8_STAGE(bufoff, gbase, voff) do { _Pragma("unroll") for (int _i = 0; _i < 2; ++_i) \
;         __builtin_amdgcn_global_load_lds((const unsigned*)((const char*)(gbase) + (voff)[_i]), (PG8_LAS unsigned*)(lds + (bufoff) + ldsw + _i * 8192), 16, 0, 0); } while (0)
; #define PG8_LDA(dst, b, h) do { _Pragma("unroll") for (int m = 0; m < 4; ++m) _Pragma("unroll") for (int k = 0; k < 2; ++k) dst[m][k] = *(const PG8_LAS bf16x8*)(lds + PG8_SA(b, h) + aoff + m * 2048 + k * 1024); } while (0)
; #define PG8_MMA(ai, bj, At, Bt) do { __builtin_amdgcn_s_setprio(1); _Pragma("unroll") for (int m = 0; m < 4; ++m) _Pragma("unroll") for (int n = 0; n < 2; ++n) _Pragma("unroll") for (int k = 0; k < 2; ++k) \
;         acc[ai][bj][m][n] = __builtin_amdgcn_mfma_f32_16x16x32_bf16(Bt[n][k], At[m][k], acc[ai][bj][m][n], 0, 0, 0); __builtin_amdgcn_s_setprio(0); } while (0)
; #define PG8_WAIT_V(n) asm volatile("s_waitcnt vmcnt(" #n ")" ::: "memory")
; #define PG8_WAIT_L(n) asm volatile("s_waitcnt lgkmcnt(" #n ")" ::: "memory")
; #define PG8_BAR __builtin_amdgcn_s_barrier()
; #define PG8_SCHED __builtin_amdgcn_sched_barrier(0)
; template <class Epi, class Sched, bool ALIGN_EPI = false, bool SP2 = false, bool A_TILED = false, bool B_TILED = false>
; __device__ __forceinline__ void gemm_phase(PG8_LAS unsigned char* lds, const Gemm g, const Sched& S, const Epi& E) {
;     ...
;             PG8_LDA(At, 1, 1); PG8_STAGE(PG8_SB(1, 0), b3, voffB); PG8_STAGE(PG8_SB(1, 1), b3 + hstepB, voffB); PG8_STAGE(PG8_SA(1, 0), a3, voffA);
;             PG8_WAIT_V(8); PG8_WAIT_L(0); PG8_BAR; PG8_MMA(1, 0, At, B0); PG8_MMA(1, 1, At, B1); PG8_BAR; PG8_SCHED;
	s_add_i32 s30, s56, s34
	v_lshl_add_u64 v[186:187], v[186:187], 0, s[12:13]
	s_mov_b32 m0, s30
	ds_read_b128 v[178:181], v145 offset:49152
	ds_read_b128 v[182:185], v145 offset:50176
	ds_read_b128 v[190:193], v145 offset:51200
	ds_read_b128 v[194:197], v145 offset:52224
	ds_read_b128 v[198:201], v145 offset:53248
	ds_read_b128 v[202:205], v145 offset:54272
	ds_read_b128 v[206:209], v145 offset:55296
	ds_read_b128 v[210:213], v145 offset:56320
	global_load_lds_dwordx4 v[186:187], off
	s_add_i32 m0, s30, 0x2000
	s_add_u32 s28, s28, 0x2b0080
	v_lshl_add_u64 v[186:187], v[214:215], 0, s[12:13]
	s_addc_u32 s29, s29, 0
	s_add_i32 s30, s57, s34
	global_load_lds_dwordx4 v[186:187], off
	v_lshl_add_u64 v[186:187], s[28:29], 0, v[128:129]
	s_mov_b32 m0, s30
	s_nop 0
	global_load_lds_dwordx4 v[186:187], off
	v_lshl_add_u64 v[186:187], s[28:29], 0, v[134:135]
	s_add_i32 m0, s30, 0x2000
	s_nop 0
	global_load_lds_dwordx4 v[186:187], off
	v_lshl_add_u64 v[186:187], s[26:27], 0, v[130:131]
	s_mov_b32 m0, s39
	s_nop 0
	global_load_lds_dwordx4 v[186:187], off
	v_lshl_add_u64 v[186:187], s[26:27], 0, v[132:133]
	s_mov_b32 m0, s40
	s_nop 0
	global_load_lds_dwordx4 v[186:187], off
	s_waitcnt vmcnt(8)
	s_waitcnt lgkmcnt(0)
	s_barrier
	s_setprio 1
	s_waitcnt lgkmcnt(0)
	v_mfma_f32_16x16x32_bf16 v[60:63], v[146:149], v[178:181], v[60:63]
	v_mfma_f32_16x16x32_bf16 v[56:59], v[154:157], v[178:181], v[56:59]
	v_mfma_f32_16x16x32_bf16 v[48:51], v[154:157], v[190:193], v[48:51]
	v_mfma_f32_16x16x32_bf16 v[52:55], v[146:149], v[190:193], v[52:55]
	v_mfma_f32_16x16x32_bf16 v[44:47], v[146:149], v[198:201], v[44:47]
	v_mfma_f32_16x16x32_bf16 v[36:39], v[154:157], v[198:201], v[36:39]
	v_mfma_f32_16x16x32_bf16 v[20:23], v[154:157], v[206:209], v[20:23]
	v_mfma_f32_16x16x32_bf16 v[28:31], v[146:149], v[206:209], v[28:31]
	v_mfma_f32_16x16x32_bf16 v[60:63], v[150:153], v[182:185], v[60:63]
	v_mfma_f32_16x16x32_bf16 v[56:59], v[158:161], v[182:185], v[56:59]
	v_mfma_f32_16x16x32_bf16 v[48:51], v[158:161], v[194:197], v[48:51]
	v_mfma_f32_16x16x32_bf16 v[52:55], v[150:153], v[194:197], v[52:55]
	v_mfma_f32_16x16x32_bf16 v[44:47], v[150:153], v[202:205], v[44:47]
	v_mfma_f32_16x16x32_bf16 v[36:39], v[158:161], v[202:205], v[36:39]
	v_mfma_f32_16x16x32_bf16 v[20:23], v[158:161], v[210:213], v[20:23]
	v_mfma_f32_16x16x32_bf16 v[28:31], v[150:153], v[210:213], v[28:31]
	s_setprio 0
	s_setprio 1
	v_mfma_f32_16x16x32_bf16 v[40:43], v[162:165], v[178:181], v[40:43]
	v_mfma_f32_16x16x32_bf16 v[32:35], v[170:173], v[178:181], v[32:35]
	v_mfma_f32_16x16x32_bf16 v[16:19], v[170:173], v[190:193], v[16:19]
	v_mfma_f32_16x16x32_bf16 v[24:27], v[162:165], v[190:193], v[24:27]
	v_mfma_f32_16x16x32_bf16 v[12:15], v[162:165], v[198:201], v[12:15]
	v_mfma_f32_16x16x32_bf16 v[8:11], v[170:173], v[198:201], v[8:11]
	v_mfma_f32_16x16x32_bf16 v[0:3], v[170:173], v[206:209], v[0:3]
	v_mfma_f32_16x16x32_bf16 v[4:7], v[162:165], v[206:209], v[4:7]
	v_mfma_f32_16x16x32_bf16 v[40:43], v[166:169], v[182:185], v[40:43]
	v_mfma_f32_16x16x32_bf16 v[32:35], v[174:177], v[182:185], v[32:35]
	v_mfma_f32_16x16x32_bf16 v[16:19], v[174:177], v[194:197], v[16:19]
	v_mfma_f32_16x16x32_bf16 v[24:27], v[166:169], v[194:197], v[24:27]
	v_mfma_f32_16x16x32_bf16 v[12:15], v[166:169], v[202:205], v[12:15]
	v_mfma_f32_16x16x32_bf16 v[8:11], v[174:177], v[202:205], v[8:11]
	v_mfma_f32_16x16x32_bf16 v[0:3], v[174:177], v[210:213], v[0:3]
	v_mfma_f32_16x16x32_bf16 v[4:7], v[166:169], v[210:213], v[4:7]
	s_setprio 0
	s_barrier
	s_add_u32 s53, s53, 0x100
	s_addc_u32 s54, s54, 0
	s_add_u32 s24, s24, 0x10000
	s_addc_u32 s25, s25, 0
	s_cmp_ge_i32 s55, s19
	s_mov_b32 s26, s55
	s_cbranch_scc0 .LBB0_1097
	s_and_b64 vcc, exec, s[14:15]
	s_cbranch_vccz .LBB0_1100
	s_barrier
